# speedup vs baseline: 1.0085x; 1.0085x over previous
; __device__ __forceinline__ unsigned pk2(float lo, float hi) { f32x2_t v = {lo, hi}; bf16x2_t b = __builtin_convertvector(v, bf16x2_t); return __builtin_bit_cast(unsigned, b); }
;     __device__ __forceinline__ void operator()(const pg8::f32x4 (&acc)[2][2][4][2], const pg8::Unit& u, int wr, int wc, int fr, int fq) const {
;     ...
;             u32x4 cy[2], ny[2];
;             cy[0] = *(const u32x4*)(YG + (size_t)row0 * ldyg + col0); cy[1] = *(const u32x4*)(YG + (size_t)row0 * ldyg + col0 + 128);
; #pragma unroll
;             for (int g = 0; g < 8; ++g) {
;                 const int ai = g >> 2, m = g & 3, r = row0 + ai * 128 + m * 16;
;                 if (g < 7) {
;                     const int rn = row0 + ((g + 1) >> 2) * 128 + ((g + 1) & 3) * 16;
;                     ny[0] = *(const u32x4*)(YG + (size_t)rn * ldyg + col0); ny[1] = *(const u32x4*)(YG + (size_t)rn * ldyg + col0 + 128);
;                 }
;                 float ss = 0.f;
; #pragma unroll
;                 for (int bj = 0; bj < 2; ++bj) {
;                     const u32x4 y = cy[bj];
;                     const float yf[8] = {bflo(y.x), bfhi(y.x), bflo(y.y), bfhi(y.y), bflo(y.z), bfhi(y.z), bflo(y.w), bfhi(y.w)};
;                     f32x4 v0 = acc[ai][bj][m][0], v1 = acc[ai][bj][m][1];
; #pragma unroll
;                     for (int k = 0; k < 4; ++k) {
;                         v0[k] = yf[k] * __builtin_amdgcn_rcpf(1.f + __builtin_amdgcn_exp2f(-LOG2E * v0[k])); v1[k] = yf[4 + k] * __builtin_amdgcn_rcpf(1.f + __builtin_amdgcn_exp2f(-LOG2E * v1[k]));
;                         ss += v0[k] * v0[k] + v1[k] * v1[k];
;                     }
;                     u32x4 w; w.x = pk2(v0[0], v0[1]); w.y = pk2(v0[2], v0[3]); w.z = pk2(v1[0], v1[1]); w.w = pk2(v1[2], v1[3]);
;                     *(u32x4*)(O + (size_t)r * ldc + col0 + bj * 128) = w;
;                 }
;                 ss += __shfl_xor(ss, 16); ss += __shfl_xor(ss, 32);
;                 if (fq == 0) atomicAdd(rss + r, (u64)(ss * RSS_FIX));
;                 cy[0] = ny[0]; cy[1] = ny[1];
;             }
.LBB0_577:
	v_lshl_add_u32 v156, s30, 8, v137
	v_lshl_or_b32 v152, s28, 8, v141
	v_ashrrev_i32_e32 v157, 31, v156
	v_lshlrev_b64 v[154:155], 10, v[156:157]
	v_ashrrev_i32_e32 v153, 31, v152
	v_lshl_add_u64 v[158:159], s[8:9], 0, v[154:155]
	v_lshlrev_b64 v[154:155], 1, v[152:153]
	v_lshl_add_u64 v[158:159], v[158:159], 0, v[154:155]
	global_load_dwordx4 v[168:171], v[158:159], off
	global_load_dwordx4 v[172:175], v[158:159], off offset:256
	v_and_b32_e32 v160, 64, v164
	v_xor_b32_e32 v161, 16, v164
	v_add_u32_e32 v158, 64, v160
	v_xor_b32_e32 v165, 32, v164
	v_mul_f32_e32 v120, 0xbfb8aa3b, v120
	v_cmp_lt_i32_e32 vcc, v161, v158
	v_mul_f32_e32 v124, 0xbfb8aa3b, v124
	v_mul_f32_e32 v125, 0xbfb8aa3b, v125
	v_mul_f32_e32 v121, 0xbfb8aa3b, v121
	v_mul_f32_e32 v126, 0xbfb8aa3b, v126
	v_mul_f32_e32 v122, 0xbfb8aa3b, v122
	v_mul_f32_e32 v127, 0xbfb8aa3b, v127
	v_mul_f32_e32 v123, 0xbfb8aa3b, v123
	v_or_b32_e32 v160, 16, v156
	v_exp_f32_e32 v159, v120
	v_cndmask_b32_e32 v120, v164, v161, vcc
	v_cmp_lt_i32_e32 vcc, v165, v158
	v_exp_f32_e32 v124, v124
	v_exp_f32_e32 v125, v125
	v_exp_f32_e32 v167, v121
	v_exp_f32_e32 v126, v126
	v_exp_f32_e32 v122, v122
	v_exp_f32_e32 v127, v127
	v_exp_f32_e32 v123, v123
	v_cndmask_b32_e32 v121, v164, v165, vcc
	v_ashrrev_i32_e32 v161, 31, v160
	v_lshlrev_b32_e32 v166, 2, v120
	v_lshlrev_b32_e32 v165, 2, v121
	v_lshlrev_b64 v[120:121], 10, v[160:161]
	v_lshl_add_u64 v[120:121], s[8:9], 0, v[120:121]
	v_lshl_add_u64 v[120:121], v[120:121], 0, v[154:155]
	v_add_f32_e32 v158, 1.0, v124
	v_add_f32_e32 v177, 1.0, v125
	v_add_f32_e32 v178, 1.0, v126
	v_add_f32_e32 v179, 1.0, v122
	v_add_f32_e32 v181, 1.0, v127
	v_add_f32_e32 v202, 1.0, v123
	global_load_dwordx4 v[124:127], v[120:121], off
	s_nop 0
	global_load_dwordx4 v[120:123], v[120:121], off offset:256
	v_mul_f32_e32 v116, 0xbfb8aa3b, v116
	v_mul_f32_e32 v117, 0xbfb8aa3b, v117
	v_exp_f32_e32 v176, v116
	v_exp_f32_e32 v203, v117
	v_add_f32_e32 v159, 1.0, v159
	v_add_f32_e32 v167, 1.0, v167
	v_mul_f32_e32 v118, 0xbfb8aa3b, v118
	v_add_f32_e32 v204, 1.0, v176
	v_rcp_f32_e32 v176, v159
	v_rcp_f32_e32 v159, v177
	v_rcp_f32_e32 v177, v167
	v_add_f32_e32 v167, 1.0, v203
	v_exp_f32_e32 v118, v118
	v_mul_f32_e32 v114, 0xbfb8aa3b, v114
	v_rcp_f32_e32 v203, v167
	v_exp_f32_e32 v167, v114
	v_mul_f32_e32 v112, 0xbfb8aa3b, v112
	v_mul_f32_e32 v113, 0xbfb8aa3b, v113
	v_exp_f32_e32 v112, v112
	v_exp_f32_e32 v113, v113
	v_mul_f32_e32 v114, 0xbfb8aa3b, v119
	v_add_f32_e32 v118, 1.0, v118
	v_exp_f32_e32 v119, v114
	v_mul_f32_e32 v115, 0xbfb8aa3b, v115
	v_rcp_f32_e32 v114, v118
	v_add_f32_e32 v118, 1.0, v167
	v_exp_f32_e32 v167, v115
	v_rcp_f32_e32 v158, v158
	v_rcp_f32_e32 v180, v179
	v_rcp_f32_e32 v179, v181
	v_rcp_f32_e32 v181, v202
	v_add_f32_e32 v112, 1.0, v112
	v_rcp_f32_e32 v178, v178
	v_add_f32_e32 v113, 1.0, v113
	v_rcp_f32_e32 v112, v112
	v_rcp_f32_e32 v113, v113
	v_add_f32_e32 v119, 1.0, v119
	v_rcp_f32_e32 v202, v204
	v_rcp_f32_e32 v115, v119
	v_add_f32_e32 v119, 1.0, v167
	s_waitcnt vmcnt(0)
	v_lshlrev_b32_e32 v206, 16, v170
	v_and_b32_e32 v207, 0xffff0000, v170
	v_lshlrev_b32_e32 v204, 16, v168
	v_and_b32_e32 v205, 0xffff0000, v168
	v_lshlrev_b32_e32 v170, 16, v171
	v_and_b32_e32 v171, 0xffff0000, v171
	v_pk_mul_f32 v[176:177], v[176:177], v[206:207]
	v_lshlrev_b32_e32 v168, 16, v169
	v_and_b32_e32 v169, 0xffff0000, v169
	v_pk_mul_f32 v[158:159], v[158:159], v[204:205]
	v_pk_mul_f32 v[180:181], v[180:181], v[170:171]
	v_pk_mul_f32 v[204:205], v[176:177], v[176:177]
	v_rcp_f32_e32 v118, v118
	v_rcp_f32_e32 v119, v119
	v_pk_mul_f32 v[178:179], v[178:179], v[168:169]
	v_pk_mul_f32 v[206:207], v[180:181], v[180:181]
	v_cvt_pk_bf16_f32 v168, v158, v159
	v_cvt_pk_bf16_f32 v171, v180, v181
	v_pk_fma_f32 v[158:159], v[158:159], v[158:159], v[204:205]
	v_lshlrev_b32_e32 v180, 16, v174
	v_and_b32_e32 v181, 0xffff0000, v174
	v_cvt_pk_bf16_f32 v169, v178, v179
	v_cvt_pk_bf16_f32 v170, v176, v177
	v_pk_fma_f32 v[176:177], v[178:179], v[178:179], v[206:207]
	v_lshlrev_b32_e32 v178, 16, v172
	v_and_b32_e32 v179, 0xffff0000, v172
	v_pk_mul_f32 v[180:181], v[112:113], v[180:181]
	v_lshlrev_b32_e32 v172, 16, v173
	v_and_b32_e32 v173, 0xffff0000, v173
	v_add_f32_e32 v158, v158, v159
	v_pk_mul_f32 v[178:179], v[202:203], v[178:179]
	v_pk_mul_f32 v[112:113], v[180:181], v[180:181]
	v_pk_mul_f32 v[172:173], v[114:115], v[172:173]
	v_lshlrev_b32_e32 v114, 16, v175
	v_and_b32_e32 v115, 0xffff0000, v175
	v_add_f32_e32 v158, v176, v158
	v_pk_fma_f32 v[112:113], v[178:179], v[178:179], v[112:113]
	v_pk_mul_f32 v[118:119], v[118:119], v[114:115]
	v_add_f32_e32 v158, v177, v158
	v_pk_mul_f32 v[114:115], v[118:119], v[118:119]
	v_add_f32_e32 v112, v112, v158
	v_pk_fma_f32 v[114:115], v[172:173], v[172:173], v[114:115]
	v_add_f32_e32 v112, v113, v112
	v_add_f32_e32 v112, v114, v112
	v_add_f32_e32 v115, v115, v112
	ds_bpermute_b32 v167, v166, v115
	v_lshlrev_b64 v[116:117], 11, v[156:157]
	v_lshl_add_u64 v[112:113], s[14:15], 0, v[116:117]
	v_lshl_add_u64 v[158:159], v[112:113], 0, v[154:155]
	v_cvt_pk_bf16_f32 v114, v178, v179
	s_waitcnt lgkmcnt(0)
	v_add_f32_e32 v112, v115, v167
	ds_bpermute_b32 v113, v165, v112
	v_cvt_pk_bf16_f32 v115, v172, v173
	v_cvt_pk_bf16_f32 v116, v180, v181
	v_cvt_pk_bf16_f32 v117, v118, v119
	global_store_dwordx4 v[158:159], v[168:171], off
	global_store_dwordx4 v[158:159], v[114:117], off offset:256
	s_and_saveexec_b64 s[28:29], s[2:3]
	s_cbranch_execz .LBB0_579
	s_waitcnt lgkmcnt(0)
	v_add_f32_e32 v112, v112, v113
	v_mul_f32_e32 v112, 0x4b800000, v112
	v_trunc_f32_e32 v112, v112
	v_mul_f32_e32 v113, 0x2f800000, v112
	v_floor_f32_e32 v113, v113
	v_fmac_f32_e32 v112, 0xcf800000, v113
	v_cvt_u32_f32_e32 v112, v112
	v_cvt_u32_f32_e32 v113, v113
	v_lshl_add_u64 v[114:115], v[156:157], 3, s[16:17]
	global_atomic_add_x2 v[114:115], v[112:113], off
; __device__ __forceinline__ unsigned pk2(float lo, float hi) { f32x2_t v = {lo, hi}; bf16x2_t b = __builtin_convertvector(v, bf16x2_t); return __builtin_bit_cast(unsigned, b); }
;     __device__ __forceinline__ void operator()(const pg8::f32x4 (&acc)[2][2][4][2], const pg8::Unit& u, int wr, int wc, int fr, int fq) const {
;     ...
;             u32x4 cy[2], ny[2];
;             cy[0] = *(const u32x4*)(YG + (size_t)row0 * ldyg + col0); cy[1] = *(const u32x4*)(YG + (size_t)row0 * ldyg + col0 + 128);
; #pragma unroll
;             for (int g = 0; g < 8; ++g) {
;                 const int ai = g >> 2, m = g & 3, r = row0 + ai * 128 + m * 16;
;                 if (g < 7) {
;                     const int rn = row0 + ((g + 1) >> 2) * 128 + ((g + 1) & 3) * 16;
;                     ny[0] = *(const u32x4*)(YG + (size_t)rn * ldyg + col0); ny[1] = *(const u32x4*)(YG + (size_t)rn * ldyg + col0 + 128);
;                 }
;                 float ss = 0.f;
; #pragma unroll
;                 for (int bj = 0; bj < 2; ++bj) {
;                     const u32x4 y = cy[bj];
;                     const float yf[8] = {bflo(y.x), bfhi(y.x), bflo(y.y), bfhi(y.y), bflo(y.z), bfhi(y.z), bflo(y.w), bfhi(y.w)};
;                     f32x4 v0 = acc[ai][bj][m][0], v1 = acc[ai][bj][m][1];
; #pragma unroll
;                     for (int k = 0; k < 4; ++k) {
;                         v0[k] = yf[k] * __builtin_amdgcn_rcpf(1.f + __builtin_amdgcn_exp2f(-LOG2E * v0[k])); v1[k] = yf[4 + k] * __builtin_amdgcn_rcpf(1.f + __builtin_amdgcn_exp2f(-LOG2E * v1[k]));
;                         ss += v0[k] * v0[k] + v1[k] * v1[k];
;                     }
;                     u32x4 w; w.x = pk2(v0[0], v0[1]); w.y = pk2(v0[2], v0[3]); w.z = pk2(v1[0], v1[1]); w.w = pk2(v1[2], v1[3]);
;                     *(u32x4*)(O + (size_t)r * ldc + col0 + bj * 128) = w;
;                 }
;                 ss += __shfl_xor(ss, 16); ss += __shfl_xor(ss, 32);
;                 if (fq == 0) atomicAdd(rss + r, (u64)(ss * RSS_FIX));
;                 cy[0] = ny[0]; cy[1] = ny[1];
;             }
.LBB0_579:
	s_or_b64 exec, exec, s[28:29]
	v_or_b32_e32 v158, 32, v156
	v_ashrrev_i32_e32 v159, 31, v158
	s_waitcnt lgkmcnt(0)
	v_lshlrev_b64 v[112:113], 10, v[158:159]
	v_lshl_add_u64 v[112:113], s[8:9], 0, v[112:113]
	v_lshl_add_u64 v[112:113], v[112:113], 0, v[154:155]
	global_load_dwordx4 v[116:119], v[112:113], off
	s_nop 0
	global_load_dwordx4 v[112:115], v[112:113], off offset:256
	v_mul_f32_e32 v108, 0xbfb8aa3b, v108
	v_mul_f32_e32 v109, 0xbfb8aa3b, v109
	v_exp_f32_e32 v108, v108
	v_mul_f32_e32 v104, 0xbfb8aa3b, v104
	v_exp_f32_e32 v109, v109
	v_mul_f32_e32 v105, 0xbfb8aa3b, v105
	v_exp_f32_e32 v104, v104
	v_exp_f32_e32 v105, v105
	v_add_f32_e32 v108, 1.0, v108
	v_add_f32_e32 v109, 1.0, v109
	v_rcp_f32_e32 v108, v108
	v_add_f32_e32 v104, 1.0, v104
	v_rcp_f32_e32 v109, v109
	v_add_f32_e32 v105, 1.0, v105
	v_rcp_f32_e32 v104, v104
	v_rcp_f32_e32 v105, v105
	v_lshlrev_b32_e32 v168, 16, v124
	v_and_b32_e32 v169, 0xffff0000, v124
	v_pk_mul_f32 v[108:109], v[108:109], v[168:169]
	v_lshlrev_b32_e32 v168, 16, v126
	v_and_b32_e32 v169, 0xffff0000, v126
	v_mul_f32_e32 v110, 0xbfb8aa3b, v110
	v_exp_f32_e32 v110, v110
	v_pk_mul_f32 v[168:169], v[104:105], v[168:169]
	v_mul_f32_e32 v107, 0xbfb8aa3b, v107
	v_pk_mul_f32 v[104:105], v[168:169], v[168:169]
	v_exp_f32_e32 v107, v107
	v_pk_fma_f32 v[170:171], v[108:109], v[108:109], v[104:105]
	v_mul_f32_e32 v105, 0xbfb8aa3b, v106
	v_exp_f32_e32 v105, v105
	v_mul_f32_e32 v106, 0xbfb8aa3b, v111
	v_add_f32_e32 v104, 1.0, v110
	v_exp_f32_e32 v110, v106
	v_add_f32_e32 v105, 1.0, v105
	v_rcp_f32_e32 v106, v105
	v_mul_f32_e32 v100, 0xbfb8aa3b, v100
	v_add_f32_e32 v105, 1.0, v110
	v_mul_f32_e32 v101, 0xbfb8aa3b, v101
	v_rcp_f32_e32 v104, v104
	v_rcp_f32_e32 v105, v105
	v_add_f32_e32 v107, 1.0, v107
	v_exp_f32_e32 v100, v100
	v_exp_f32_e32 v101, v101
	v_rcp_f32_e32 v107, v107
	v_lshlrev_b32_e32 v110, 16, v125
	v_and_b32_e32 v111, 0xffff0000, v125
	v_pk_mul_f32 v[110:111], v[104:105], v[110:111]
	v_lshlrev_b32_e32 v104, 16, v127
	v_and_b32_e32 v105, 0xffff0000, v127
	v_add_f32_e32 v100, 1.0, v100
	v_add_f32_e32 v101, 1.0, v101
	v_pk_mul_f32 v[124:125], v[106:107], v[104:105]
	v_rcp_f32_e32 v100, v100
	v_rcp_f32_e32 v101, v101
	v_pk_mul_f32 v[104:105], v[124:125], v[124:125]
	v_mul_f32_e32 v96, 0xbfb8aa3b, v96
	v_mul_f32_e32 v97, 0xbfb8aa3b, v97
	v_mul_f32_e32 v98, 0xbfb8aa3b, v98
	v_pk_fma_f32 v[126:127], v[110:111], v[110:111], v[104:105]
	v_cvt_pk_bf16_f32 v105, v110, v111
	v_exp_f32_e32 v96, v96
	v_exp_f32_e32 v97, v97
	v_lshlrev_b32_e32 v110, 16, v120
	v_and_b32_e32 v111, 0xffff0000, v120
	v_mul_f32_e32 v102, 0xbfb8aa3b, v102
	v_exp_f32_e32 v120, v98
	v_mul_f32_e32 v98, 0xbfb8aa3b, v103
	v_exp_f32_e32 v102, v102
	v_exp_f32_e32 v103, v98
	v_mul_f32_e32 v99, 0xbfb8aa3b, v99
	v_pk_mul_f32 v[100:101], v[100:101], v[110:111]
	v_lshlrev_b32_e32 v110, 16, v122
	v_and_b32_e32 v111, 0xffff0000, v122
	v_exp_f32_e32 v122, v99
	v_add_f32_e32 v96, 1.0, v96
	v_add_f32_e32 v97, 1.0, v97
	v_rcp_f32_e32 v96, v96
	v_rcp_f32_e32 v97, v97
	v_add_f32_e32 v102, 1.0, v102
	v_add_f32_e32 v103, 1.0, v103
	v_rcp_f32_e32 v98, v102
	v_add_f32_e32 v102, 1.0, v120
	v_rcp_f32_e32 v99, v103
	v_add_f32_e32 v103, 1.0, v122
	v_rcp_f32_e32 v102, v102
	v_rcp_f32_e32 v103, v103
	v_pk_mul_f32 v[110:111], v[96:97], v[110:111]
	v_lshlrev_b32_e32 v120, 16, v121
	v_and_b32_e32 v121, 0xffff0000, v121
	v_add_f32_e32 v122, v170, v171
	v_pk_mul_f32 v[96:97], v[110:111], v[110:111]
	v_pk_mul_f32 v[120:121], v[98:99], v[120:121]
	v_lshlrev_b32_e32 v98, 16, v123
	v_and_b32_e32 v99, 0xffff0000, v123
	v_add_f32_e32 v122, v126, v122
	v_pk_fma_f32 v[96:97], v[100:101], v[100:101], v[96:97]
	v_pk_mul_f32 v[102:103], v[102:103], v[98:99]
	v_add_f32_e32 v122, v127, v122
	v_pk_mul_f32 v[98:99], v[102:103], v[102:103]
	v_add_f32_e32 v96, v96, v122
	v_pk_fma_f32 v[98:99], v[120:121], v[120:121], v[98:99]
	v_add_f32_e32 v96, v97, v96
	v_add_f32_e32 v96, v98, v96
	v_add_f32_e32 v99, v99, v96
	ds_bpermute_b32 v122, v166, v99
	v_cvt_pk_bf16_f32 v104, v108, v109
	v_lshlrev_b64 v[108:109], 11, v[160:161]
	v_lshl_add_u64 v[96:97], s[14:15], 0, v[108:109]
	v_lshl_add_u64 v[108:109], v[96:97], 0, v[154:155]
	s_waitcnt lgkmcnt(0)
	v_add_f32_e32 v96, v99, v122
	ds_bpermute_b32 v97, v165, v96
	v_cvt_pk_bf16_f32 v106, v168, v169
	v_cvt_pk_bf16_f32 v107, v124, v125
	v_cvt_pk_bf16_f32 v98, v100, v101
	v_cvt_pk_bf16_f32 v99, v120, v121
	v_cvt_pk_bf16_f32 v100, v110, v111
	v_cvt_pk_bf16_f32 v101, v102, v103
	global_store_dwordx4 v[108:109], v[104:107], off
	global_store_dwordx4 v[108:109], v[98:101], off offset:256
	s_and_saveexec_b64 s[28:29], s[2:3]
	s_cbranch_execz .LBB0_581
	s_waitcnt lgkmcnt(0)
	v_add_f32_e32 v96, v96, v97
	v_mul_f32_e32 v96, 0x4b800000, v96
	v_trunc_f32_e32 v96, v96
	v_mul_f32_e32 v97, 0x2f800000, v96
	v_floor_f32_e32 v97, v97
	v_fmac_f32_e32 v96, 0xcf800000, v97
	v_cvt_u32_f32_e32 v96, v96
	v_cvt_u32_f32_e32 v97, v97
	v_lshl_add_u64 v[98:99], v[160:161], 3, s[16:17]
	global_atomic_add_x2 v[98:99], v[96:97], off
; __device__ __forceinline__ unsigned pk2(float lo, float hi) { f32x2_t v = {lo, hi}; bf16x2_t b = __builtin_convertvector(v, bf16x2_t); return __builtin_bit_cast(unsigned, b); }
;     __device__ __forceinline__ void operator()(const pg8::f32x4 (&acc)[2][2][4][2], const pg8::Unit& u, int wr, int wc, int fr, int fq) const {
;     ...
;             u32x4 cy[2], ny[2];
;             cy[0] = *(const u32x4*)(YG + (size_t)row0 * ldyg + col0); cy[1] = *(const u32x4*)(YG + (size_t)row0 * ldyg + col0 + 128);
; #pragma unroll
;             for (int g = 0; g < 8; ++g) {
;                 const int ai = g >> 2, m = g & 3, r = row0 + ai * 128 + m * 16;
;                 if (g < 7) {
;                     const int rn = row0 + ((g + 1) >> 2) * 128 + ((g + 1) & 3) * 16;
;                     ny[0] = *(const u32x4*)(YG + (size_t)rn * ldyg + col0); ny[1] = *(const u32x4*)(YG + (size_t)rn * ldyg + col0 + 128);
;                 }
;                 float ss = 0.f;
; #pragma unroll
;                 for (int bj = 0; bj < 2; ++bj) {
;                     const u32x4 y = cy[bj];
;                     const float yf[8] = {bflo(y.x), bfhi(y.x), bflo(y.y), bfhi(y.y), bflo(y.z), bfhi(y.z), bflo(y.w), bfhi(y.w)};
;                     f32x4 v0 = acc[ai][bj][m][0], v1 = acc[ai][bj][m][1];
; #pragma unroll
;                     for (int k = 0; k < 4; ++k) {
;                         v0[k] = yf[k] * __builtin_amdgcn_rcpf(1.f + __builtin_amdgcn_exp2f(-LOG2E * v0[k])); v1[k] = yf[4 + k] * __builtin_amdgcn_rcpf(1.f + __builtin_amdgcn_exp2f(-LOG2E * v1[k]));
;                         ss += v0[k] * v0[k] + v1[k] * v1[k];
;                     }
;                     u32x4 w; w.x = pk2(v0[0], v0[1]); w.y = pk2(v0[2], v0[3]); w.z = pk2(v1[0], v1[1]); w.w = pk2(v1[2], v1[3]);
;                     *(u32x4*)(O + (size_t)r * ldc + col0 + bj * 128) = w;
;                 }
;                 ss += __shfl_xor(ss, 16); ss += __shfl_xor(ss, 32);
;                 if (fq == 0) atomicAdd(rss + r, (u64)(ss * RSS_FIX));
;                 cy[0] = ny[0]; cy[1] = ny[1];
;             }
.LBB0_581:
	s_or_b64 exec, exec, s[28:29]
	v_or_b32_e32 v104, 48, v156
	v_ashrrev_i32_e32 v105, 31, v104
	s_waitcnt lgkmcnt(0)
	v_lshlrev_b64 v[96:97], 10, v[104:105]
	v_lshl_add_u64 v[96:97], s[8:9], 0, v[96:97]
	v_lshl_add_u64 v[96:97], v[96:97], 0, v[154:155]
	global_load_dwordx4 v[100:103], v[96:97], off
	s_nop 0
	global_load_dwordx4 v[96:99], v[96:97], off offset:256
	v_mul_f32_e32 v92, 0xbfb8aa3b, v92
	v_mul_f32_e32 v93, 0xbfb8aa3b, v93
	v_exp_f32_e32 v92, v92
	v_mul_f32_e32 v88, 0xbfb8aa3b, v88
	v_exp_f32_e32 v93, v93
	v_mul_f32_e32 v89, 0xbfb8aa3b, v89
	v_exp_f32_e32 v88, v88
	v_exp_f32_e32 v89, v89
	v_add_f32_e32 v92, 1.0, v92
	v_add_f32_e32 v93, 1.0, v93
	v_rcp_f32_e32 v92, v92
	v_add_f32_e32 v88, 1.0, v88
	v_rcp_f32_e32 v93, v93
	v_add_f32_e32 v89, 1.0, v89
	v_rcp_f32_e32 v88, v88
	v_rcp_f32_e32 v89, v89
	s_waitcnt vmcnt(5)
	v_lshlrev_b32_e32 v106, 16, v116
	v_and_b32_e32 v107, 0xffff0000, v116
	v_pk_mul_f32 v[92:93], v[92:93], v[106:107]
	v_lshlrev_b32_e32 v106, 16, v118
	v_and_b32_e32 v107, 0xffff0000, v118
	v_mul_f32_e32 v94, 0xbfb8aa3b, v94
	v_exp_f32_e32 v94, v94
	v_pk_mul_f32 v[106:107], v[88:89], v[106:107]
	v_mul_f32_e32 v91, 0xbfb8aa3b, v91
	v_pk_mul_f32 v[88:89], v[106:107], v[106:107]
	v_exp_f32_e32 v91, v91
	v_pk_fma_f32 v[108:109], v[92:93], v[92:93], v[88:89]
	v_mul_f32_e32 v89, 0xbfb8aa3b, v90
	v_exp_f32_e32 v89, v89
	v_mul_f32_e32 v90, 0xbfb8aa3b, v95
	v_add_f32_e32 v88, 1.0, v94
	v_exp_f32_e32 v94, v90
	v_add_f32_e32 v89, 1.0, v89
	v_rcp_f32_e32 v90, v89
	v_rcp_f32_e32 v88, v88
	v_add_f32_e32 v89, 1.0, v94
	v_rcp_f32_e32 v89, v89
	v_add_f32_e32 v91, 1.0, v91
	v_rcp_f32_e32 v91, v91
	v_lshlrev_b32_e32 v94, 16, v117
	v_and_b32_e32 v95, 0xffff0000, v117
	v_mul_f32_e32 v84, 0xbfb8aa3b, v84
	v_mul_f32_e32 v85, 0xbfb8aa3b, v85
	v_pk_mul_f32 v[94:95], v[88:89], v[94:95]
	v_lshlrev_b32_e32 v88, 16, v119
	v_and_b32_e32 v89, 0xffff0000, v119
	v_exp_f32_e32 v84, v84
	v_mul_f32_e32 v80, 0xbfb8aa3b, v80
	v_exp_f32_e32 v85, v85
	v_mul_f32_e32 v81, 0xbfb8aa3b, v81
	v_mul_f32_e32 v82, 0xbfb8aa3b, v82
	v_pk_mul_f32 v[110:111], v[90:91], v[88:89]
	v_cvt_pk_bf16_f32 v90, v106, v107
	v_exp_f32_e32 v80, v80
	v_exp_f32_e32 v81, v81
	v_mul_f32_e32 v86, 0xbfb8aa3b, v86
	v_exp_f32_e32 v106, v82
	v_mul_f32_e32 v82, 0xbfb8aa3b, v87
	v_exp_f32_e32 v86, v86
	v_exp_f32_e32 v87, v82
	v_mul_f32_e32 v83, 0xbfb8aa3b, v83
	v_pk_mul_f32 v[88:89], v[110:111], v[110:111]
	v_cvt_pk_bf16_f32 v91, v110, v111
	v_exp_f32_e32 v110, v83
	v_add_f32_e32 v84, 1.0, v84
	v_add_f32_e32 v85, 1.0, v85
	v_rcp_f32_e32 v84, v84
	v_add_f32_e32 v80, 1.0, v80
	v_rcp_f32_e32 v85, v85
	v_add_f32_e32 v81, 1.0, v81
	v_rcp_f32_e32 v80, v80
	v_rcp_f32_e32 v81, v81
	v_add_f32_e32 v86, 1.0, v86
	v_add_f32_e32 v87, 1.0, v87
	v_rcp_f32_e32 v82, v86
	v_add_f32_e32 v86, 1.0, v106
	v_rcp_f32_e32 v83, v87
	v_add_f32_e32 v87, 1.0, v110
	v_pk_fma_f32 v[116:117], v[94:95], v[94:95], v[88:89]
	v_cvt_pk_bf16_f32 v89, v94, v95
	s_waitcnt vmcnt(4)
	v_lshlrev_b32_e32 v94, 16, v112
	v_and_b32_e32 v95, 0xffff0000, v112
	v_rcp_f32_e32 v86, v86
	v_rcp_f32_e32 v87, v87
	v_pk_mul_f32 v[84:85], v[84:85], v[94:95]
	v_lshlrev_b32_e32 v94, 16, v114
	v_and_b32_e32 v95, 0xffff0000, v114
	v_pk_mul_f32 v[94:95], v[80:81], v[94:95]
	v_lshlrev_b32_e32 v106, 16, v113
	v_and_b32_e32 v107, 0xffff0000, v113
	v_add_f32_e32 v108, v108, v109
	v_pk_mul_f32 v[80:81], v[94:95], v[94:95]
	v_pk_mul_f32 v[106:107], v[82:83], v[106:107]
	v_lshlrev_b32_e32 v82, 16, v115
	v_and_b32_e32 v83, 0xffff0000, v115
	v_add_f32_e32 v108, v116, v108
	v_pk_fma_f32 v[80:81], v[84:85], v[84:85], v[80:81]
	v_pk_mul_f32 v[86:87], v[86:87], v[82:83]
	v_add_f32_e32 v108, v117, v108
	v_pk_mul_f32 v[82:83], v[86:87], v[86:87]
	v_add_f32_e32 v80, v80, v108
	v_pk_fma_f32 v[82:83], v[106:107], v[106:107], v[82:83]
	v_add_f32_e32 v80, v81, v80
	v_add_f32_e32 v80, v82, v80
	v_add_f32_e32 v83, v83, v80
	ds_bpermute_b32 v108, v166, v83
	v_cvt_pk_bf16_f32 v88, v92, v93
	v_lshlrev_b64 v[92:93], 11, v[158:159]
	v_lshl_add_u64 v[80:81], s[14:15], 0, v[92:93]
	v_lshl_add_u64 v[92:93], v[80:81], 0, v[154:155]
	s_waitcnt lgkmcnt(0)
	v_add_f32_e32 v80, v83, v108
	ds_bpermute_b32 v81, v165, v80
	v_cvt_pk_bf16_f32 v82, v84, v85
	v_cvt_pk_bf16_f32 v83, v106, v107
	v_cvt_pk_bf16_f32 v84, v94, v95
	v_cvt_pk_bf16_f32 v85, v86, v87
	global_store_dwordx4 v[92:93], v[88:91], off
	global_store_dwordx4 v[92:93], v[82:85], off offset:256
	s_and_saveexec_b64 s[28:29], s[2:3]
	s_cbranch_execz .LBB0_583
	s_waitcnt lgkmcnt(0)
	v_add_f32_e32 v80, v80, v81
	v_mul_f32_e32 v80, 0x4b800000, v80
	v_trunc_f32_e32 v80, v80
	v_mul_f32_e32 v81, 0x2f800000, v80
	v_floor_f32_e32 v81, v81
	v_fmac_f32_e32 v80, 0xcf800000, v81
	v_cvt_u32_f32_e32 v80, v80
	v_cvt_u32_f32_e32 v81, v81
	v_lshl_add_u64 v[82:83], v[158:159], 3, s[16:17]
	global_atomic_add_x2 v[82:83], v[80:81], off
; __device__ __forceinline__ unsigned pk2(float lo, float hi) { f32x2_t v = {lo, hi}; bf16x2_t b = __builtin_convertvector(v, bf16x2_t); return __builtin_bit_cast(unsigned, b); }
;     __device__ __forceinline__ void operator()(const pg8::f32x4 (&acc)[2][2][4][2], const pg8::Unit& u, int wr, int wc, int fr, int fq) const {
;     ...
;             u32x4 cy[2], ny[2];
;             cy[0] = *(const u32x4*)(YG + (size_t)row0 * ldyg + col0); cy[1] = *(const u32x4*)(YG + (size_t)row0 * ldyg + col0 + 128);
; #pragma unroll
;             for (int g = 0; g < 8; ++g) {
;                 const int ai = g >> 2, m = g & 3, r = row0 + ai * 128 + m * 16;
;                 if (g < 7) {
;                     const int rn = row0 + ((g + 1) >> 2) * 128 + ((g + 1) & 3) * 16;
;                     ny[0] = *(const u32x4*)(YG + (size_t)rn * ldyg + col0); ny[1] = *(const u32x4*)(YG + (size_t)rn * ldyg + col0 + 128);
;                 }
;                 float ss = 0.f;
; #pragma unroll
;                 for (int bj = 0; bj < 2; ++bj) {
;                     const u32x4 y = cy[bj];
;                     const float yf[8] = {bflo(y.x), bfhi(y.x), bflo(y.y), bfhi(y.y), bflo(y.z), bfhi(y.z), bflo(y.w), bfhi(y.w)};
;                     f32x4 v0 = acc[ai][bj][m][0], v1 = acc[ai][bj][m][1];
; #pragma unroll
;                     for (int k = 0; k < 4; ++k) {
;                         v0[k] = yf[k] * __builtin_amdgcn_rcpf(1.f + __builtin_amdgcn_exp2f(-LOG2E * v0[k])); v1[k] = yf[4 + k] * __builtin_amdgcn_rcpf(1.f + __builtin_amdgcn_exp2f(-LOG2E * v1[k]));
;                         ss += v0[k] * v0[k] + v1[k] * v1[k];
;                     }
;                     u32x4 w; w.x = pk2(v0[0], v0[1]); w.y = pk2(v0[2], v0[3]); w.z = pk2(v1[0], v1[1]); w.w = pk2(v1[2], v1[3]);
;                     *(u32x4*)(O + (size_t)r * ldc + col0 + bj * 128) = w;
;                 }
;                 ss += __shfl_xor(ss, 16); ss += __shfl_xor(ss, 32);
;                 if (fq == 0) atomicAdd(rss + r, (u64)(ss * RSS_FIX));
;                 cy[0] = ny[0]; cy[1] = ny[1];
;             }
.LBB0_583:
	s_or_b64 exec, exec, s[28:29]
	v_add_u32_e32 v88, 0x80, v156
	v_ashrrev_i32_e32 v89, 31, v88
	s_waitcnt lgkmcnt(0)
	v_lshlrev_b64 v[80:81], 10, v[88:89]
	v_lshl_add_u64 v[80:81], s[8:9], 0, v[80:81]
	v_lshl_add_u64 v[80:81], v[80:81], 0, v[154:155]
	global_load_dwordx4 v[84:87], v[80:81], off
	s_nop 0
	global_load_dwordx4 v[80:83], v[80:81], off offset:256
	v_mul_f32_e32 v76, 0xbfb8aa3b, v76
	v_mul_f32_e32 v77, 0xbfb8aa3b, v77
	v_exp_f32_e32 v76, v76
	v_mul_f32_e32 v72, 0xbfb8aa3b, v72
	v_exp_f32_e32 v77, v77
	v_mul_f32_e32 v73, 0xbfb8aa3b, v73
	v_exp_f32_e32 v72, v72
	v_exp_f32_e32 v73, v73
	v_add_f32_e32 v76, 1.0, v76
	v_add_f32_e32 v77, 1.0, v77
	v_rcp_f32_e32 v76, v76
	v_add_f32_e32 v72, 1.0, v72
	v_rcp_f32_e32 v77, v77
	v_add_f32_e32 v73, 1.0, v73
	v_rcp_f32_e32 v72, v72
	v_rcp_f32_e32 v73, v73
	s_waitcnt vmcnt(5)
	v_lshlrev_b32_e32 v90, 16, v100
	v_and_b32_e32 v91, 0xffff0000, v100
	v_pk_mul_f32 v[76:77], v[76:77], v[90:91]
	v_lshlrev_b32_e32 v90, 16, v102
	v_and_b32_e32 v91, 0xffff0000, v102
	v_mul_f32_e32 v78, 0xbfb8aa3b, v78
	v_exp_f32_e32 v78, v78
	v_pk_mul_f32 v[90:91], v[72:73], v[90:91]
	v_mul_f32_e32 v75, 0xbfb8aa3b, v75
	v_pk_mul_f32 v[72:73], v[90:91], v[90:91]
	v_exp_f32_e32 v75, v75
	v_pk_fma_f32 v[92:93], v[76:77], v[76:77], v[72:73]
	v_mul_f32_e32 v73, 0xbfb8aa3b, v74
	v_exp_f32_e32 v73, v73
	v_mul_f32_e32 v74, 0xbfb8aa3b, v79
	v_add_f32_e32 v72, 1.0, v78
	v_exp_f32_e32 v78, v74
	v_add_f32_e32 v73, 1.0, v73
	v_rcp_f32_e32 v74, v73
	v_rcp_f32_e32 v72, v72
	v_add_f32_e32 v73, 1.0, v78
	v_rcp_f32_e32 v73, v73
	v_add_f32_e32 v75, 1.0, v75
	v_rcp_f32_e32 v75, v75
	v_lshlrev_b32_e32 v78, 16, v101
	v_and_b32_e32 v79, 0xffff0000, v101
	v_mul_f32_e32 v68, 0xbfb8aa3b, v68
	v_mul_f32_e32 v69, 0xbfb8aa3b, v69
	v_pk_mul_f32 v[78:79], v[72:73], v[78:79]
	v_lshlrev_b32_e32 v72, 16, v103
	v_and_b32_e32 v73, 0xffff0000, v103
	v_exp_f32_e32 v68, v68
	v_mul_f32_e32 v64, 0xbfb8aa3b, v64
	v_exp_f32_e32 v69, v69
	v_mul_f32_e32 v65, 0xbfb8aa3b, v65
	v_mul_f32_e32 v66, 0xbfb8aa3b, v66
	v_pk_mul_f32 v[94:95], v[74:75], v[72:73]
	v_cvt_pk_bf16_f32 v74, v90, v91
	v_exp_f32_e32 v64, v64
	v_exp_f32_e32 v65, v65
	v_mul_f32_e32 v70, 0xbfb8aa3b, v70
	v_exp_f32_e32 v90, v66
	v_mul_f32_e32 v66, 0xbfb8aa3b, v71
	v_exp_f32_e32 v70, v70
	v_exp_f32_e32 v71, v66
	v_mul_f32_e32 v67, 0xbfb8aa3b, v67
	v_pk_mul_f32 v[72:73], v[94:95], v[94:95]
	v_cvt_pk_bf16_f32 v75, v94, v95
	v_exp_f32_e32 v94, v67
	v_add_f32_e32 v68, 1.0, v68
	v_add_f32_e32 v69, 1.0, v69
	v_rcp_f32_e32 v68, v68
	v_add_f32_e32 v64, 1.0, v64
	v_rcp_f32_e32 v69, v69
	v_add_f32_e32 v65, 1.0, v65
	v_rcp_f32_e32 v64, v64
	v_rcp_f32_e32 v65, v65
	v_add_f32_e32 v70, 1.0, v70
	v_add_f32_e32 v71, 1.0, v71
	v_rcp_f32_e32 v66, v70
	v_add_f32_e32 v70, 1.0, v90
	v_rcp_f32_e32 v67, v71
	v_add_f32_e32 v71, 1.0, v94
	v_pk_fma_f32 v[100:101], v[78:79], v[78:79], v[72:73]
	v_cvt_pk_bf16_f32 v73, v78, v79
	s_waitcnt vmcnt(4)
	v_lshlrev_b32_e32 v78, 16, v96
	v_and_b32_e32 v79, 0xffff0000, v96
	v_rcp_f32_e32 v70, v70
	v_rcp_f32_e32 v71, v71
	v_pk_mul_f32 v[68:69], v[68:69], v[78:79]
	v_lshlrev_b32_e32 v78, 16, v98
	v_and_b32_e32 v79, 0xffff0000, v98
	v_pk_mul_f32 v[78:79], v[64:65], v[78:79]
	v_lshlrev_b32_e32 v90, 16, v97
	v_and_b32_e32 v91, 0xffff0000, v97
	v_add_f32_e32 v92, v92, v93
	v_pk_mul_f32 v[64:65], v[78:79], v[78:79]
	v_pk_mul_f32 v[90:91], v[66:67], v[90:91]
	v_lshlrev_b32_e32 v66, 16, v99
	v_and_b32_e32 v67, 0xffff0000, v99
	v_add_f32_e32 v92, v100, v92
	v_pk_fma_f32 v[64:65], v[68:69], v[68:69], v[64:65]
	v_pk_mul_f32 v[70:71], v[70:71], v[66:67]
	v_add_f32_e32 v92, v101, v92
	v_pk_mul_f32 v[66:67], v[70:71], v[70:71]
	v_add_f32_e32 v64, v64, v92
	v_pk_fma_f32 v[66:67], v[90:91], v[90:91], v[66:67]
	v_add_f32_e32 v64, v65, v64
	v_add_f32_e32 v64, v66, v64
	v_add_f32_e32 v67, v67, v64
	ds_bpermute_b32 v92, v166, v67
	v_cvt_pk_bf16_f32 v72, v76, v77
	v_lshlrev_b64 v[76:77], 11, v[104:105]
	v_lshl_add_u64 v[64:65], s[14:15], 0, v[76:77]
	v_lshl_add_u64 v[76:77], v[64:65], 0, v[154:155]
	s_waitcnt lgkmcnt(0)
	v_add_f32_e32 v64, v67, v92
	ds_bpermute_b32 v65, v165, v64
	v_cvt_pk_bf16_f32 v66, v68, v69
	v_cvt_pk_bf16_f32 v67, v90, v91
	v_cvt_pk_bf16_f32 v68, v78, v79
	v_cvt_pk_bf16_f32 v69, v70, v71
	global_store_dwordx4 v[76:77], v[72:75], off
	global_store_dwordx4 v[76:77], v[66:69], off offset:256
	s_and_saveexec_b64 s[28:29], s[2:3]
	s_cbranch_execz .LBB0_585
	s_waitcnt lgkmcnt(0)
	v_add_f32_e32 v64, v64, v65
	v_mul_f32_e32 v64, 0x4b800000, v64
	v_trunc_f32_e32 v64, v64
	v_mul_f32_e32 v65, 0x2f800000, v64
	v_floor_f32_e32 v65, v65
	v_fmac_f32_e32 v64, 0xcf800000, v65
	v_cvt_u32_f32_e32 v64, v64
	v_cvt_u32_f32_e32 v65, v65
	v_lshl_add_u64 v[66:67], v[104:105], 3, s[16:17]
	global_atomic_add_x2 v[66:67], v[64:65], off
; __device__ __forceinline__ unsigned pk2(float lo, float hi) { f32x2_t v = {lo, hi}; bf16x2_t b = __builtin_convertvector(v, bf16x2_t); return __builtin_bit_cast(unsigned, b); }
;     __device__ __forceinline__ void operator()(const pg8::f32x4 (&acc)[2][2][4][2], const pg8::Unit& u, int wr, int wc, int fr, int fq) const {
;     ...
;             u32x4 cy[2], ny[2];
;             cy[0] = *(const u32x4*)(YG + (size_t)row0 * ldyg + col0); cy[1] = *(const u32x4*)(YG + (size_t)row0 * ldyg + col0 + 128);
; #pragma unroll
;             for (int g = 0; g < 8; ++g) {
;                 const int ai = g >> 2, m = g & 3, r = row0 + ai * 128 + m * 16;
;                 if (g < 7) {
;                     const int rn = row0 + ((g + 1) >> 2) * 128 + ((g + 1) & 3) * 16;
;                     ny[0] = *(const u32x4*)(YG + (size_t)rn * ldyg + col0); ny[1] = *(const u32x4*)(YG + (size_t)rn * ldyg + col0 + 128);
;                 }
;                 float ss = 0.f;
; #pragma unroll
;                 for (int bj = 0; bj < 2; ++bj) {
;                     const u32x4 y = cy[bj];
;                     const float yf[8] = {bflo(y.x), bfhi(y.x), bflo(y.y), bfhi(y.y), bflo(y.z), bfhi(y.z), bflo(y.w), bfhi(y.w)};
;                     f32x4 v0 = acc[ai][bj][m][0], v1 = acc[ai][bj][m][1];
; #pragma unroll
;                     for (int k = 0; k < 4; ++k) {
;                         v0[k] = yf[k] * __builtin_amdgcn_rcpf(1.f + __builtin_amdgcn_exp2f(-LOG2E * v0[k])); v1[k] = yf[4 + k] * __builtin_amdgcn_rcpf(1.f + __builtin_amdgcn_exp2f(-LOG2E * v1[k]));
;                         ss += v0[k] * v0[k] + v1[k] * v1[k];
;                     }
;                     u32x4 w; w.x = pk2(v0[0], v0[1]); w.y = pk2(v0[2], v0[3]); w.z = pk2(v1[0], v1[1]); w.w = pk2(v1[2], v1[3]);
;                     *(u32x4*)(O + (size_t)r * ldc + col0 + bj * 128) = w;
;                 }
;                 ss += __shfl_xor(ss, 16); ss += __shfl_xor(ss, 32);
;                 if (fq == 0) atomicAdd(rss + r, (u64)(ss * RSS_FIX));
;                 cy[0] = ny[0]; cy[1] = ny[1];
;             }
.LBB0_585:
	s_or_b64 exec, exec, s[28:29]
	v_or_b32_e32 v72, 16, v88
	v_ashrrev_i32_e32 v73, 31, v72
	s_waitcnt lgkmcnt(0)
	v_lshlrev_b64 v[64:65], 10, v[72:73]
	v_lshl_add_u64 v[64:65], s[8:9], 0, v[64:65]
	v_lshl_add_u64 v[64:65], v[64:65], 0, v[154:155]
	global_load_dwordx4 v[68:71], v[64:65], off
	s_nop 0
	global_load_dwordx4 v[64:67], v[64:65], off offset:256
	v_mul_f32_e32 v60, 0xbfb8aa3b, v60
	v_mul_f32_e32 v61, 0xbfb8aa3b, v61
	v_exp_f32_e32 v60, v60
	v_mul_f32_e32 v56, 0xbfb8aa3b, v56
	v_exp_f32_e32 v61, v61
	v_mul_f32_e32 v57, 0xbfb8aa3b, v57
	v_exp_f32_e32 v56, v56
	v_exp_f32_e32 v57, v57
	v_add_f32_e32 v60, 1.0, v60
	v_add_f32_e32 v61, 1.0, v61
	v_rcp_f32_e32 v60, v60
	v_add_f32_e32 v56, 1.0, v56
	v_rcp_f32_e32 v61, v61
	v_add_f32_e32 v57, 1.0, v57
	v_rcp_f32_e32 v56, v56
	v_rcp_f32_e32 v57, v57
	s_waitcnt vmcnt(5)
	v_lshlrev_b32_e32 v74, 16, v84
	v_and_b32_e32 v75, 0xffff0000, v84
	v_pk_mul_f32 v[60:61], v[60:61], v[74:75]
	v_lshlrev_b32_e32 v74, 16, v86
	v_and_b32_e32 v75, 0xffff0000, v86
	v_mul_f32_e32 v62, 0xbfb8aa3b, v62
	v_exp_f32_e32 v62, v62
	v_pk_mul_f32 v[74:75], v[56:57], v[74:75]
	v_mul_f32_e32 v59, 0xbfb8aa3b, v59
	v_pk_mul_f32 v[56:57], v[74:75], v[74:75]
	v_exp_f32_e32 v59, v59
	v_pk_fma_f32 v[76:77], v[60:61], v[60:61], v[56:57]
	v_mul_f32_e32 v57, 0xbfb8aa3b, v58
	v_exp_f32_e32 v57, v57
	v_mul_f32_e32 v58, 0xbfb8aa3b, v63
	v_add_f32_e32 v56, 1.0, v62
	v_exp_f32_e32 v62, v58
	v_add_f32_e32 v57, 1.0, v57
	v_rcp_f32_e32 v58, v57
	v_rcp_f32_e32 v56, v56
	v_add_f32_e32 v57, 1.0, v62
	v_rcp_f32_e32 v57, v57
	v_add_f32_e32 v59, 1.0, v59
	v_rcp_f32_e32 v59, v59
	v_lshlrev_b32_e32 v62, 16, v85
	v_and_b32_e32 v63, 0xffff0000, v85
	v_mul_f32_e32 v52, 0xbfb8aa3b, v52
	v_mul_f32_e32 v53, 0xbfb8aa3b, v53
	v_pk_mul_f32 v[62:63], v[56:57], v[62:63]
	v_lshlrev_b32_e32 v56, 16, v87
	v_and_b32_e32 v57, 0xffff0000, v87
	v_exp_f32_e32 v52, v52
	v_mul_f32_e32 v48, 0xbfb8aa3b, v48
	v_exp_f32_e32 v53, v53
	v_mul_f32_e32 v49, 0xbfb8aa3b, v49
	v_mul_f32_e32 v50, 0xbfb8aa3b, v50
	v_pk_mul_f32 v[78:79], v[58:59], v[56:57]
	v_cvt_pk_bf16_f32 v58, v74, v75
	v_exp_f32_e32 v48, v48
	v_exp_f32_e32 v49, v49
	v_mul_f32_e32 v54, 0xbfb8aa3b, v54
	v_exp_f32_e32 v74, v50
	v_mul_f32_e32 v50, 0xbfb8aa3b, v55
	v_exp_f32_e32 v54, v54
	v_exp_f32_e32 v55, v50
	v_mul_f32_e32 v51, 0xbfb8aa3b, v51
	v_pk_mul_f32 v[56:57], v[78:79], v[78:79]
	v_cvt_pk_bf16_f32 v59, v78, v79
	v_exp_f32_e32 v78, v51
	v_add_f32_e32 v52, 1.0, v52
	v_add_f32_e32 v53, 1.0, v53
	v_rcp_f32_e32 v52, v52
	v_add_f32_e32 v48, 1.0, v48
	v_rcp_f32_e32 v53, v53
	v_add_f32_e32 v49, 1.0, v49
	v_rcp_f32_e32 v48, v48
	v_rcp_f32_e32 v49, v49
	v_add_f32_e32 v54, 1.0, v54
	v_add_f32_e32 v55, 1.0, v55
	v_rcp_f32_e32 v50, v54
	v_add_f32_e32 v54, 1.0, v74
	v_rcp_f32_e32 v51, v55
	v_add_f32_e32 v55, 1.0, v78
	v_pk_fma_f32 v[84:85], v[62:63], v[62:63], v[56:57]
	v_cvt_pk_bf16_f32 v57, v62, v63
	s_waitcnt vmcnt(4)
	v_lshlrev_b32_e32 v62, 16, v80
	v_and_b32_e32 v63, 0xffff0000, v80
	v_rcp_f32_e32 v54, v54
	v_rcp_f32_e32 v55, v55
	v_pk_mul_f32 v[52:53], v[52:53], v[62:63]
	v_lshlrev_b32_e32 v62, 16, v82
	v_and_b32_e32 v63, 0xffff0000, v82
	v_pk_mul_f32 v[62:63], v[48:49], v[62:63]
	v_lshlrev_b32_e32 v74, 16, v81
	v_and_b32_e32 v75, 0xffff0000, v81
	v_add_f32_e32 v76, v76, v77
	v_pk_mul_f32 v[48:49], v[62:63], v[62:63]
	v_pk_mul_f32 v[74:75], v[50:51], v[74:75]
	v_lshlrev_b32_e32 v50, 16, v83
	v_and_b32_e32 v51, 0xffff0000, v83
	v_add_f32_e32 v76, v84, v76
	v_pk_fma_f32 v[48:49], v[52:53], v[52:53], v[48:49]
	v_pk_mul_f32 v[54:55], v[54:55], v[50:51]
	v_add_f32_e32 v76, v85, v76
	v_pk_mul_f32 v[50:51], v[54:55], v[54:55]
	v_add_f32_e32 v48, v48, v76
	v_pk_fma_f32 v[50:51], v[74:75], v[74:75], v[50:51]
	v_add_f32_e32 v48, v49, v48
	v_add_f32_e32 v48, v50, v48
	v_add_f32_e32 v51, v51, v48
	ds_bpermute_b32 v76, v166, v51
	v_cvt_pk_bf16_f32 v56, v60, v61
	v_lshlrev_b64 v[60:61], 11, v[88:89]
	v_lshl_add_u64 v[48:49], s[14:15], 0, v[60:61]
	v_lshl_add_u64 v[60:61], v[48:49], 0, v[154:155]
	s_waitcnt lgkmcnt(0)
	v_add_f32_e32 v48, v51, v76
	ds_bpermute_b32 v49, v165, v48
	v_cvt_pk_bf16_f32 v50, v52, v53
	v_cvt_pk_bf16_f32 v51, v74, v75
	v_cvt_pk_bf16_f32 v52, v62, v63
	v_cvt_pk_bf16_f32 v53, v54, v55
	global_store_dwordx4 v[60:61], v[56:59], off
	global_store_dwordx4 v[60:61], v[50:53], off offset:256
	s_and_saveexec_b64 s[28:29], s[2:3]
	s_cbranch_execz .LBB0_587
	s_waitcnt lgkmcnt(0)
	v_add_f32_e32 v48, v48, v49
	v_mul_f32_e32 v48, 0x4b800000, v48
	v_trunc_f32_e32 v48, v48
	v_mul_f32_e32 v49, 0x2f800000, v48
	v_floor_f32_e32 v49, v49
	v_fmac_f32_e32 v48, 0xcf800000, v49
	v_cvt_u32_f32_e32 v48, v48
	v_cvt_u32_f32_e32 v49, v49
	v_lshl_add_u64 v[50:51], v[88:89], 3, s[16:17]
	global_atomic_add_x2 v[50:51], v[48:49], off
; __device__ __forceinline__ unsigned pk2(float lo, float hi) { f32x2_t v = {lo, hi}; bf16x2_t b = __builtin_convertvector(v, bf16x2_t); return __builtin_bit_cast(unsigned, b); }
;     __device__ __forceinline__ void operator()(const pg8::f32x4 (&acc)[2][2][4][2], const pg8::Unit& u, int wr, int wc, int fr, int fq) const {
;     ...
;             u32x4 cy[2], ny[2];
;             cy[0] = *(const u32x4*)(YG + (size_t)row0 * ldyg + col0); cy[1] = *(const u32x4*)(YG + (size_t)row0 * ldyg + col0 + 128);
; #pragma unroll
;             for (int g = 0; g < 8; ++g) {
;                 const int ai = g >> 2, m = g & 3, r = row0 + ai * 128 + m * 16;
;                 if (g < 7) {
;                     const int rn = row0 + ((g + 1) >> 2) * 128 + ((g + 1) & 3) * 16;
;                     ny[0] = *(const u32x4*)(YG + (size_t)rn * ldyg + col0); ny[1] = *(const u32x4*)(YG + (size_t)rn * ldyg + col0 + 128);
;                 }
;                 float ss = 0.f;
; #pragma unroll
;                 for (int bj = 0; bj < 2; ++bj) {
;                     const u32x4 y = cy[bj];
;                     const float yf[8] = {bflo(y.x), bfhi(y.x), bflo(y.y), bfhi(y.y), bflo(y.z), bfhi(y.z), bflo(y.w), bfhi(y.w)};
;                     f32x4 v0 = acc[ai][bj][m][0], v1 = acc[ai][bj][m][1];
; #pragma unroll
;                     for (int k = 0; k < 4; ++k) {
;                         v0[k] = yf[k] * __builtin_amdgcn_rcpf(1.f + __builtin_amdgcn_exp2f(-LOG2E * v0[k])); v1[k] = yf[4 + k] * __builtin_amdgcn_rcpf(1.f + __builtin_amdgcn_exp2f(-LOG2E * v1[k]));
;                         ss += v0[k] * v0[k] + v1[k] * v1[k];
;                     }
;                     u32x4 w; w.x = pk2(v0[0], v0[1]); w.y = pk2(v0[2], v0[3]); w.z = pk2(v1[0], v1[1]); w.w = pk2(v1[2], v1[3]);
;                     *(u32x4*)(O + (size_t)r * ldc + col0 + bj * 128) = w;
;                 }
;                 ss += __shfl_xor(ss, 16); ss += __shfl_xor(ss, 32);
;                 if (fq == 0) atomicAdd(rss + r, (u64)(ss * RSS_FIX));
;                 cy[0] = ny[0]; cy[1] = ny[1];
;             }
.LBB0_587:
	s_or_b64 exec, exec, s[28:29]
	v_or_b32_e32 v56, 32, v88
	v_ashrrev_i32_e32 v57, 31, v56
	s_waitcnt lgkmcnt(0)
	v_lshlrev_b64 v[48:49], 10, v[56:57]
	v_lshl_add_u64 v[48:49], s[8:9], 0, v[48:49]
	v_lshl_add_u64 v[48:49], v[48:49], 0, v[154:155]
	global_load_dwordx4 v[52:55], v[48:49], off
	s_nop 0
	global_load_dwordx4 v[48:51], v[48:49], off offset:256
	v_mul_f32_e32 v44, 0xbfb8aa3b, v44
	v_mul_f32_e32 v45, 0xbfb8aa3b, v45
	v_exp_f32_e32 v44, v44
	v_mul_f32_e32 v40, 0xbfb8aa3b, v40
	v_exp_f32_e32 v45, v45
	v_mul_f32_e32 v41, 0xbfb8aa3b, v41
	v_exp_f32_e32 v40, v40
	v_exp_f32_e32 v41, v41
	v_add_f32_e32 v44, 1.0, v44
	v_add_f32_e32 v45, 1.0, v45
	v_rcp_f32_e32 v44, v44
	v_add_f32_e32 v40, 1.0, v40
	v_rcp_f32_e32 v45, v45
	v_add_f32_e32 v41, 1.0, v41
	v_rcp_f32_e32 v40, v40
	v_rcp_f32_e32 v41, v41
	s_waitcnt vmcnt(5)
	v_lshlrev_b32_e32 v58, 16, v68
	v_and_b32_e32 v59, 0xffff0000, v68
	v_pk_mul_f32 v[44:45], v[44:45], v[58:59]
	v_lshlrev_b32_e32 v58, 16, v70
	v_and_b32_e32 v59, 0xffff0000, v70
	v_mul_f32_e32 v46, 0xbfb8aa3b, v46
	v_exp_f32_e32 v46, v46
	v_pk_mul_f32 v[58:59], v[40:41], v[58:59]
	v_mul_f32_e32 v43, 0xbfb8aa3b, v43
	v_pk_mul_f32 v[40:41], v[58:59], v[58:59]
	v_exp_f32_e32 v43, v43
	v_pk_fma_f32 v[60:61], v[44:45], v[44:45], v[40:41]
	v_mul_f32_e32 v41, 0xbfb8aa3b, v42
	v_exp_f32_e32 v41, v41
	v_mul_f32_e32 v42, 0xbfb8aa3b, v47
	v_add_f32_e32 v40, 1.0, v46
	v_exp_f32_e32 v46, v42
	v_add_f32_e32 v41, 1.0, v41
	v_rcp_f32_e32 v42, v41
	v_rcp_f32_e32 v40, v40
	v_add_f32_e32 v41, 1.0, v46
	v_rcp_f32_e32 v41, v41
	v_add_f32_e32 v43, 1.0, v43
	v_rcp_f32_e32 v43, v43
	v_lshlrev_b32_e32 v46, 16, v69
	v_and_b32_e32 v47, 0xffff0000, v69
	v_mul_f32_e32 v36, 0xbfb8aa3b, v36
	v_mul_f32_e32 v37, 0xbfb8aa3b, v37
	v_pk_mul_f32 v[46:47], v[40:41], v[46:47]
	v_lshlrev_b32_e32 v40, 16, v71
	v_and_b32_e32 v41, 0xffff0000, v71
	v_exp_f32_e32 v36, v36
	v_mul_f32_e32 v32, 0xbfb8aa3b, v32
	v_exp_f32_e32 v37, v37
	v_mul_f32_e32 v33, 0xbfb8aa3b, v33
	v_mul_f32_e32 v34, 0xbfb8aa3b, v34
	v_pk_mul_f32 v[62:63], v[42:43], v[40:41]
	v_cvt_pk_bf16_f32 v42, v58, v59
	v_exp_f32_e32 v32, v32
	v_exp_f32_e32 v33, v33
	v_mul_f32_e32 v38, 0xbfb8aa3b, v38
	v_exp_f32_e32 v58, v34
	v_mul_f32_e32 v34, 0xbfb8aa3b, v39
	v_exp_f32_e32 v38, v38
	v_exp_f32_e32 v39, v34
	v_mul_f32_e32 v35, 0xbfb8aa3b, v35
	v_pk_mul_f32 v[40:41], v[62:63], v[62:63]
	v_cvt_pk_bf16_f32 v43, v62, v63
	v_exp_f32_e32 v62, v35
	v_add_f32_e32 v36, 1.0, v36
	v_add_f32_e32 v37, 1.0, v37
	v_rcp_f32_e32 v36, v36
	v_add_f32_e32 v32, 1.0, v32
	v_rcp_f32_e32 v37, v37
	v_add_f32_e32 v33, 1.0, v33
	v_rcp_f32_e32 v32, v32
	v_rcp_f32_e32 v33, v33
	v_add_f32_e32 v38, 1.0, v38
	v_add_f32_e32 v39, 1.0, v39
	v_rcp_f32_e32 v34, v38
	v_add_f32_e32 v38, 1.0, v58
	v_rcp_f32_e32 v35, v39
	v_add_f32_e32 v39, 1.0, v62
	v_pk_fma_f32 v[68:69], v[46:47], v[46:47], v[40:41]
	v_cvt_pk_bf16_f32 v41, v46, v47
	s_waitcnt vmcnt(4)
	v_lshlrev_b32_e32 v46, 16, v64
	v_and_b32_e32 v47, 0xffff0000, v64
	v_rcp_f32_e32 v38, v38
	v_rcp_f32_e32 v39, v39
	v_pk_mul_f32 v[36:37], v[36:37], v[46:47]
	v_lshlrev_b32_e32 v46, 16, v66
	v_and_b32_e32 v47, 0xffff0000, v66
	v_pk_mul_f32 v[46:47], v[32:33], v[46:47]
	v_lshlrev_b32_e32 v58, 16, v65
	v_and_b32_e32 v59, 0xffff0000, v65
	v_add_f32_e32 v60, v60, v61
	v_pk_mul_f32 v[32:33], v[46:47], v[46:47]
	v_pk_mul_f32 v[58:59], v[34:35], v[58:59]
	v_lshlrev_b32_e32 v34, 16, v67
	v_and_b32_e32 v35, 0xffff0000, v67
	v_add_f32_e32 v60, v68, v60
	v_pk_fma_f32 v[32:33], v[36:37], v[36:37], v[32:33]
	v_pk_mul_f32 v[38:39], v[38:39], v[34:35]
	v_add_f32_e32 v60, v69, v60
	v_pk_mul_f32 v[34:35], v[38:39], v[38:39]
	v_add_f32_e32 v32, v32, v60
	v_pk_fma_f32 v[34:35], v[58:59], v[58:59], v[34:35]
	v_add_f32_e32 v32, v33, v32
	v_add_f32_e32 v32, v34, v32
	v_add_f32_e32 v35, v35, v32
	ds_bpermute_b32 v60, v166, v35
	v_cvt_pk_bf16_f32 v40, v44, v45
	v_lshlrev_b64 v[44:45], 11, v[72:73]
	v_lshl_add_u64 v[32:33], s[14:15], 0, v[44:45]
	v_lshl_add_u64 v[44:45], v[32:33], 0, v[154:155]
	s_waitcnt lgkmcnt(0)
	v_add_f32_e32 v32, v35, v60
	ds_bpermute_b32 v33, v165, v32
	v_cvt_pk_bf16_f32 v34, v36, v37
	v_cvt_pk_bf16_f32 v35, v58, v59
	v_cvt_pk_bf16_f32 v36, v46, v47
	v_cvt_pk_bf16_f32 v37, v38, v39
	global_store_dwordx4 v[44:45], v[40:43], off
	global_store_dwordx4 v[44:45], v[34:37], off offset:256
	s_and_saveexec_b64 s[28:29], s[2:3]
	s_cbranch_execz .LBB0_589
	s_waitcnt lgkmcnt(0)
	v_add_f32_e32 v32, v32, v33
	v_mul_f32_e32 v32, 0x4b800000, v32
	v_trunc_f32_e32 v32, v32
	v_mul_f32_e32 v33, 0x2f800000, v32
	v_floor_f32_e32 v33, v33
	v_fmac_f32_e32 v32, 0xcf800000, v33
	v_cvt_u32_f32_e32 v32, v32
	v_cvt_u32_f32_e32 v33, v33
	v_lshl_add_u64 v[34:35], v[72:73], 3, s[16:17]
	global_atomic_add_x2 v[34:35], v[32:33], off
; __device__ __forceinline__ unsigned pk2(float lo, float hi) { f32x2_t v = {lo, hi}; bf16x2_t b = __builtin_convertvector(v, bf16x2_t); return __builtin_bit_cast(unsigned, b); }
;     __device__ __forceinline__ void operator()(const pg8::f32x4 (&acc)[2][2][4][2], const pg8::Unit& u, int wr, int wc, int fr, int fq) const {
;     ...
;             u32x4 cy[2], ny[2];
;             cy[0] = *(const u32x4*)(YG + (size_t)row0 * ldyg + col0); cy[1] = *(const u32x4*)(YG + (size_t)row0 * ldyg + col0 + 128);
; #pragma unroll
;             for (int g = 0; g < 8; ++g) {
;                 const int ai = g >> 2, m = g & 3, r = row0 + ai * 128 + m * 16;
;                 if (g < 7) {
;                     const int rn = row0 + ((g + 1) >> 2) * 128 + ((g + 1) & 3) * 16;
;                     ny[0] = *(const u32x4*)(YG + (size_t)rn * ldyg + col0); ny[1] = *(const u32x4*)(YG + (size_t)rn * ldyg + col0 + 128);
;                 }
;                 float ss = 0.f;
; #pragma unroll
;                 for (int bj = 0; bj < 2; ++bj) {
;                     const u32x4 y = cy[bj];
;                     const float yf[8] = {bflo(y.x), bfhi(y.x), bflo(y.y), bfhi(y.y), bflo(y.z), bfhi(y.z), bflo(y.w), bfhi(y.w)};
;                     f32x4 v0 = acc[ai][bj][m][0], v1 = acc[ai][bj][m][1];
; #pragma unroll
;                     for (int k = 0; k < 4; ++k) {
;                         v0[k] = yf[k] * __builtin_amdgcn_rcpf(1.f + __builtin_amdgcn_exp2f(-LOG2E * v0[k])); v1[k] = yf[4 + k] * __builtin_amdgcn_rcpf(1.f + __builtin_amdgcn_exp2f(-LOG2E * v1[k]));
;                         ss += v0[k] * v0[k] + v1[k] * v1[k];
;                     }
;                     u32x4 w; w.x = pk2(v0[0], v0[1]); w.y = pk2(v0[2], v0[3]); w.z = pk2(v1[0], v1[1]); w.w = pk2(v1[2], v1[3]);
;                     *(u32x4*)(O + (size_t)r * ldc + col0 + bj * 128) = w;
;                 }
;                 ss += __shfl_xor(ss, 16); ss += __shfl_xor(ss, 32);
;                 if (fq == 0) atomicAdd(rss + r, (u64)(ss * RSS_FIX));
;                 cy[0] = ny[0]; cy[1] = ny[1];
;             }
.LBB0_589:
	s_or_b64 exec, exec, s[28:29]
	v_or_b32_e32 v40, 48, v88
	v_ashrrev_i32_e32 v41, 31, v40
	s_waitcnt lgkmcnt(0)
	v_lshlrev_b64 v[32:33], 10, v[40:41]
	v_lshl_add_u64 v[32:33], s[8:9], 0, v[32:33]
	v_lshl_add_u64 v[32:33], v[32:33], 0, v[154:155]
	global_load_dwordx4 v[36:39], v[32:33], off
	s_nop 0
	global_load_dwordx4 v[32:35], v[32:33], off offset:256
	v_mul_f32_e32 v28, 0xbfb8aa3b, v28
	v_mul_f32_e32 v29, 0xbfb8aa3b, v29
	v_exp_f32_e32 v28, v28
	v_mul_f32_e32 v24, 0xbfb8aa3b, v24
	v_exp_f32_e32 v29, v29
	v_mul_f32_e32 v25, 0xbfb8aa3b, v25
	v_exp_f32_e32 v24, v24
	v_exp_f32_e32 v25, v25
	v_add_f32_e32 v28, 1.0, v28
	v_add_f32_e32 v29, 1.0, v29
	v_rcp_f32_e32 v28, v28
	v_add_f32_e32 v24, 1.0, v24
	v_rcp_f32_e32 v29, v29
	v_add_f32_e32 v25, 1.0, v25
	v_rcp_f32_e32 v24, v24
	v_rcp_f32_e32 v25, v25
	s_waitcnt vmcnt(5)
	v_lshlrev_b32_e32 v42, 16, v52
	v_and_b32_e32 v43, 0xffff0000, v52
	v_pk_mul_f32 v[28:29], v[28:29], v[42:43]
	v_lshlrev_b32_e32 v42, 16, v54
	v_and_b32_e32 v43, 0xffff0000, v54
	v_mul_f32_e32 v30, 0xbfb8aa3b, v30
	v_exp_f32_e32 v30, v30
	v_pk_mul_f32 v[42:43], v[24:25], v[42:43]
	v_mul_f32_e32 v27, 0xbfb8aa3b, v27
	v_pk_mul_f32 v[24:25], v[42:43], v[42:43]
	v_exp_f32_e32 v27, v27
	v_pk_fma_f32 v[44:45], v[28:29], v[28:29], v[24:25]
	v_mul_f32_e32 v25, 0xbfb8aa3b, v26
	v_exp_f32_e32 v25, v25
	v_mul_f32_e32 v26, 0xbfb8aa3b, v31
	v_add_f32_e32 v24, 1.0, v30
	v_exp_f32_e32 v30, v26
	v_add_f32_e32 v25, 1.0, v25
	v_rcp_f32_e32 v26, v25
	v_rcp_f32_e32 v24, v24
	v_add_f32_e32 v25, 1.0, v30
	v_rcp_f32_e32 v25, v25
	v_add_f32_e32 v27, 1.0, v27
	v_rcp_f32_e32 v27, v27
	v_lshlrev_b32_e32 v30, 16, v53
	v_and_b32_e32 v31, 0xffff0000, v53
	v_mul_f32_e32 v20, 0xbfb8aa3b, v20
	v_mul_f32_e32 v21, 0xbfb8aa3b, v21
	v_pk_mul_f32 v[30:31], v[24:25], v[30:31]
	v_lshlrev_b32_e32 v24, 16, v55
	v_and_b32_e32 v25, 0xffff0000, v55
	v_exp_f32_e32 v20, v20
	v_mul_f32_e32 v16, 0xbfb8aa3b, v16
	v_exp_f32_e32 v21, v21
	v_mul_f32_e32 v17, 0xbfb8aa3b, v17
	v_mul_f32_e32 v18, 0xbfb8aa3b, v18
	v_pk_mul_f32 v[46:47], v[26:27], v[24:25]
	v_cvt_pk_bf16_f32 v26, v42, v43
	v_exp_f32_e32 v16, v16
	v_exp_f32_e32 v17, v17
	v_mul_f32_e32 v22, 0xbfb8aa3b, v22
	v_exp_f32_e32 v42, v18
	v_mul_f32_e32 v18, 0xbfb8aa3b, v23
	v_exp_f32_e32 v22, v22
	v_exp_f32_e32 v23, v18
	v_mul_f32_e32 v19, 0xbfb8aa3b, v19
	v_pk_mul_f32 v[24:25], v[46:47], v[46:47]
	v_cvt_pk_bf16_f32 v27, v46, v47
	v_exp_f32_e32 v46, v19
	v_add_f32_e32 v20, 1.0, v20
	v_add_f32_e32 v21, 1.0, v21
	v_rcp_f32_e32 v20, v20
	v_add_f32_e32 v16, 1.0, v16
	v_rcp_f32_e32 v21, v21
	v_add_f32_e32 v17, 1.0, v17
	v_rcp_f32_e32 v16, v16
	v_rcp_f32_e32 v17, v17
	v_add_f32_e32 v22, 1.0, v22
	v_add_f32_e32 v23, 1.0, v23
	v_rcp_f32_e32 v18, v22
	v_add_f32_e32 v22, 1.0, v42
	v_rcp_f32_e32 v19, v23
	v_add_f32_e32 v23, 1.0, v46
	v_pk_fma_f32 v[52:53], v[30:31], v[30:31], v[24:25]
	v_cvt_pk_bf16_f32 v25, v30, v31
	s_waitcnt vmcnt(4)
	v_lshlrev_b32_e32 v30, 16, v48
	v_and_b32_e32 v31, 0xffff0000, v48
	v_rcp_f32_e32 v22, v22
	v_rcp_f32_e32 v23, v23
	v_pk_mul_f32 v[20:21], v[20:21], v[30:31]
	v_lshlrev_b32_e32 v30, 16, v50
	v_and_b32_e32 v31, 0xffff0000, v50
	v_pk_mul_f32 v[30:31], v[16:17], v[30:31]
	v_lshlrev_b32_e32 v42, 16, v49
	v_and_b32_e32 v43, 0xffff0000, v49
	v_add_f32_e32 v44, v44, v45
	v_pk_mul_f32 v[16:17], v[30:31], v[30:31]
	v_pk_mul_f32 v[42:43], v[18:19], v[42:43]
	v_lshlrev_b32_e32 v18, 16, v51
	v_and_b32_e32 v19, 0xffff0000, v51
	v_add_f32_e32 v44, v52, v44
	v_pk_fma_f32 v[16:17], v[20:21], v[20:21], v[16:17]
	v_pk_mul_f32 v[22:23], v[22:23], v[18:19]
	v_add_f32_e32 v44, v53, v44
	v_pk_mul_f32 v[18:19], v[22:23], v[22:23]
	v_add_f32_e32 v16, v16, v44
	v_pk_fma_f32 v[18:19], v[42:43], v[42:43], v[18:19]
	v_add_f32_e32 v16, v17, v16
	v_add_f32_e32 v16, v18, v16
	v_add_f32_e32 v19, v19, v16
	ds_bpermute_b32 v44, v166, v19
	v_cvt_pk_bf16_f32 v24, v28, v29
	v_lshlrev_b64 v[28:29], 11, v[56:57]
	v_lshl_add_u64 v[16:17], s[14:15], 0, v[28:29]
	v_lshl_add_u64 v[28:29], v[16:17], 0, v[154:155]
	s_waitcnt lgkmcnt(0)
	v_add_f32_e32 v16, v19, v44
	ds_bpermute_b32 v17, v165, v16
	v_cvt_pk_bf16_f32 v18, v20, v21
	v_cvt_pk_bf16_f32 v19, v42, v43
	v_cvt_pk_bf16_f32 v20, v30, v31
	v_cvt_pk_bf16_f32 v21, v22, v23
	global_store_dwordx4 v[28:29], v[24:27], off
	global_store_dwordx4 v[28:29], v[18:21], off offset:256
	s_and_saveexec_b64 s[28:29], s[2:3]
	s_cbranch_execz .LBB0_591
	s_waitcnt lgkmcnt(0)
	v_add_f32_e32 v16, v16, v17
	v_mul_f32_e32 v16, 0x4b800000, v16
	v_trunc_f32_e32 v16, v16
	v_mul_f32_e32 v17, 0x2f800000, v16
	v_floor_f32_e32 v17, v17
	v_fmac_f32_e32 v16, 0xcf800000, v17
	v_cvt_u32_f32_e32 v16, v16
	v_cvt_u32_f32_e32 v17, v17
	v_lshl_add_u64 v[18:19], v[56:57], 3, s[16:17]
	global_atomic_add_x2 v[18:19], v[16:17], off
; __device__ __forceinline__ unsigned pk2(float lo, float hi) { f32x2_t v = {lo, hi}; bf16x2_t b = __builtin_convertvector(v, bf16x2_t); return __builtin_bit_cast(unsigned, b); }
;     __device__ __forceinline__ void operator()(const pg8::f32x4 (&acc)[2][2][4][2], const pg8::Unit& u, int wr, int wc, int fr, int fq) const {
;     ...
;             u32x4 cy[2], ny[2];
;             cy[0] = *(const u32x4*)(YG + (size_t)row0 * ldyg + col0); cy[1] = *(const u32x4*)(YG + (size_t)row0 * ldyg + col0 + 128);
; #pragma unroll
;             for (int g = 0; g < 8; ++g) {
;                 const int ai = g >> 2, m = g & 3, r = row0 + ai * 128 + m * 16;
;                 if (g < 7) {
;                     const int rn = row0 + ((g + 1) >> 2) * 128 + ((g + 1) & 3) * 16;
;                     ny[0] = *(const u32x4*)(YG + (size_t)rn * ldyg + col0); ny[1] = *(const u32x4*)(YG + (size_t)rn * ldyg + col0 + 128);
;                 }
;                 float ss = 0.f;
; #pragma unroll
;                 for (int bj = 0; bj < 2; ++bj) {
;                     const u32x4 y = cy[bj];
;                     const float yf[8] = {bflo(y.x), bfhi(y.x), bflo(y.y), bfhi(y.y), bflo(y.z), bfhi(y.z), bflo(y.w), bfhi(y.w)};
;                     f32x4 v0 = acc[ai][bj][m][0], v1 = acc[ai][bj][m][1];
; #pragma unroll
;                     for (int k = 0; k < 4; ++k) {
;                         v0[k] = yf[k] * __builtin_amdgcn_rcpf(1.f + __builtin_amdgcn_exp2f(-LOG2E * v0[k])); v1[k] = yf[4 + k] * __builtin_amdgcn_rcpf(1.f + __builtin_amdgcn_exp2f(-LOG2E * v1[k]));
;                         ss += v0[k] * v0[k] + v1[k] * v1[k];
;                     }
;                     u32x4 w; w.x = pk2(v0[0], v0[1]); w.y = pk2(v0[2], v0[3]); w.z = pk2(v1[0], v1[1]); w.w = pk2(v1[2], v1[3]);
;                     *(u32x4*)(O + (size_t)r * ldc + col0 + bj * 128) = w;
;                 }
;                 ss += __shfl_xor(ss, 16); ss += __shfl_xor(ss, 32);
;                 if (fq == 0) atomicAdd(rss + r, (u64)(ss * RSS_FIX));
;                 cy[0] = ny[0]; cy[1] = ny[1];
;             }
.LBB0_591:
	s_or_b64 exec, exec, s[28:29]
	v_mul_f32_e32 v12, 0xbfb8aa3b, v12
	v_mul_f32_e32 v13, 0xbfb8aa3b, v13
	v_exp_f32_e32 v12, v12
	v_mul_f32_e32 v8, 0xbfb8aa3b, v8
	v_exp_f32_e32 v13, v13
	v_mul_f32_e32 v9, 0xbfb8aa3b, v9
	v_exp_f32_e32 v8, v8
	v_exp_f32_e32 v9, v9
	v_add_f32_e32 v12, 1.0, v12
	v_add_f32_e32 v13, 1.0, v13
	v_rcp_f32_e32 v12, v12
	v_add_f32_e32 v8, 1.0, v8
	v_rcp_f32_e32 v13, v13
	v_add_f32_e32 v9, 1.0, v9
	v_rcp_f32_e32 v8, v8
	v_rcp_f32_e32 v9, v9
	s_waitcnt vmcnt(3)
	v_lshlrev_b32_e32 v16, 16, v36
	s_waitcnt lgkmcnt(0)
	v_and_b32_e32 v17, 0xffff0000, v36
	v_pk_mul_f32 v[12:13], v[12:13], v[16:17]
	v_lshlrev_b32_e32 v16, 16, v38
	v_and_b32_e32 v17, 0xffff0000, v38
	v_mul_f32_e32 v14, 0xbfb8aa3b, v14
	v_exp_f32_e32 v14, v14
	v_pk_mul_f32 v[16:17], v[8:9], v[16:17]
	v_mul_f32_e32 v11, 0xbfb8aa3b, v11
	v_pk_mul_f32 v[8:9], v[16:17], v[16:17]
	v_exp_f32_e32 v11, v11
	v_pk_fma_f32 v[18:19], v[12:13], v[12:13], v[8:9]
	v_mul_f32_e32 v9, 0xbfb8aa3b, v10
	v_exp_f32_e32 v9, v9
	v_mul_f32_e32 v10, 0xbfb8aa3b, v15
	v_add_f32_e32 v8, 1.0, v14
	v_exp_f32_e32 v14, v10
	v_add_f32_e32 v9, 1.0, v9
	v_rcp_f32_e32 v10, v9
	v_rcp_f32_e32 v8, v8
	v_add_f32_e32 v9, 1.0, v14
	v_rcp_f32_e32 v9, v9
	v_add_f32_e32 v11, 1.0, v11
	v_rcp_f32_e32 v11, v11
	v_lshlrev_b32_e32 v14, 16, v37
	v_and_b32_e32 v15, 0xffff0000, v37
	v_mul_f32_e32 v4, 0xbfb8aa3b, v4
	v_mul_f32_e32 v5, 0xbfb8aa3b, v5
	v_pk_mul_f32 v[14:15], v[8:9], v[14:15]
	v_lshlrev_b32_e32 v8, 16, v39
	v_and_b32_e32 v9, 0xffff0000, v39
	v_exp_f32_e32 v4, v4
	v_mul_f32_e32 v0, 0xbfb8aa3b, v0
	v_exp_f32_e32 v5, v5
	v_mul_f32_e32 v1, 0xbfb8aa3b, v1
	v_mul_f32_e32 v2, 0xbfb8aa3b, v2
	v_pk_mul_f32 v[20:21], v[10:11], v[8:9]
	v_cvt_pk_bf16_f32 v10, v16, v17
	v_exp_f32_e32 v0, v0
	v_exp_f32_e32 v1, v1
	v_mul_f32_e32 v6, 0xbfb8aa3b, v6
	v_exp_f32_e32 v16, v2
	v_mul_f32_e32 v2, 0xbfb8aa3b, v7
	v_exp_f32_e32 v6, v6
	v_exp_f32_e32 v7, v2
	v_mul_f32_e32 v3, 0xbfb8aa3b, v3
	v_pk_mul_f32 v[8:9], v[20:21], v[20:21]
	v_cvt_pk_bf16_f32 v11, v20, v21
	v_exp_f32_e32 v20, v3
	v_add_f32_e32 v4, 1.0, v4
	v_add_f32_e32 v5, 1.0, v5
	v_rcp_f32_e32 v4, v4
	v_add_f32_e32 v0, 1.0, v0
	v_rcp_f32_e32 v5, v5
	v_add_f32_e32 v1, 1.0, v1
	v_rcp_f32_e32 v0, v0
	v_rcp_f32_e32 v1, v1
	v_add_f32_e32 v6, 1.0, v6
	v_add_f32_e32 v7, 1.0, v7
	v_rcp_f32_e32 v2, v6
	v_add_f32_e32 v6, 1.0, v16
	v_rcp_f32_e32 v3, v7
	v_add_f32_e32 v7, 1.0, v20
	v_pk_fma_f32 v[22:23], v[14:15], v[14:15], v[8:9]
	v_cvt_pk_bf16_f32 v9, v14, v15
	s_waitcnt vmcnt(2)
	v_lshlrev_b32_e32 v14, 16, v32
	v_and_b32_e32 v15, 0xffff0000, v32
	v_rcp_f32_e32 v6, v6
	v_rcp_f32_e32 v7, v7
	v_pk_mul_f32 v[4:5], v[4:5], v[14:15]
	v_lshlrev_b32_e32 v14, 16, v34
	v_and_b32_e32 v15, 0xffff0000, v34
	v_pk_mul_f32 v[14:15], v[0:1], v[14:15]
	v_lshlrev_b32_e32 v16, 16, v33
	v_and_b32_e32 v17, 0xffff0000, v33
	v_add_f32_e32 v18, v18, v19
	v_pk_mul_f32 v[0:1], v[14:15], v[14:15]
	v_pk_mul_f32 v[16:17], v[2:3], v[16:17]
	v_lshlrev_b32_e32 v2, 16, v35
	v_and_b32_e32 v3, 0xffff0000, v35
	v_add_f32_e32 v18, v22, v18
	v_pk_fma_f32 v[0:1], v[4:5], v[4:5], v[0:1]
	v_pk_mul_f32 v[6:7], v[6:7], v[2:3]
	v_add_f32_e32 v18, v23, v18
	v_pk_mul_f32 v[2:3], v[6:7], v[6:7]
	v_add_f32_e32 v0, v0, v18
	v_pk_fma_f32 v[2:3], v[16:17], v[16:17], v[2:3]
	v_add_f32_e32 v0, v1, v0
	v_add_f32_e32 v0, v2, v0
	v_add_f32_e32 v3, v3, v0
	ds_bpermute_b32 v18, v166, v3
	v_cvt_pk_bf16_f32 v8, v12, v13
	v_lshlrev_b64 v[12:13], 11, v[40:41]
	v_lshl_add_u64 v[0:1], s[14:15], 0, v[12:13]
	v_lshl_add_u64 v[12:13], v[152:153], 1, v[0:1]
	s_waitcnt lgkmcnt(0)
	v_add_f32_e32 v0, v3, v18
	ds_bpermute_b32 v1, v165, v0
	v_cvt_pk_bf16_f32 v2, v4, v5
	v_cvt_pk_bf16_f32 v3, v16, v17
	v_cvt_pk_bf16_f32 v4, v14, v15
	v_cvt_pk_bf16_f32 v5, v6, v7
	global_store_dwordx4 v[12:13], v[8:11], off
	global_store_dwordx4 v[12:13], v[2:5], off offset:256
	s_and_saveexec_b64 s[28:29], s[2:3]
	s_cbranch_execz .LBB0_593
	s_waitcnt lgkmcnt(0)
	v_add_f32_e32 v0, v0, v1
	v_mul_f32_e32 v0, 0x4b800000, v0
	v_trunc_f32_e32 v0, v0
	v_mul_f32_e32 v1, 0x2f800000, v0
	v_floor_f32_e32 v1, v1
	v_fmac_f32_e32 v0, 0xcf800000, v1
	v_cvt_u32_f32_e32 v0, v0
	v_cvt_u32_f32_e32 v1, v1
	v_lshl_add_u64 v[2:3], v[40:41], 3, s[16:17]
	global_atomic_add_x2 v[2:3], v[0:1], off

;     __device__ __forceinline__ void operator()(const pg8::f32x4 (&acc)[2][2][4][2], const pg8::Unit& u, int wr, int wc, int fr, int fq) const {
;         const int row0 = u.pm * 256 + wr * 64 + fr, col0 = u.pn * 256 + wc * 32 + 8 * fq;
;         if (mode >= 5) {
;             const bool hasF = mode == 5, outF = mode == 7;
;             u32x4 cb2 = {0u, 0u, 0u, 0u}, nb2 = cb2, cbb, nbb; float csc, nsc = 1.f, ss = 0.f;
;             {
;                 if (hasF) cb2 = *(const u32x4*)(base2 + (size_t)row0 * 1024 + col0);
;                 cbb = *(const u32x4*)(baseb + (size_t)row0 * 1024 + col0);
;                 csc = rowscale(row0);
;             }
;             nbb = cbb;
; #pragma unroll
;             for (int p = 0; p < 16; ++p) {
;                 const int g = p >> 1, bj = p & 1, ai = g >> 2, m = g & 3, r = row0 + ai * 128 + m * 16, c = col0 + bj * 128;
;                 if (p < 15) {
;                     const int gn = (p + 1) >> 1, rn = row0 + (gn >> 2) * 128 + (gn & 3) * 16, cn = col0 + ((p + 1) & 1) * 128;
;                     if (hasF) nb2 = *(const u32x4*)(base2 + (size_t)rn * 1024 + cn);
;                     nbb = *(const u32x4*)(baseb + (size_t)rn * 1024 + cn);
;                     if (bj == 1) nsc = rowscale(rn);
;                 }
;                 const f32x4 r0 = {bflo(cbb.x), bfhi(cbb.x), bflo(cbb.y), bfhi(cbb.y)}, r1 = {bflo(cbb.z), bfhi(cbb.z), bflo(cbb.w), bfhi(cbb.w)};
;                 const f32x4 q0 = {bflo(cb2.x), bfhi(cb2.x), bflo(cb2.y), bfhi(cb2.y)}, q1 = {bflo(cb2.z), bfhi(cb2.z), bflo(cb2.w), bfhi(cb2.w)};
;                 const f32x4 v0 = acc[ai][bj][m][0] * csc + q0 + r0, v1 = acc[ai][bj][m][1] * csc + q1 + r1;
;                 if (outF) {
;                     float* op = out + (size_t)r * 1024 + c;
;                     *(f32x4*)op = v0; *(f32x4*)(op + 4) = v1;
;                 } else {
;                     u32x4 w; w.x = pk2(v0[0], v0[1]); w.y = pk2(v0[2], v0[3]); w.z = pk2(v1[0], v1[1]); w.w = pk2(v1[2], v1[3]);
;                     *(u32x4*)(O + (size_t)r * 1024 + c) = w;
;                     ss += (v0[0] * v0[0] + v0[1] * v0[1]) + (v0[2] * v0[2] + v0[3] * v0[3]) + (v1[0] * v1[0] + v1[1] * v1[1]) + (v1[2] * v1[2] + v1[3] * v1[3]);
;                     if (bj == 1) {
;                         ss += __shfl_xor(ss, 16); ss += __shfl_xor(ss, 32);
.LBB0_670:
	v_lshl_add_u64 v[164:165], v[2:3], 3, s[22:23]
	global_load_dwordx2 v[176:177], v[164:165], off
	v_lshl_or_b32 v162, s0, 8, v149
	v_lshlrev_b64 v[132:133], 11, v[2:3]
	v_ashrrev_i32_e32 v163, 31, v162
	v_lshl_add_u64 v[132:133], s[78:79], 0, v[132:133]
	v_lshlrev_b64 v[134:135], 1, v[162:163]
	v_lshl_add_u64 v[178:179], v[132:133], 0, v[134:135]
	global_load_dwordx4 v[168:171], v[178:179], off
	global_load_dwordx4 v[172:175], v[178:179], off offset:256
	v_lshlrev_b64 v[132:133], 11, v[160:161]
	v_lshl_add_u64 v[132:133], s[78:79], 0, v[132:133]
	v_lshl_add_u64 v[166:167], v[132:133], 0, v[134:135]
	global_load_dwordx4 v[132:135], v[166:167], off
	s_waitcnt vmcnt(0)
	v_ffbh_u32_e32 v1, v177
	v_min_u32_e32 v1, 32, v1
	v_lshlrev_b64 v[176:177], v1, v[176:177]
	v_min_u32_e32 v176, 1, v176
	v_sub_u32_e32 v1, 32, v1
	v_lshlrev_b32_e32 v180, 16, v168
	v_and_b32_e32 v181, 0xffff0000, v168
	v_or_b32_e32 v168, v177, v176
	v_cvt_f32_u32_e32 v177, v168
	v_lshlrev_b32_e32 v168, 16, v169
	v_and_b32_e32 v169, 0xffff0000, v169
	v_lshlrev_b32_e32 v176, 16, v170
	v_ldexp_f32 v1, v177, v1
	v_fmamk_f32 v1, v1, 0x2f000000, v202
	v_mul_f32_e32 v177, 0x4b800000, v1
	v_cmp_gt_f32_e32 vcc, s66, v1
	s_nop 1
	v_cndmask_b32_e32 v1, v1, v177, vcc
	v_rsq_f32_e32 v1, v1
	v_and_b32_e32 v177, 0xffff0000, v170
	v_lshlrev_b32_e32 v170, 16, v171
	v_and_b32_e32 v171, 0xffff0000, v171
	v_mul_f32_e32 v205, 0x45800000, v1
	v_cndmask_b32_e32 v206, v1, v205, vcc
	v_pk_fma_f32 v[208:209], v[128:129], v[206:207], 0 op_sel_hi:[1,0,0]
	v_pk_fma_f32 v[210:211], v[130:131], v[206:207], 0 op_sel_hi:[1,0,0]
	v_pk_fma_f32 v[212:213], v[124:125], v[206:207], 0 op_sel_hi:[1,0,0]
	v_pk_fma_f32 v[214:215], v[126:127], v[206:207], 0 op_sel_hi:[1,0,0]
	v_pk_add_f32 v[210:211], v[210:211], v[168:169]
	v_pk_add_f32 v[180:181], v[208:209], v[180:181]
	v_pk_add_f32 v[208:209], v[214:215], v[170:171]
	v_pk_add_f32 v[176:177], v[212:213], v[176:177]
	v_cvt_pk_bf16_f32 v168, v180, v181
	v_cvt_pk_bf16_f32 v169, v210, v211
	v_cvt_pk_bf16_f32 v170, v176, v177
	v_cvt_pk_bf16_f32 v171, v208, v209
	global_store_dwordx4 v[178:179], v[168:171], off
	v_mul_f32_e32 v1, v181, v181
	v_fmac_f32_e32 v1, v180, v180
	v_lshl_add_u64 v[168:169], v[160:161], 3, s[22:23]
	global_load_dwordx2 v[168:169], v[168:169], off
	v_mul_f32_e32 v170, v211, v211
	v_fmac_f32_e32 v170, v210, v210
	v_add_f32_e32 v1, v1, v170
	v_mul_f32_e32 v170, v177, v177
	v_fmac_f32_e32 v170, v176, v176
	v_add_f32_e32 v1, v170, v1
	v_mul_f32_e32 v170, v209, v209
	v_fmac_f32_e32 v170, v208, v208
	v_add_f32_e32 v1, v170, v1
	v_lshlrev_b32_e32 v170, 16, v172
	v_and_b32_e32 v171, 0xffff0000, v172
	v_lshlrev_b32_e32 v172, 16, v173
	v_and_b32_e32 v173, 0xffff0000, v173
	v_pk_fma_f32 v[180:181], v[96:97], v[206:207], 0 op_sel_hi:[1,0,0]
	v_pk_fma_f32 v[208:209], v[98:99], v[206:207], 0 op_sel_hi:[1,0,0]
	v_lshlrev_b32_e32 v176, 16, v174
	v_and_b32_e32 v177, 0xffff0000, v174
	v_lshlrev_b32_e32 v174, 16, v175
	v_and_b32_e32 v175, 0xffff0000, v175
	v_pk_add_f32 v[208:209], v[208:209], v[172:173]
	v_pk_add_f32 v[170:171], v[180:181], v[170:171]
	v_pk_fma_f32 v[172:173], v[92:93], v[206:207], 0 op_sel_hi:[1,0,0]
	v_pk_fma_f32 v[180:181], v[94:95], v[206:207], 0 op_sel_hi:[1,0,0]
	s_nop 0
	v_pk_add_f32 v[180:181], v[180:181], v[174:175]
	v_pk_add_f32 v[174:175], v[172:173], v[176:177]
	v_mul_f32_e32 v173, v171, v171
	v_mul_f32_e32 v176, v209, v209
	v_fmac_f32_e32 v173, v170, v170
	v_fmac_f32_e32 v176, v208, v208
	v_add_f32_e32 v173, v173, v176
	v_mul_f32_e32 v176, v175, v175
	v_mul_f32_e32 v172, v181, v181
	v_fmac_f32_e32 v176, v174, v174
	v_fmac_f32_e32 v172, v180, v180
	v_add_f32_e32 v173, v176, v173
	v_add_f32_e32 v172, v172, v173
	v_add_f32_e32 v173, v172, v1
	v_and_b32_e32 v172, 64, v204
	v_xor_b32_e32 v1, 16, v204
	v_add_u32_e32 v176, 64, v172
	v_cmp_lt_i32_e32 vcc, v1, v176
	v_cvt_pk_bf16_f32 v172, v170, v171
	v_xor_b32_e32 v171, 32, v204
	v_cndmask_b32_e32 v1, v204, v1, vcc
	v_lshlrev_b32_e32 v1, 2, v1
	ds_bpermute_b32 v177, v1, v173
	v_cmp_lt_i32_e32 vcc, v171, v176
	v_cvt_pk_bf16_f32 v174, v174, v175
	v_cvt_pk_bf16_f32 v175, v180, v181
	v_cndmask_b32_e32 v171, v204, v171, vcc
	s_waitcnt lgkmcnt(0)
	v_add_f32_e32 v170, v173, v177
	v_lshlrev_b32_e32 v176, 2, v171
	ds_bpermute_b32 v171, v176, v170
	v_cvt_pk_bf16_f32 v173, v208, v209
	global_store_dwordx4 v[178:179], v[172:175], off offset:256
	s_and_saveexec_b64 s[0:1], s[6:7]
	s_cbranch_execz .LBB0_672
	s_waitcnt lgkmcnt(0)
	v_add_f32_e32 v170, v170, v171
	v_mul_f32_e32 v170, 0x4b800000, v170
	v_trunc_f32_e32 v170, v170
	v_mul_f32_e32 v171, 0x2f800000, v170
	v_floor_f32_e32 v171, v171
	v_fmac_f32_e32 v170, 0xcf800000, v171
	v_cvt_u32_f32_e32 v170, v170
	v_cvt_u32_f32_e32 v171, v171
	v_lshl_add_u64 v[172:173], v[2:3], 3, s[18:19]
	global_atomic_add_x2 v[172:173], v[170:171], off
;     __device__ __forceinline__ void operator()(const pg8::f32x4 (&acc)[2][2][4][2], const pg8::Unit& u, int wr, int wc, int fr, int fq) const {
;         const int row0 = u.pm * 256 + wr * 64 + fr, col0 = u.pn * 256 + wc * 32 + 8 * fq;
;         if (mode >= 5) {
;             const bool hasF = mode == 5, outF = mode == 7;
;             u32x4 cb2 = {0u, 0u, 0u, 0u}, nb2 = cb2, cbb, nbb; float csc, nsc = 1.f, ss = 0.f;
;             {
;                 if (hasF) cb2 = *(const u32x4*)(base2 + (size_t)row0 * 1024 + col0);
;                 cbb = *(const u32x4*)(baseb + (size_t)row0 * 1024 + col0);
;                 csc = rowscale(row0);
;             }
;             nbb = cbb;
; #pragma unroll
;             for (int p = 0; p < 16; ++p) {
;                 const int g = p >> 1, bj = p & 1, ai = g >> 2, m = g & 3, r = row0 + ai * 128 + m * 16, c = col0 + bj * 128;
;                 if (p < 15) {
;                     const int gn = (p + 1) >> 1, rn = row0 + (gn >> 2) * 128 + (gn & 3) * 16, cn = col0 + ((p + 1) & 1) * 128;
;                     if (hasF) nb2 = *(const u32x4*)(base2 + (size_t)rn * 1024 + cn);
;                     nbb = *(const u32x4*)(baseb + (size_t)rn * 1024 + cn);
;                     if (bj == 1) nsc = rowscale(rn);
;                 }
;                 const f32x4 r0 = {bflo(cbb.x), bfhi(cbb.x), bflo(cbb.y), bfhi(cbb.y)}, r1 = {bflo(cbb.z), bfhi(cbb.z), bflo(cbb.w), bfhi(cbb.w)};
;                 const f32x4 q0 = {bflo(cb2.x), bfhi(cb2.x), bflo(cb2.y), bfhi(cb2.y)}, q1 = {bflo(cb2.z), bfhi(cb2.z), bflo(cb2.w), bfhi(cb2.w)};
;                 const f32x4 v0 = acc[ai][bj][m][0] * csc + q0 + r0, v1 = acc[ai][bj][m][1] * csc + q1 + r1;
;                 if (outF) {
;                     float* op = out + (size_t)r * 1024 + c;
;                     *(f32x4*)op = v0; *(f32x4*)(op + 4) = v1;
;                 } else {
;                     u32x4 w; w.x = pk2(v0[0], v0[1]); w.y = pk2(v0[2], v0[3]); w.z = pk2(v1[0], v1[1]); w.w = pk2(v1[2], v1[3]);
;                     *(u32x4*)(O + (size_t)r * 1024 + c) = w;
;                     ss += (v0[0] * v0[0] + v0[1] * v0[1]) + (v0[2] * v0[2] + v0[3] * v0[3]) + (v1[0] * v1[0] + v1[1] * v1[1]) + (v1[2] * v1[2] + v1[3] * v1[3]);
;                     if (bj == 1) {
;                         ss += __shfl_xor(ss, 16); ss += __shfl_xor(ss, 32);
.LBB0_672:
	s_or_b64 exec, exec, s[0:1]
	s_waitcnt vmcnt(1)
	v_ffbh_u32_e32 v170, v169
	v_min_u32_e32 v170, 32, v170
	v_lshlrev_b64 v[168:169], v170, v[168:169]
	v_min_u32_e32 v168, 1, v168
	v_or_b32_e32 v168, v169, v168
	v_cvt_f32_u32_e32 v168, v168
	global_load_dwordx4 v[178:181], v[166:167], off offset:256
	v_sub_u32_e32 v169, 32, v170
	v_ldexp_f32 v168, v168, v169
	v_fmamk_f32 v168, v168, 0x2f000000, v202
	v_mul_f32_e32 v169, 0x4b800000, v168
	v_cmp_gt_f32_e32 vcc, s66, v168
	s_nop 1
	v_cndmask_b32_e32 v168, v168, v169, vcc
	v_rsq_f32_e32 v170, v168
	v_lshlrev_b32_e32 v168, 16, v132
	v_and_b32_e32 v169, 0xffff0000, v132
	v_lshlrev_b32_e32 v132, 16, v133
	s_waitcnt lgkmcnt(0)
	v_mul_f32_e32 v171, 0x45800000, v170
	v_cndmask_b32_e32 v174, v170, v171, vcc
	v_and_b32_e32 v133, 0xffff0000, v133
	v_pk_fma_f32 v[172:173], v[120:121], v[174:175], 0 op_sel_hi:[1,0,0]
	v_pk_fma_f32 v[206:207], v[122:123], v[174:175], 0 op_sel_hi:[1,0,0]
	v_lshlrev_b32_e32 v170, 16, v134
	v_and_b32_e32 v171, 0xffff0000, v134
	v_lshlrev_b32_e32 v134, 16, v135
	v_and_b32_e32 v135, 0xffff0000, v135
	v_pk_add_f32 v[206:207], v[206:207], v[132:133]
	v_pk_add_f32 v[208:209], v[172:173], v[168:169]
	v_pk_fma_f32 v[132:133], v[116:117], v[174:175], 0 op_sel_hi:[1,0,0]
	v_pk_fma_f32 v[168:169], v[118:119], v[174:175], 0 op_sel_hi:[1,0,0]
	v_pk_add_f32 v[212:213], v[132:133], v[170:171]
	v_pk_add_f32 v[210:211], v[168:169], v[134:135]
	v_or_b32_e32 v168, 32, v2
	v_cvt_pk_bf16_f32 v132, v208, v209
	v_cvt_pk_bf16_f32 v133, v206, v207
	v_cvt_pk_bf16_f32 v134, v212, v213
	v_cvt_pk_bf16_f32 v135, v210, v211
	v_ashrrev_i32_e32 v169, 31, v168
	global_store_dwordx4 v[166:167], v[132:135], off
	v_lshl_add_u64 v[170:171], v[168:169], 3, s[22:23]
	global_load_dwordx2 v[170:171], v[170:171], off
	v_lshlrev_b64 v[132:133], 11, v[168:169]
	v_lshl_add_u64 v[132:133], s[78:79], 0, v[132:133]
	v_lshl_add_u64 v[172:173], v[162:163], 1, v[132:133]
	global_load_dwordx4 v[132:135], v[172:173], off
	v_mul_f32_e32 v177, v209, v209
	v_mul_f32_e32 v205, v207, v207
	v_mul_f32_e32 v207, v213, v213
	v_fmac_f32_e32 v177, v208, v208
	v_fmac_f32_e32 v205, v206, v206
	v_mul_f32_e32 v209, v211, v211
	v_fmac_f32_e32 v207, v212, v212
	v_add_f32_e32 v177, v177, v205
	v_pk_fma_f32 v[214:215], v[88:89], v[174:175], 0 op_sel_hi:[1,0,0]
	v_pk_fma_f32 v[216:217], v[90:91], v[174:175], 0 op_sel_hi:[1,0,0]
	v_fmac_f32_e32 v209, v210, v210
	v_add_f32_e32 v177, v207, v177
	v_pk_fma_f32 v[218:219], v[84:85], v[174:175], 0 op_sel_hi:[1,0,0]
	v_pk_fma_f32 v[174:175], v[86:87], v[174:175], 0 op_sel_hi:[1,0,0]
	v_add_f32_e32 v177, v209, v177
	s_waitcnt vmcnt(3)
	v_lshlrev_b32_e32 v206, 16, v178
	v_and_b32_e32 v207, 0xffff0000, v178
	v_lshlrev_b32_e32 v178, 16, v179
	v_and_b32_e32 v179, 0xffff0000, v179
	v_lshlrev_b32_e32 v208, 16, v180
	v_and_b32_e32 v209, 0xffff0000, v180
	v_lshlrev_b32_e32 v180, 16, v181
	v_and_b32_e32 v181, 0xffff0000, v181
	v_pk_add_f32 v[210:211], v[216:217], v[178:179]
	v_pk_add_f32 v[178:179], v[214:215], v[206:207]
	v_pk_add_f32 v[206:207], v[174:175], v[180:181]
	v_mul_f32_e32 v175, v179, v179
	v_mul_f32_e32 v205, v211, v211
	v_pk_add_f32 v[180:181], v[218:219], v[208:209]
	v_fmac_f32_e32 v175, v178, v178
	v_fmac_f32_e32 v205, v210, v210
	v_add_f32_e32 v175, v175, v205
	v_mul_f32_e32 v205, v181, v181
	v_mul_f32_e32 v174, v207, v207
	v_fmac_f32_e32 v205, v180, v180
	v_fmac_f32_e32 v174, v206, v206
	v_add_f32_e32 v175, v205, v175
	v_add_f32_e32 v174, v174, v175
	v_add_f32_e32 v174, v177, v174
	ds_bpermute_b32 v175, v1, v174
	v_cvt_pk_bf16_f32 v178, v178, v179
	v_cvt_pk_bf16_f32 v179, v210, v211
	v_cvt_pk_bf16_f32 v180, v180, v181
	v_cvt_pk_bf16_f32 v181, v206, v207
	s_waitcnt lgkmcnt(0)
	v_add_f32_e32 v174, v174, v175
	ds_bpermute_b32 v175, v176, v174
	global_store_dwordx4 v[166:167], v[178:181], off offset:256
	s_and_saveexec_b64 s[0:1], s[6:7]
	s_cbranch_execz .LBB0_674
	s_waitcnt lgkmcnt(0)
	v_add_f32_e32 v166, v174, v175
	v_mul_f32_e32 v166, 0x4b800000, v166
	v_trunc_f32_e32 v166, v166
	v_mul_f32_e32 v167, 0x2f800000, v166
	v_floor_f32_e32 v167, v167
	v_fmac_f32_e32 v166, 0xcf800000, v167
	v_cvt_u32_f32_e32 v166, v166
	v_cvt_u32_f32_e32 v167, v167
	v_lshl_add_u64 v[174:175], v[160:161], 3, s[18:19]
	global_atomic_add_x2 v[174:175], v[166:167], off
;     __device__ __forceinline__ void operator()(const pg8::f32x4 (&acc)[2][2][4][2], const pg8::Unit& u, int wr, int wc, int fr, int fq) const {
;         const int row0 = u.pm * 256 + wr * 64 + fr, col0 = u.pn * 256 + wc * 32 + 8 * fq;
;         if (mode >= 5) {
;             const bool hasF = mode == 5, outF = mode == 7;
;             u32x4 cb2 = {0u, 0u, 0u, 0u}, nb2 = cb2, cbb, nbb; float csc, nsc = 1.f, ss = 0.f;
;             {
;                 if (hasF) cb2 = *(const u32x4*)(base2 + (size_t)row0 * 1024 + col0);
;                 cbb = *(const u32x4*)(baseb + (size_t)row0 * 1024 + col0);
;                 csc = rowscale(row0);
;             }
;             nbb = cbb;
; #pragma unroll
;             for (int p = 0; p < 16; ++p) {
;                 const int g = p >> 1, bj = p & 1, ai = g >> 2, m = g & 3, r = row0 + ai * 128 + m * 16, c = col0 + bj * 128;
;                 if (p < 15) {
;                     const int gn = (p + 1) >> 1, rn = row0 + (gn >> 2) * 128 + (gn & 3) * 16, cn = col0 + ((p + 1) & 1) * 128;
;                     if (hasF) nb2 = *(const u32x4*)(base2 + (size_t)rn * 1024 + cn);
;                     nbb = *(const u32x4*)(baseb + (size_t)rn * 1024 + cn);
;                     if (bj == 1) nsc = rowscale(rn);
;                 }
;                 const f32x4 r0 = {bflo(cbb.x), bfhi(cbb.x), bflo(cbb.y), bfhi(cbb.y)}, r1 = {bflo(cbb.z), bfhi(cbb.z), bflo(cbb.w), bfhi(cbb.w)};
;                 const f32x4 q0 = {bflo(cb2.x), bfhi(cb2.x), bflo(cb2.y), bfhi(cb2.y)}, q1 = {bflo(cb2.z), bfhi(cb2.z), bflo(cb2.w), bfhi(cb2.w)};
;                 const f32x4 v0 = acc[ai][bj][m][0] * csc + q0 + r0, v1 = acc[ai][bj][m][1] * csc + q1 + r1;
;                 if (outF) {
;                     float* op = out + (size_t)r * 1024 + c;
;                     *(f32x4*)op = v0; *(f32x4*)(op + 4) = v1;
;                 } else {
;                     u32x4 w; w.x = pk2(v0[0], v0[1]); w.y = pk2(v0[2], v0[3]); w.z = pk2(v1[0], v1[1]); w.w = pk2(v1[2], v1[3]);
;                     *(u32x4*)(O + (size_t)r * 1024 + c) = w;
;                     ss += (v0[0] * v0[0] + v0[1] * v0[1]) + (v0[2] * v0[2] + v0[3] * v0[3]) + (v1[0] * v1[0] + v1[1] * v1[1]) + (v1[2] * v1[2] + v1[3] * v1[3]);
;                     if (bj == 1) {
;                         ss += __shfl_xor(ss, 16); ss += __shfl_xor(ss, 32);
.LBB0_674:
	s_or_b64 exec, exec, s[0:1]
	s_waitcnt vmcnt(2)
	v_ffbh_u32_e32 v166, v171
	v_min_u32_e32 v174, 32, v166
	v_lshlrev_b64 v[166:167], v174, v[170:171]
	v_min_u32_e32 v166, 1, v166
	v_or_b32_e32 v166, v167, v166
	v_cvt_f32_u32_e32 v166, v166
	global_load_dwordx4 v[178:181], v[172:173], off offset:256
	v_sub_u32_e32 v167, 32, v174
	v_ldexp_f32 v166, v166, v167
	v_fmamk_f32 v166, v166, 0x2f000000, v202
	v_mul_f32_e32 v167, 0x4b800000, v166
	v_cmp_gt_f32_e32 vcc, s66, v166
	s_nop 1
	v_cndmask_b32_e32 v166, v166, v167, vcc
	v_rsq_f32_e32 v170, v166
	s_waitcnt vmcnt(2)
	v_lshlrev_b32_e32 v166, 16, v132
	v_and_b32_e32 v167, 0xffff0000, v132
	v_lshlrev_b32_e32 v132, 16, v133
	v_mul_f32_e32 v171, 0x45800000, v170
	v_cndmask_b32_e32 v206, v170, v171, vcc
	v_and_b32_e32 v133, 0xffff0000, v133
	s_waitcnt lgkmcnt(0)
	v_pk_fma_f32 v[174:175], v[112:113], v[206:207], 0 op_sel_hi:[1,0,0]
	v_pk_fma_f32 v[208:209], v[114:115], v[206:207], 0 op_sel_hi:[1,0,0]
	v_lshlrev_b32_e32 v170, 16, v134
	v_and_b32_e32 v171, 0xffff0000, v134
	v_lshlrev_b32_e32 v134, 16, v135
	v_and_b32_e32 v135, 0xffff0000, v135
	v_pk_add_f32 v[208:209], v[208:209], v[132:133]
	v_pk_add_f32 v[210:211], v[174:175], v[166:167]
	v_pk_fma_f32 v[132:133], v[108:109], v[206:207], 0 op_sel_hi:[1,0,0]
	v_pk_fma_f32 v[166:167], v[110:111], v[206:207], 0 op_sel_hi:[1,0,0]
	v_pk_add_f32 v[214:215], v[132:133], v[170:171]
	v_pk_add_f32 v[212:213], v[166:167], v[134:135]
	v_or_b32_e32 v170, 48, v2
	v_cvt_pk_bf16_f32 v132, v210, v211
	v_cvt_pk_bf16_f32 v133, v208, v209
	v_cvt_pk_bf16_f32 v134, v214, v215
	v_cvt_pk_bf16_f32 v135, v212, v213
	v_ashrrev_i32_e32 v171, 31, v170
	global_store_dwordx4 v[172:173], v[132:135], off
	v_lshl_add_u64 v[166:167], v[170:171], 3, s[22:23]
	global_load_dwordx2 v[166:167], v[166:167], off
	v_lshlrev_b64 v[132:133], 11, v[170:171]
	v_lshl_add_u64 v[132:133], s[78:79], 0, v[132:133]
	v_lshl_add_u64 v[174:175], v[162:163], 1, v[132:133]
	global_load_dwordx4 v[132:135], v[174:175], off
	v_mul_f32_e32 v177, v211, v211
	v_mul_f32_e32 v205, v209, v209
	v_mul_f32_e32 v209, v215, v215
	v_fmac_f32_e32 v177, v210, v210
	v_fmac_f32_e32 v205, v208, v208
	v_mul_f32_e32 v211, v213, v213
	v_fmac_f32_e32 v209, v214, v214
	v_add_f32_e32 v177, v177, v205
	v_pk_fma_f32 v[216:217], v[80:81], v[206:207], 0 op_sel_hi:[1,0,0]
	v_pk_fma_f32 v[218:219], v[82:83], v[206:207], 0 op_sel_hi:[1,0,0]
	v_fmac_f32_e32 v211, v212, v212
	v_add_f32_e32 v177, v209, v177
	v_pk_fma_f32 v[220:221], v[76:77], v[206:207], 0 op_sel_hi:[1,0,0]
	v_pk_fma_f32 v[206:207], v[78:79], v[206:207], 0 op_sel_hi:[1,0,0]
	v_add_f32_e32 v177, v211, v177
	s_waitcnt vmcnt(3)
	v_lshlrev_b32_e32 v208, 16, v178
	v_and_b32_e32 v209, 0xffff0000, v178
	v_lshlrev_b32_e32 v178, 16, v179
	v_and_b32_e32 v179, 0xffff0000, v179
	v_lshlrev_b32_e32 v210, 16, v180
	v_and_b32_e32 v211, 0xffff0000, v180
	v_lshlrev_b32_e32 v180, 16, v181
	v_and_b32_e32 v181, 0xffff0000, v181
	v_pk_add_f32 v[212:213], v[218:219], v[178:179]
	v_pk_add_f32 v[178:179], v[216:217], v[208:209]
	v_pk_add_f32 v[180:181], v[206:207], v[180:181]
	v_mul_f32_e32 v206, v179, v179
	v_mul_f32_e32 v207, v213, v213
	v_pk_add_f32 v[208:209], v[220:221], v[210:211]
	v_fmac_f32_e32 v206, v178, v178
	v_fmac_f32_e32 v207, v212, v212
	v_add_f32_e32 v206, v206, v207
	v_mul_f32_e32 v207, v209, v209
	v_mul_f32_e32 v205, v181, v181
	v_fmac_f32_e32 v207, v208, v208
	v_fmac_f32_e32 v205, v180, v180
	v_add_f32_e32 v206, v207, v206
	v_add_f32_e32 v205, v205, v206
	v_add_f32_e32 v177, v177, v205
	ds_bpermute_b32 v205, v1, v177
	v_cvt_pk_bf16_f32 v206, v178, v179
	v_cvt_pk_bf16_f32 v207, v212, v213
	v_cvt_pk_bf16_f32 v208, v208, v209
	v_cvt_pk_bf16_f32 v209, v180, v181
	s_waitcnt lgkmcnt(0)
	v_add_f32_e32 v177, v177, v205
	ds_bpermute_b32 v178, v176, v177
	global_store_dwordx4 v[172:173], v[206:209], off offset:256
	s_and_saveexec_b64 s[0:1], s[6:7]
	s_cbranch_execz .LBB0_676
	s_waitcnt lgkmcnt(0)
	v_add_f32_e32 v172, v177, v178
	v_mul_f32_e32 v172, 0x4b800000, v172
	v_trunc_f32_e32 v172, v172
	v_mul_f32_e32 v173, 0x2f800000, v172
	v_floor_f32_e32 v173, v173
	v_fmac_f32_e32 v172, 0xcf800000, v173
	v_cvt_u32_f32_e32 v172, v172
	v_cvt_u32_f32_e32 v173, v173
	v_lshl_add_u64 v[168:169], v[168:169], 3, s[18:19]
	global_atomic_add_x2 v[168:169], v[172:173], off
;     __device__ __forceinline__ void operator()(const pg8::f32x4 (&acc)[2][2][4][2], const pg8::Unit& u, int wr, int wc, int fr, int fq) const {
;         const int row0 = u.pm * 256 + wr * 64 + fr, col0 = u.pn * 256 + wc * 32 + 8 * fq;
;         if (mode >= 5) {
;             const bool hasF = mode == 5, outF = mode == 7;
;             u32x4 cb2 = {0u, 0u, 0u, 0u}, nb2 = cb2, cbb, nbb; float csc, nsc = 1.f, ss = 0.f;
;             {
;                 if (hasF) cb2 = *(const u32x4*)(base2 + (size_t)row0 * 1024 + col0);
;                 cbb = *(const u32x4*)(baseb + (size_t)row0 * 1024 + col0);
;                 csc = rowscale(row0);
;             }
;             nbb = cbb;
; #pragma unroll
;             for (int p = 0; p < 16; ++p) {
;                 const int g = p >> 1, bj = p & 1, ai = g >> 2, m = g & 3, r = row0 + ai * 128 + m * 16, c = col0 + bj * 128;
;                 if (p < 15) {
;                     const int gn = (p + 1) >> 1, rn = row0 + (gn >> 2) * 128 + (gn & 3) * 16, cn = col0 + ((p + 1) & 1) * 128;
;                     if (hasF) nb2 = *(const u32x4*)(base2 + (size_t)rn * 1024 + cn);
;                     nbb = *(const u32x4*)(baseb + (size_t)rn * 1024 + cn);
;                     if (bj == 1) nsc = rowscale(rn);
;                 }
;                 const f32x4 r0 = {bflo(cbb.x), bfhi(cbb.x), bflo(cbb.y), bfhi(cbb.y)}, r1 = {bflo(cbb.z), bfhi(cbb.z), bflo(cbb.w), bfhi(cbb.w)};
;                 const f32x4 q0 = {bflo(cb2.x), bfhi(cb2.x), bflo(cb2.y), bfhi(cb2.y)}, q1 = {bflo(cb2.z), bfhi(cb2.z), bflo(cb2.w), bfhi(cb2.w)};
;                 const f32x4 v0 = acc[ai][bj][m][0] * csc + q0 + r0, v1 = acc[ai][bj][m][1] * csc + q1 + r1;
;                 if (outF) {
;                     float* op = out + (size_t)r * 1024 + c;
;                     *(f32x4*)op = v0; *(f32x4*)(op + 4) = v1;
;                 } else {
;                     u32x4 w; w.x = pk2(v0[0], v0[1]); w.y = pk2(v0[2], v0[3]); w.z = pk2(v1[0], v1[1]); w.w = pk2(v1[2], v1[3]);
;                     *(u32x4*)(O + (size_t)r * 1024 + c) = w;
;                     ss += (v0[0] * v0[0] + v0[1] * v0[1]) + (v0[2] * v0[2] + v0[3] * v0[3]) + (v1[0] * v1[0] + v1[1] * v1[1]) + (v1[2] * v1[2] + v1[3] * v1[3]);
;                     if (bj == 1) {
;                         ss += __shfl_xor(ss, 16); ss += __shfl_xor(ss, 32);
.LBB0_676:
	s_or_b64 exec, exec, s[0:1]
	s_waitcnt vmcnt(2)
	v_ffbh_u32_e32 v168, v167
	v_min_u32_e32 v168, 32, v168
	v_lshlrev_b64 v[166:167], v168, v[166:167]
	v_min_u32_e32 v166, 1, v166
	v_or_b32_e32 v166, v167, v166
	v_cvt_f32_u32_e32 v166, v166
	s_waitcnt lgkmcnt(0)
	global_load_dwordx4 v[178:181], v[174:175], off offset:256
	v_sub_u32_e32 v167, 32, v168
	v_ldexp_f32 v166, v166, v167
	v_fmamk_f32 v166, v166, 0x2f000000, v202
	v_mul_f32_e32 v167, 0x4b800000, v166
	v_cmp_gt_f32_e32 vcc, s66, v166
	s_nop 1
	v_cndmask_b32_e32 v166, v166, v167, vcc
	v_rsq_f32_e32 v168, v166
	s_waitcnt vmcnt(2)
	v_lshlrev_b32_e32 v166, 16, v132
	v_and_b32_e32 v167, 0xffff0000, v132
	v_lshlrev_b32_e32 v132, 16, v133
	v_mul_f32_e32 v169, 0x45800000, v168
	v_cndmask_b32_e32 v172, v168, v169, vcc
	v_and_b32_e32 v133, 0xffff0000, v133
	v_pk_fma_f32 v[206:207], v[104:105], v[172:173], 0 op_sel_hi:[1,0,0]
	v_pk_fma_f32 v[208:209], v[106:107], v[172:173], 0 op_sel_hi:[1,0,0]
	v_lshlrev_b32_e32 v168, 16, v134
	v_and_b32_e32 v169, 0xffff0000, v134
	v_lshlrev_b32_e32 v134, 16, v135
	v_and_b32_e32 v135, 0xffff0000, v135
	v_pk_add_f32 v[208:209], v[208:209], v[132:133]
	v_pk_add_f32 v[206:207], v[206:207], v[166:167]
	v_pk_fma_f32 v[132:133], v[100:101], v[172:173], 0 op_sel_hi:[1,0,0]
	v_pk_fma_f32 v[166:167], v[102:103], v[172:173], 0 op_sel_hi:[1,0,0]
	v_pk_add_f32 v[212:213], v[132:133], v[168:169]
	v_pk_add_f32 v[210:211], v[166:167], v[134:135]
	v_add_u32_e32 v166, 0x80, v2
	v_cvt_pk_bf16_f32 v132, v206, v207
	v_cvt_pk_bf16_f32 v133, v208, v209
	v_cvt_pk_bf16_f32 v134, v212, v213
	v_cvt_pk_bf16_f32 v135, v210, v211
	v_ashrrev_i32_e32 v167, 31, v166
	global_store_dwordx4 v[174:175], v[132:135], off
	v_mul_f32_e32 v177, v207, v207
	v_mul_f32_e32 v205, v209, v209
	v_lshlrev_b64 v[132:133], 11, v[166:167]
	v_lshl_add_u64 v[132:133], s[78:79], 0, v[132:133]
	v_lshl_add_u64 v[168:169], v[162:163], 1, v[132:133]
	global_load_dwordx4 v[132:135], v[168:169], off
	s_nop 0
	global_load_dwordx2 v[164:165], v[164:165], off offset:1024
	v_mul_f32_e32 v207, v213, v213
	v_fmac_f32_e32 v177, v206, v206
	v_fmac_f32_e32 v205, v208, v208
	v_mul_f32_e32 v209, v211, v211
	v_fmac_f32_e32 v207, v212, v212
	v_add_f32_e32 v177, v177, v205
	v_pk_fma_f32 v[214:215], v[72:73], v[172:173], 0 op_sel_hi:[1,0,0]
	v_pk_fma_f32 v[216:217], v[74:75], v[172:173], 0 op_sel_hi:[1,0,0]
	v_fmac_f32_e32 v209, v210, v210
	v_add_f32_e32 v177, v207, v177
	v_pk_fma_f32 v[218:219], v[68:69], v[172:173], 0 op_sel_hi:[1,0,0]
	v_pk_fma_f32 v[172:173], v[70:71], v[172:173], 0 op_sel_hi:[1,0,0]
	v_add_f32_e32 v177, v209, v177
	s_waitcnt vmcnt(3)
	v_lshlrev_b32_e32 v206, 16, v178
	v_and_b32_e32 v207, 0xffff0000, v178
	v_lshlrev_b32_e32 v178, 16, v179
	v_and_b32_e32 v179, 0xffff0000, v179
	v_lshlrev_b32_e32 v208, 16, v180
	v_and_b32_e32 v209, 0xffff0000, v180
	v_lshlrev_b32_e32 v180, 16, v181
	v_and_b32_e32 v181, 0xffff0000, v181
	v_pk_add_f32 v[210:211], v[216:217], v[178:179]
	v_pk_add_f32 v[178:179], v[214:215], v[206:207]
	v_pk_add_f32 v[206:207], v[172:173], v[180:181]
	v_mul_f32_e32 v173, v179, v179
	v_mul_f32_e32 v205, v211, v211
	v_pk_add_f32 v[180:181], v[218:219], v[208:209]
	v_fmac_f32_e32 v173, v178, v178
	v_fmac_f32_e32 v205, v210, v210
	v_add_f32_e32 v173, v173, v205
	v_mul_f32_e32 v205, v181, v181
	v_mul_f32_e32 v172, v207, v207
	v_fmac_f32_e32 v205, v180, v180
	v_fmac_f32_e32 v172, v206, v206
	v_add_f32_e32 v173, v205, v173
	v_add_f32_e32 v172, v172, v173
	v_add_f32_e32 v172, v177, v172
	ds_bpermute_b32 v173, v1, v172
	v_cvt_pk_bf16_f32 v178, v178, v179
	v_cvt_pk_bf16_f32 v179, v210, v211
	v_cvt_pk_bf16_f32 v180, v180, v181
	v_cvt_pk_bf16_f32 v181, v206, v207
	s_waitcnt lgkmcnt(0)
	v_add_f32_e32 v172, v172, v173
	ds_bpermute_b32 v173, v176, v172
	global_store_dwordx4 v[174:175], v[178:181], off offset:256
	s_and_saveexec_b64 s[0:1], s[6:7]
	s_cbranch_execz .LBB0_678
	s_waitcnt lgkmcnt(0)
	v_add_f32_e32 v172, v172, v173
	v_mul_f32_e32 v172, 0x4b800000, v172
	v_trunc_f32_e32 v172, v172
	v_mul_f32_e32 v173, 0x2f800000, v172
	v_floor_f32_e32 v173, v173
	v_fmac_f32_e32 v172, 0xcf800000, v173
	v_cvt_u32_f32_e32 v172, v172
	v_cvt_u32_f32_e32 v173, v173
	v_lshl_add_u64 v[170:171], v[170:171], 3, s[18:19]
	global_atomic_add_x2 v[170:171], v[172:173], off
;     __device__ __forceinline__ void operator()(const pg8::f32x4 (&acc)[2][2][4][2], const pg8::Unit& u, int wr, int wc, int fr, int fq) const {
;         const int row0 = u.pm * 256 + wr * 64 + fr, col0 = u.pn * 256 + wc * 32 + 8 * fq;
;         if (mode >= 5) {
;             const bool hasF = mode == 5, outF = mode == 7;
;             u32x4 cb2 = {0u, 0u, 0u, 0u}, nb2 = cb2, cbb, nbb; float csc, nsc = 1.f, ss = 0.f;
;             {
;                 if (hasF) cb2 = *(const u32x4*)(base2 + (size_t)row0 * 1024 + col0);
;                 cbb = *(const u32x4*)(baseb + (size_t)row0 * 1024 + col0);
;                 csc = rowscale(row0);
;             }
;             nbb = cbb;
; #pragma unroll
;             for (int p = 0; p < 16; ++p) {
;                 const int g = p >> 1, bj = p & 1, ai = g >> 2, m = g & 3, r = row0 + ai * 128 + m * 16, c = col0 + bj * 128;
;                 if (p < 15) {
;                     const int gn = (p + 1) >> 1, rn = row0 + (gn >> 2) * 128 + (gn & 3) * 16, cn = col0 + ((p + 1) & 1) * 128;
;                     if (hasF) nb2 = *(const u32x4*)(base2 + (size_t)rn * 1024 + cn);
;                     nbb = *(const u32x4*)(baseb + (size_t)rn * 1024 + cn);
;                     if (bj == 1) nsc = rowscale(rn);
;                 }
;                 const f32x4 r0 = {bflo(cbb.x), bfhi(cbb.x), bflo(cbb.y), bfhi(cbb.y)}, r1 = {bflo(cbb.z), bfhi(cbb.z), bflo(cbb.w), bfhi(cbb.w)};
;                 const f32x4 q0 = {bflo(cb2.x), bfhi(cb2.x), bflo(cb2.y), bfhi(cb2.y)}, q1 = {bflo(cb2.z), bfhi(cb2.z), bflo(cb2.w), bfhi(cb2.w)};
;                 const f32x4 v0 = acc[ai][bj][m][0] * csc + q0 + r0, v1 = acc[ai][bj][m][1] * csc + q1 + r1;
;                 if (outF) {
;                     float* op = out + (size_t)r * 1024 + c;
;                     *(f32x4*)op = v0; *(f32x4*)(op + 4) = v1;
;                 } else {
;                     u32x4 w; w.x = pk2(v0[0], v0[1]); w.y = pk2(v0[2], v0[3]); w.z = pk2(v1[0], v1[1]); w.w = pk2(v1[2], v1[3]);
;                     *(u32x4*)(O + (size_t)r * 1024 + c) = w;
;                     ss += (v0[0] * v0[0] + v0[1] * v0[1]) + (v0[2] * v0[2] + v0[3] * v0[3]) + (v1[0] * v1[0] + v1[1] * v1[1]) + (v1[2] * v1[2] + v1[3] * v1[3]);
;                     if (bj == 1) {
;                         ss += __shfl_xor(ss, 16); ss += __shfl_xor(ss, 32);
.LBB0_678:
	s_or_b64 exec, exec, s[0:1]
	s_waitcnt vmcnt(1)
	v_ffbh_u32_e32 v170, v165
	v_min_u32_e32 v170, 32, v170
	v_lshlrev_b64 v[164:165], v170, v[164:165]
	v_min_u32_e32 v164, 1, v164
	v_or_b32_e32 v164, v165, v164
	v_cvt_f32_u32_e32 v164, v164
	global_load_dwordx4 v[178:181], v[168:169], off offset:256
	v_sub_u32_e32 v165, 32, v170
	v_ldexp_f32 v164, v164, v165
	v_fmamk_f32 v164, v164, 0x2f000000, v202
	v_mul_f32_e32 v165, 0x4b800000, v164
	v_cmp_gt_f32_e32 vcc, s66, v164
	s_nop 1
	v_cndmask_b32_e32 v164, v164, v165, vcc
	v_rsq_f32_e32 v170, v164
	v_lshlrev_b32_e32 v164, 16, v132
	v_and_b32_e32 v165, 0xffff0000, v132
	v_lshlrev_b32_e32 v132, 16, v133
	v_mul_f32_e32 v171, 0x45800000, v170
	v_cndmask_b32_e32 v174, v170, v171, vcc
	v_and_b32_e32 v133, 0xffff0000, v133
	s_waitcnt lgkmcnt(0)
	v_pk_fma_f32 v[172:173], v[64:65], v[174:175], 0 op_sel_hi:[1,0,0]
	v_pk_fma_f32 v[206:207], v[66:67], v[174:175], 0 op_sel_hi:[1,0,0]
	v_lshlrev_b32_e32 v170, 16, v134
	v_and_b32_e32 v171, 0xffff0000, v134
	v_lshlrev_b32_e32 v134, 16, v135
	v_and_b32_e32 v135, 0xffff0000, v135
	v_pk_add_f32 v[206:207], v[206:207], v[132:133]
	v_pk_add_f32 v[208:209], v[172:173], v[164:165]
	v_pk_fma_f32 v[132:133], v[60:61], v[174:175], 0 op_sel_hi:[1,0,0]
	v_pk_fma_f32 v[164:165], v[62:63], v[174:175], 0 op_sel_hi:[1,0,0]
	v_pk_add_f32 v[212:213], v[132:133], v[170:171]
	v_pk_add_f32 v[210:211], v[164:165], v[134:135]
	v_or_b32_e32 v164, 16, v166
	v_cvt_pk_bf16_f32 v132, v208, v209
	v_cvt_pk_bf16_f32 v133, v206, v207
	v_cvt_pk_bf16_f32 v134, v212, v213
	v_cvt_pk_bf16_f32 v135, v210, v211
	v_ashrrev_i32_e32 v165, 31, v164
	global_store_dwordx4 v[168:169], v[132:135], off
	v_lshl_add_u64 v[172:173], v[164:165], 3, s[22:23]
	global_load_dwordx2 v[172:173], v[172:173], off
	v_lshlrev_b64 v[132:133], 11, v[164:165]
	v_lshl_add_u64 v[132:133], s[78:79], 0, v[132:133]
	v_lshl_add_u64 v[170:171], v[162:163], 1, v[132:133]
	global_load_dwordx4 v[132:135], v[170:171], off
	v_mul_f32_e32 v177, v209, v209
	v_mul_f32_e32 v205, v207, v207
	v_mul_f32_e32 v207, v213, v213
	v_fmac_f32_e32 v177, v208, v208
	v_fmac_f32_e32 v205, v206, v206
	v_mul_f32_e32 v209, v211, v211
	v_fmac_f32_e32 v207, v212, v212
	v_add_f32_e32 v177, v177, v205
	v_pk_fma_f32 v[214:215], v[32:33], v[174:175], 0 op_sel_hi:[1,0,0]
	v_pk_fma_f32 v[216:217], v[34:35], v[174:175], 0 op_sel_hi:[1,0,0]
	v_fmac_f32_e32 v209, v210, v210
	v_add_f32_e32 v177, v207, v177
	v_pk_fma_f32 v[218:219], v[28:29], v[174:175], 0 op_sel_hi:[1,0,0]
	v_pk_fma_f32 v[174:175], v[30:31], v[174:175], 0 op_sel_hi:[1,0,0]
	v_add_f32_e32 v177, v209, v177
	s_waitcnt vmcnt(3)
	v_lshlrev_b32_e32 v206, 16, v178
	v_and_b32_e32 v207, 0xffff0000, v178
	v_lshlrev_b32_e32 v178, 16, v179
	v_and_b32_e32 v179, 0xffff0000, v179
	v_lshlrev_b32_e32 v208, 16, v180
	v_and_b32_e32 v209, 0xffff0000, v180
	v_lshlrev_b32_e32 v180, 16, v181
	v_and_b32_e32 v181, 0xffff0000, v181
	v_pk_add_f32 v[210:211], v[216:217], v[178:179]
	v_pk_add_f32 v[178:179], v[214:215], v[206:207]
	v_pk_add_f32 v[206:207], v[174:175], v[180:181]
	v_mul_f32_e32 v175, v179, v179
	v_mul_f32_e32 v205, v211, v211
	v_pk_add_f32 v[180:181], v[218:219], v[208:209]
	v_fmac_f32_e32 v175, v178, v178
	v_fmac_f32_e32 v205, v210, v210
	v_add_f32_e32 v175, v175, v205
	v_mul_f32_e32 v205, v181, v181
	v_mul_f32_e32 v174, v207, v207
	v_fmac_f32_e32 v205, v180, v180
	v_fmac_f32_e32 v174, v206, v206
	v_add_f32_e32 v175, v205, v175
	v_add_f32_e32 v174, v174, v175
	v_add_f32_e32 v174, v177, v174
	ds_bpermute_b32 v175, v1, v174
	v_cvt_pk_bf16_f32 v178, v178, v179
	v_cvt_pk_bf16_f32 v179, v210, v211
	v_cvt_pk_bf16_f32 v180, v180, v181
	v_cvt_pk_bf16_f32 v181, v206, v207
	s_waitcnt lgkmcnt(0)
	v_add_f32_e32 v174, v174, v175
	ds_bpermute_b32 v175, v176, v174
	global_store_dwordx4 v[168:169], v[178:181], off offset:256
	s_and_saveexec_b64 s[0:1], s[6:7]
	s_cbranch_execz .LBB0_680
	s_waitcnt lgkmcnt(0)
	v_add_f32_e32 v168, v174, v175
	v_mul_f32_e32 v168, 0x4b800000, v168
	v_trunc_f32_e32 v168, v168
	v_mul_f32_e32 v169, 0x2f800000, v168
	v_floor_f32_e32 v169, v169
	v_fmac_f32_e32 v168, 0xcf800000, v169
	v_cvt_u32_f32_e32 v168, v168
	v_cvt_u32_f32_e32 v169, v169
	v_lshl_add_u64 v[174:175], v[166:167], 3, s[18:19]
	global_atomic_add_x2 v[174:175], v[168:169], off
;     __device__ __forceinline__ void operator()(const pg8::f32x4 (&acc)[2][2][4][2], const pg8::Unit& u, int wr, int wc, int fr, int fq) const {
;         const int row0 = u.pm * 256 + wr * 64 + fr, col0 = u.pn * 256 + wc * 32 + 8 * fq;
;         if (mode >= 5) {
;             const bool hasF = mode == 5, outF = mode == 7;
;             u32x4 cb2 = {0u, 0u, 0u, 0u}, nb2 = cb2, cbb, nbb; float csc, nsc = 1.f, ss = 0.f;
;             {
;                 if (hasF) cb2 = *(const u32x4*)(base2 + (size_t)row0 * 1024 + col0);
;                 cbb = *(const u32x4*)(baseb + (size_t)row0 * 1024 + col0);
;                 csc = rowscale(row0);
;             }
;             nbb = cbb;
; #pragma unroll
;             for (int p = 0; p < 16; ++p) {
;                 const int g = p >> 1, bj = p & 1, ai = g >> 2, m = g & 3, r = row0 + ai * 128 + m * 16, c = col0 + bj * 128;
;                 if (p < 15) {
;                     const int gn = (p + 1) >> 1, rn = row0 + (gn >> 2) * 128 + (gn & 3) * 16, cn = col0 + ((p + 1) & 1) * 128;
;                     if (hasF) nb2 = *(const u32x4*)(base2 + (size_t)rn * 1024 + cn);
;                     nbb = *(const u32x4*)(baseb + (size_t)rn * 1024 + cn);
;                     if (bj == 1) nsc = rowscale(rn);
;                 }
;                 const f32x4 r0 = {bflo(cbb.x), bfhi(cbb.x), bflo(cbb.y), bfhi(cbb.y)}, r1 = {bflo(cbb.z), bfhi(cbb.z), bflo(cbb.w), bfhi(cbb.w)};
;                 const f32x4 q0 = {bflo(cb2.x), bfhi(cb2.x), bflo(cb2.y), bfhi(cb2.y)}, q1 = {bflo(cb2.z), bfhi(cb2.z), bflo(cb2.w), bfhi(cb2.w)};
;                 const f32x4 v0 = acc[ai][bj][m][0] * csc + q0 + r0, v1 = acc[ai][bj][m][1] * csc + q1 + r1;
;                 if (outF) {
;                     float* op = out + (size_t)r * 1024 + c;
;                     *(f32x4*)op = v0; *(f32x4*)(op + 4) = v1;
;                 } else {
;                     u32x4 w; w.x = pk2(v0[0], v0[1]); w.y = pk2(v0[2], v0[3]); w.z = pk2(v1[0], v1[1]); w.w = pk2(v1[2], v1[3]);
;                     *(u32x4*)(O + (size_t)r * 1024 + c) = w;
;                     ss += (v0[0] * v0[0] + v0[1] * v0[1]) + (v0[2] * v0[2] + v0[3] * v0[3]) + (v1[0] * v1[0] + v1[1] * v1[1]) + (v1[2] * v1[2] + v1[3] * v1[3]);
;                     if (bj == 1) {
;                         ss += __shfl_xor(ss, 16); ss += __shfl_xor(ss, 32);
.LBB0_680:
	s_or_b64 exec, exec, s[0:1]
	s_waitcnt vmcnt(2)
	v_ffbh_u32_e32 v167, v173
	v_min_u32_e32 v167, 32, v167
	v_lshlrev_b64 v[168:169], v167, v[172:173]
	v_min_u32_e32 v168, 1, v168
	v_or_b32_e32 v168, v169, v168
	v_cvt_f32_u32_e32 v168, v168
	global_load_dwordx4 v[178:181], v[170:171], off offset:256
	v_sub_u32_e32 v167, 32, v167
	s_waitcnt vmcnt(2)
	v_and_b32_e32 v169, 0xffff0000, v132
	v_ldexp_f32 v167, v168, v167
	v_fmamk_f32 v167, v167, 0x2f000000, v202
	v_mul_f32_e32 v168, 0x4b800000, v167
	v_cmp_gt_f32_e32 vcc, s66, v167
	v_and_b32_e32 v173, 0xffff0000, v134
	s_nop 0
	v_cndmask_b32_e32 v167, v167, v168, vcc
	v_rsq_f32_e32 v167, v167
	v_lshlrev_b32_e32 v168, 16, v132
	v_lshlrev_b32_e32 v132, 16, v133
	v_and_b32_e32 v133, 0xffff0000, v133
	v_mul_f32_e32 v172, 0x45800000, v167
	v_cndmask_b32_e32 v206, v167, v172, vcc
	s_waitcnt lgkmcnt(0)
	v_pk_fma_f32 v[174:175], v[56:57], v[206:207], 0 op_sel_hi:[1,0,0]
	v_pk_fma_f32 v[208:209], v[58:59], v[206:207], 0 op_sel_hi:[1,0,0]
	v_lshlrev_b32_e32 v172, 16, v134
	v_lshlrev_b32_e32 v134, 16, v135
	v_and_b32_e32 v135, 0xffff0000, v135
	v_pk_add_f32 v[208:209], v[208:209], v[132:133]
	v_pk_add_f32 v[210:211], v[174:175], v[168:169]
	v_pk_fma_f32 v[132:133], v[52:53], v[206:207], 0 op_sel_hi:[1,0,0]
	v_pk_fma_f32 v[168:169], v[54:55], v[206:207], 0 op_sel_hi:[1,0,0]
	v_pk_add_f32 v[214:215], v[132:133], v[172:173]
	v_pk_add_f32 v[212:213], v[168:169], v[134:135]
	v_or_b32_e32 v168, 32, v166
	v_cvt_pk_bf16_f32 v132, v210, v211
	v_cvt_pk_bf16_f32 v133, v208, v209
	v_cvt_pk_bf16_f32 v134, v214, v215
	v_cvt_pk_bf16_f32 v135, v212, v213
	v_ashrrev_i32_e32 v169, 31, v168
	global_store_dwordx4 v[170:171], v[132:135], off
	v_lshl_add_u64 v[174:175], v[168:169], 3, s[22:23]
	global_load_dwordx2 v[174:175], v[174:175], off
	v_lshlrev_b64 v[132:133], 11, v[168:169]
	v_lshl_add_u64 v[132:133], s[78:79], 0, v[132:133]
	v_lshl_add_u64 v[172:173], v[162:163], 1, v[132:133]
	global_load_dwordx4 v[132:135], v[172:173], off
	v_mul_f32_e32 v167, v211, v211
	v_mul_f32_e32 v177, v209, v209
	v_mul_f32_e32 v205, v215, v215
	v_fmac_f32_e32 v167, v210, v210
	v_fmac_f32_e32 v177, v208, v208
	v_mul_f32_e32 v209, v213, v213
	v_fmac_f32_e32 v205, v214, v214
	v_add_f32_e32 v167, v167, v177
	v_fmac_f32_e32 v209, v212, v212
	v_add_f32_e32 v167, v205, v167
	v_pk_fma_f32 v[216:217], v[24:25], v[206:207], 0 op_sel_hi:[1,0,0]
	v_pk_fma_f32 v[218:219], v[26:27], v[206:207], 0 op_sel_hi:[1,0,0]
	v_add_f32_e32 v167, v209, v167
	v_pk_fma_f32 v[220:221], v[20:21], v[206:207], 0 op_sel_hi:[1,0,0]
	v_pk_fma_f32 v[206:207], v[22:23], v[206:207], 0 op_sel_hi:[1,0,0]
	s_waitcnt vmcnt(3)
	v_lshlrev_b32_e32 v208, 16, v178
	v_and_b32_e32 v209, 0xffff0000, v178
	v_lshlrev_b32_e32 v178, 16, v179
	v_and_b32_e32 v179, 0xffff0000, v179
	v_pk_add_f32 v[212:213], v[218:219], v[178:179]
	v_pk_add_f32 v[178:179], v[216:217], v[208:209]
	v_lshlrev_b32_e32 v210, 16, v180
	v_and_b32_e32 v211, 0xffff0000, v180
	v_lshlrev_b32_e32 v180, 16, v181
	v_and_b32_e32 v181, 0xffff0000, v181
	v_mul_f32_e32 v205, v179, v179
	v_mul_f32_e32 v208, v213, v213
	v_pk_add_f32 v[206:207], v[206:207], v[180:181]
	v_pk_add_f32 v[180:181], v[220:221], v[210:211]
	v_fmac_f32_e32 v205, v178, v178
	v_fmac_f32_e32 v208, v212, v212
	v_add_f32_e32 v205, v205, v208
	v_mul_f32_e32 v208, v181, v181
	v_mul_f32_e32 v177, v207, v207
	v_fmac_f32_e32 v208, v180, v180
	v_fmac_f32_e32 v177, v206, v206
	v_add_f32_e32 v205, v208, v205
	v_add_f32_e32 v177, v177, v205
	v_add_f32_e32 v167, v167, v177
	ds_bpermute_b32 v177, v1, v167
	v_cvt_pk_bf16_f32 v178, v178, v179
	v_cvt_pk_bf16_f32 v179, v212, v213
	v_cvt_pk_bf16_f32 v180, v180, v181
	v_cvt_pk_bf16_f32 v181, v206, v207
	s_waitcnt lgkmcnt(0)
	v_add_f32_e32 v167, v167, v177
	ds_bpermute_b32 v177, v176, v167
	global_store_dwordx4 v[170:171], v[178:181], off offset:256
	s_and_saveexec_b64 s[0:1], s[6:7]
	s_cbranch_execz .LBB0_682
	s_waitcnt lgkmcnt(0)
	v_add_f32_e32 v167, v167, v177
	v_mul_f32_e32 v167, 0x4b800000, v167
	v_trunc_f32_e32 v167, v167
	v_mul_f32_e32 v170, 0x2f800000, v167
	v_floor_f32_e32 v171, v170
	v_fmac_f32_e32 v167, 0xcf800000, v171
	v_cvt_u32_f32_e32 v170, v167
	v_cvt_u32_f32_e32 v171, v171
	v_lshl_add_u64 v[164:165], v[164:165], 3, s[18:19]
	global_atomic_add_x2 v[164:165], v[170:171], off
;     __device__ __forceinline__ void operator()(const pg8::f32x4 (&acc)[2][2][4][2], const pg8::Unit& u, int wr, int wc, int fr, int fq) const {
;         const int row0 = u.pm * 256 + wr * 64 + fr, col0 = u.pn * 256 + wc * 32 + 8 * fq;
;         if (mode >= 5) {
;             const bool hasF = mode == 5, outF = mode == 7;
;             u32x4 cb2 = {0u, 0u, 0u, 0u}, nb2 = cb2, cbb, nbb; float csc, nsc = 1.f, ss = 0.f;
;             {
;                 if (hasF) cb2 = *(const u32x4*)(base2 + (size_t)row0 * 1024 + col0);
;                 cbb = *(const u32x4*)(baseb + (size_t)row0 * 1024 + col0);
;                 csc = rowscale(row0);
;             }
;             nbb = cbb;
; #pragma unroll
;             for (int p = 0; p < 16; ++p) {
;                 const int g = p >> 1, bj = p & 1, ai = g >> 2, m = g & 3, r = row0 + ai * 128 + m * 16, c = col0 + bj * 128;
;                 if (p < 15) {
;                     const int gn = (p + 1) >> 1, rn = row0 + (gn >> 2) * 128 + (gn & 3) * 16, cn = col0 + ((p + 1) & 1) * 128;
;                     if (hasF) nb2 = *(const u32x4*)(base2 + (size_t)rn * 1024 + cn);
;                     nbb = *(const u32x4*)(baseb + (size_t)rn * 1024 + cn);
;                     if (bj == 1) nsc = rowscale(rn);
;                 }
;                 const f32x4 r0 = {bflo(cbb.x), bfhi(cbb.x), bflo(cbb.y), bfhi(cbb.y)}, r1 = {bflo(cbb.z), bfhi(cbb.z), bflo(cbb.w), bfhi(cbb.w)};
;                 const f32x4 q0 = {bflo(cb2.x), bfhi(cb2.x), bflo(cb2.y), bfhi(cb2.y)}, q1 = {bflo(cb2.z), bfhi(cb2.z), bflo(cb2.w), bfhi(cb2.w)};
;                 const f32x4 v0 = acc[ai][bj][m][0] * csc + q0 + r0, v1 = acc[ai][bj][m][1] * csc + q1 + r1;
;                 if (outF) {
;                     float* op = out + (size_t)r * 1024 + c;
;                     *(f32x4*)op = v0; *(f32x4*)(op + 4) = v1;
;                 } else {
;                     u32x4 w; w.x = pk2(v0[0], v0[1]); w.y = pk2(v0[2], v0[3]); w.z = pk2(v1[0], v1[1]); w.w = pk2(v1[2], v1[3]);
;                     *(u32x4*)(O + (size_t)r * 1024 + c) = w;
;                     ss += (v0[0] * v0[0] + v0[1] * v0[1]) + (v0[2] * v0[2] + v0[3] * v0[3]) + (v1[0] * v1[0] + v1[1] * v1[1]) + (v1[2] * v1[2] + v1[3] * v1[3]);
;                     if (bj == 1) {
;                         ss += __shfl_xor(ss, 16); ss += __shfl_xor(ss, 32);
.LBB0_682:
	s_or_b64 exec, exec, s[0:1]
	s_waitcnt vmcnt(2)
	v_ffbh_u32_e32 v164, v175
	v_min_u32_e32 v167, 32, v164
	v_lshlrev_b64 v[164:165], v167, v[174:175]
	v_min_u32_e32 v164, 1, v164
	v_or_b32_e32 v164, v165, v164
	v_cvt_f32_u32_e32 v164, v164
	global_load_dwordx4 v[178:181], v[172:173], off offset:256
	v_sub_u32_e32 v165, 32, v167
	s_waitcnt vmcnt(2)
	v_lshlrev_b32_e32 v174, 16, v134
	v_ldexp_f32 v164, v164, v165
	v_fmamk_f32 v164, v164, 0x2f000000, v202
	v_mul_f32_e32 v165, 0x4b800000, v164
	v_cmp_gt_f32_e32 vcc, s66, v164
	v_and_b32_e32 v175, 0xffff0000, v134
	v_lshlrev_b32_e32 v134, 16, v135
	v_cndmask_b32_e32 v164, v164, v165, vcc
	v_rsq_f32_e32 v167, v164
	v_lshlrev_b32_e32 v164, 16, v132
	v_and_b32_e32 v165, 0xffff0000, v132
	v_lshlrev_b32_e32 v132, 16, v133
	v_mul_f32_e32 v170, 0x45800000, v167
	v_cndmask_b32_e32 v170, v167, v170, vcc
	v_and_b32_e32 v133, 0xffff0000, v133
	v_pk_fma_f32 v[206:207], v[48:49], v[170:171], 0 op_sel_hi:[1,0,0]
	v_pk_fma_f32 v[208:209], v[50:51], v[170:171], 0 op_sel_hi:[1,0,0]
	v_and_b32_e32 v135, 0xffff0000, v135
	v_pk_add_f32 v[208:209], v[208:209], v[132:133]
	v_pk_add_f32 v[206:207], v[206:207], v[164:165]
	v_pk_fma_f32 v[132:133], v[44:45], v[170:171], 0 op_sel_hi:[1,0,0]
	v_pk_fma_f32 v[164:165], v[46:47], v[170:171], 0 op_sel_hi:[1,0,0]
	v_pk_add_f32 v[174:175], v[132:133], v[174:175]
	v_pk_add_f32 v[210:211], v[164:165], v[134:135]
	v_or_b32_e32 v164, 48, v166
	v_cvt_pk_bf16_f32 v132, v206, v207
	v_cvt_pk_bf16_f32 v133, v208, v209
	v_cvt_pk_bf16_f32 v134, v174, v175
	v_cvt_pk_bf16_f32 v135, v210, v211
	v_ashrrev_i32_e32 v165, 31, v164
	global_store_dwordx4 v[172:173], v[132:135], off
	v_lshl_add_u64 v[166:167], v[164:165], 3, s[22:23]
	global_load_dwordx2 v[166:167], v[166:167], off
	v_lshlrev_b64 v[132:133], 11, v[164:165]
	v_lshl_add_u64 v[132:133], s[78:79], 0, v[132:133]
	v_lshl_add_u64 v[162:163], v[162:163], 1, v[132:133]
	global_load_dwordx4 v[132:135], v[162:163], off
	s_waitcnt lgkmcnt(0)
	v_mul_f32_e32 v177, v207, v207
	v_mul_f32_e32 v205, v209, v209
	v_mul_f32_e32 v175, v175, v175
	v_fmac_f32_e32 v177, v206, v206
	v_fmac_f32_e32 v205, v208, v208
	v_mul_f32_e32 v207, v211, v211
	v_fmac_f32_e32 v175, v174, v174
	v_add_f32_e32 v174, v177, v205
	v_fmac_f32_e32 v207, v210, v210
	v_add_f32_e32 v174, v175, v174
	v_pk_fma_f32 v[212:213], v[16:17], v[170:171], 0 op_sel_hi:[1,0,0]
	v_pk_fma_f32 v[214:215], v[18:19], v[170:171], 0 op_sel_hi:[1,0,0]
	v_add_f32_e32 v177, v207, v174
	v_pk_fma_f32 v[216:217], v[12:13], v[170:171], 0 op_sel_hi:[1,0,0]
	v_pk_fma_f32 v[170:171], v[14:15], v[170:171], 0 op_sel_hi:[1,0,0]
	s_waitcnt vmcnt(3)
	v_lshlrev_b32_e32 v174, 16, v178
	v_and_b32_e32 v175, 0xffff0000, v178
	v_lshlrev_b32_e32 v178, 16, v179
	v_and_b32_e32 v179, 0xffff0000, v179
	v_lshlrev_b32_e32 v206, 16, v180
	v_and_b32_e32 v207, 0xffff0000, v180
	v_lshlrev_b32_e32 v180, 16, v181
	v_and_b32_e32 v181, 0xffff0000, v181
	v_pk_add_f32 v[208:209], v[214:215], v[178:179]
	v_pk_add_f32 v[174:175], v[212:213], v[174:175]
	v_pk_add_f32 v[210:211], v[170:171], v[180:181]
	v_mul_f32_e32 v171, v175, v175
	v_mul_f32_e32 v178, v209, v209
	v_pk_add_f32 v[180:181], v[216:217], v[206:207]
	v_fmac_f32_e32 v171, v174, v174
	v_fmac_f32_e32 v178, v208, v208
	v_add_f32_e32 v171, v171, v178
	v_mul_f32_e32 v178, v181, v181
	v_mul_f32_e32 v170, v211, v211
	v_fmac_f32_e32 v178, v180, v180
	v_fmac_f32_e32 v170, v210, v210
	v_add_f32_e32 v171, v178, v171
	v_add_f32_e32 v170, v170, v171
	v_add_f32_e32 v170, v177, v170
	ds_bpermute_b32 v171, v1, v170
	v_cvt_pk_bf16_f32 v178, v174, v175
	v_cvt_pk_bf16_f32 v179, v208, v209
	v_cvt_pk_bf16_f32 v180, v180, v181
	v_cvt_pk_bf16_f32 v181, v210, v211
	s_waitcnt lgkmcnt(0)
	v_add_f32_e32 v170, v170, v171
	ds_bpermute_b32 v171, v176, v170
	global_store_dwordx4 v[172:173], v[178:181], off offset:256
	s_and_saveexec_b64 s[0:1], s[6:7]
	s_cbranch_execz .LBB0_684
	s_waitcnt lgkmcnt(0)
	v_add_f32_e32 v170, v170, v171
	v_mul_f32_e32 v170, 0x4b800000, v170
	v_trunc_f32_e32 v170, v170
	v_mul_f32_e32 v171, 0x2f800000, v170
	v_floor_f32_e32 v171, v171
	v_fmac_f32_e32 v170, 0xcf800000, v171
	v_cvt_u32_f32_e32 v170, v170
	v_cvt_u32_f32_e32 v171, v171
	v_lshl_add_u64 v[168:169], v[168:169], 3, s[18:19]
	global_atomic_add_x2 v[168:169], v[170:171], off
;     __device__ __forceinline__ void operator()(const pg8::f32x4 (&acc)[2][2][4][2], const pg8::Unit& u, int wr, int wc, int fr, int fq) const {
;         const int row0 = u.pm * 256 + wr * 64 + fr, col0 = u.pn * 256 + wc * 32 + 8 * fq;
;         if (mode >= 5) {
;             const bool hasF = mode == 5, outF = mode == 7;
;             u32x4 cb2 = {0u, 0u, 0u, 0u}, nb2 = cb2, cbb, nbb; float csc, nsc = 1.f, ss = 0.f;
;             {
;                 if (hasF) cb2 = *(const u32x4*)(base2 + (size_t)row0 * 1024 + col0);
;                 cbb = *(const u32x4*)(baseb + (size_t)row0 * 1024 + col0);
;                 csc = rowscale(row0);
;             }
;             nbb = cbb;
; #pragma unroll
;             for (int p = 0; p < 16; ++p) {
;                 const int g = p >> 1, bj = p & 1, ai = g >> 2, m = g & 3, r = row0 + ai * 128 + m * 16, c = col0 + bj * 128;
;                 if (p < 15) {
;                     const int gn = (p + 1) >> 1, rn = row0 + (gn >> 2) * 128 + (gn & 3) * 16, cn = col0 + ((p + 1) & 1) * 128;
;                     if (hasF) nb2 = *(const u32x4*)(base2 + (size_t)rn * 1024 + cn);
;                     nbb = *(const u32x4*)(baseb + (size_t)rn * 1024 + cn);
;                     if (bj == 1) nsc = rowscale(rn);
;                 }
;                 const f32x4 r0 = {bflo(cbb.x), bfhi(cbb.x), bflo(cbb.y), bfhi(cbb.y)}, r1 = {bflo(cbb.z), bfhi(cbb.z), bflo(cbb.w), bfhi(cbb.w)};
;                 const f32x4 q0 = {bflo(cb2.x), bfhi(cb2.x), bflo(cb2.y), bfhi(cb2.y)}, q1 = {bflo(cb2.z), bfhi(cb2.z), bflo(cb2.w), bfhi(cb2.w)};
;                 const f32x4 v0 = acc[ai][bj][m][0] * csc + q0 + r0, v1 = acc[ai][bj][m][1] * csc + q1 + r1;
;                 if (outF) {
;                     float* op = out + (size_t)r * 1024 + c;
;                     *(f32x4*)op = v0; *(f32x4*)(op + 4) = v1;
;                 } else {
;                     u32x4 w; w.x = pk2(v0[0], v0[1]); w.y = pk2(v0[2], v0[3]); w.z = pk2(v1[0], v1[1]); w.w = pk2(v1[2], v1[3]);
;                     *(u32x4*)(O + (size_t)r * 1024 + c) = w;
;                     ss += (v0[0] * v0[0] + v0[1] * v0[1]) + (v0[2] * v0[2] + v0[3] * v0[3]) + (v1[0] * v1[0] + v1[1] * v1[1]) + (v1[2] * v1[2] + v1[3] * v1[3]);
;                     if (bj == 1) {
;                         ss += __shfl_xor(ss, 16); ss += __shfl_xor(ss, 32);
.LBB0_684:
	s_or_b64 exec, exec, s[0:1]
	s_waitcnt lgkmcnt(0)
	global_load_dwordx4 v[168:171], v[162:163], off offset:256
	s_waitcnt vmcnt(3)
	v_ffbh_u32_e32 v174, v167
	v_min_u32_e32 v174, 32, v174
	v_lshlrev_b64 v[166:167], v174, v[166:167]
	v_min_u32_e32 v166, 1, v166
	v_or_b32_e32 v166, v167, v166
	v_cvt_f32_u32_e32 v167, v166
	v_sub_u32_e32 v174, 32, v174
	s_waitcnt vmcnt(2)
	v_lshlrev_b32_e32 v172, 16, v132
	v_and_b32_e32 v173, 0xffff0000, v132
	v_ldexp_f32 v167, v167, v174
	v_fmamk_f32 v167, v167, 0x2f000000, v202
	v_mul_f32_e32 v174, 0x4b800000, v167
	v_cmp_gt_f32_e32 vcc, s66, v167
	v_lshlrev_b32_e32 v132, 16, v133
	v_and_b32_e32 v133, 0xffff0000, v133
	v_cndmask_b32_e32 v167, v167, v174, vcc
	v_rsq_f32_e32 v174, v167
	v_lshlrev_b32_e32 v166, 16, v134
	v_and_b32_e32 v167, 0xffff0000, v134
	v_lshlrev_b32_e32 v134, 16, v135
	v_mul_f32_e32 v175, 0x45800000, v174
	v_cndmask_b32_e32 v174, v174, v175, vcc
	v_pk_fma_f32 v[178:179], v[40:41], v[174:175], 0 op_sel_hi:[1,0,0]
	v_pk_fma_f32 v[180:181], v[42:43], v[174:175], 0 op_sel_hi:[1,0,0]
	v_and_b32_e32 v135, 0xffff0000, v135
	v_pk_fma_f32 v[206:207], v[36:37], v[174:175], 0 op_sel_hi:[1,0,0]
	v_pk_fma_f32 v[208:209], v[38:39], v[174:175], 0 op_sel_hi:[1,0,0]
	v_pk_add_f32 v[180:181], v[180:181], v[132:133]
	v_pk_add_f32 v[172:173], v[178:179], v[172:173]
	v_pk_add_f32 v[178:179], v[208:209], v[134:135]
	v_pk_add_f32 v[134:135], v[206:207], v[166:167]
	v_mul_f32_e32 v166, v173, v173
	v_mul_f32_e32 v167, v181, v181
	v_cvt_pk_bf16_f32 v132, v172, v173
	v_mul_f32_e32 v173, v135, v135
	v_fmac_f32_e32 v166, v172, v172
	v_fmac_f32_e32 v167, v180, v180
	v_mul_f32_e32 v177, v179, v179
	v_fmac_f32_e32 v173, v134, v134
	v_add_f32_e32 v166, v166, v167
	v_fmac_f32_e32 v177, v178, v178
	v_add_f32_e32 v166, v173, v166
	v_pk_fma_f32 v[210:211], v[8:9], v[174:175], 0 op_sel_hi:[1,0,0]
	v_pk_fma_f32 v[212:213], v[10:11], v[174:175], 0 op_sel_hi:[1,0,0]
	v_add_f32_e32 v177, v177, v166
	v_pk_fma_f32 v[214:215], v[4:5], v[174:175], 0 op_sel_hi:[1,0,0]
	v_pk_fma_f32 v[174:175], v[6:7], v[174:175], 0 op_sel_hi:[1,0,0]
	v_cvt_pk_bf16_f32 v133, v180, v181
	v_cvt_pk_bf16_f32 v134, v134, v135
	v_cvt_pk_bf16_f32 v135, v178, v179
	global_store_dwordx4 v[162:163], v[132:135], off
	s_waitcnt vmcnt(1)
	v_lshlrev_b32_e32 v166, 16, v168
	v_and_b32_e32 v167, 0xffff0000, v168
	v_lshlrev_b32_e32 v168, 16, v169
	v_and_b32_e32 v169, 0xffff0000, v169
	v_lshlrev_b32_e32 v172, 16, v170
	v_and_b32_e32 v173, 0xffff0000, v170
	v_lshlrev_b32_e32 v170, 16, v171
	v_and_b32_e32 v171, 0xffff0000, v171
	v_pk_add_f32 v[168:169], v[212:213], v[168:169]
	v_pk_add_f32 v[166:167], v[210:211], v[166:167]
	v_pk_add_f32 v[170:171], v[174:175], v[170:171]
	v_pk_add_f32 v[172:173], v[214:215], v[172:173]
	v_mul_f32_e32 v175, v167, v167
	v_mul_f32_e32 v180, v169, v169
	v_mul_f32_e32 v181, v173, v173
	v_fmac_f32_e32 v175, v166, v166
	v_fmac_f32_e32 v180, v168, v168
	v_mul_f32_e32 v174, v171, v171
	v_add_f32_e32 v175, v175, v180
	v_fmac_f32_e32 v181, v172, v172
	v_fmac_f32_e32 v174, v170, v170
	v_add_f32_e32 v175, v181, v175
	v_add_f32_e32 v174, v174, v175
	v_add_f32_e32 v174, v177, v174
	ds_bpermute_b32 v1, v1, v174
	v_cvt_pk_bf16_f32 v166, v166, v167
	v_cvt_pk_bf16_f32 v167, v168, v169
	v_cvt_pk_bf16_f32 v168, v172, v173
	v_cvt_pk_bf16_f32 v169, v170, v171
	s_waitcnt lgkmcnt(0)
	v_add_f32_e32 v1, v174, v1
	ds_bpermute_b32 v132, v176, v1
	global_store_dwordx4 v[162:163], v[166:169], off offset:256
	s_and_saveexec_b64 s[0:1], s[6:7]
	s_cbranch_execz .LBB0_686
	s_waitcnt lgkmcnt(0)
	v_add_f32_e32 v1, v1, v132
	v_mul_f32_e32 v1, 0x4b800000, v1
	v_trunc_f32_e32 v1, v1
	v_mul_f32_e32 v132, 0x2f800000, v1
	v_floor_f32_e32 v133, v132
	v_fmac_f32_e32 v1, 0xcf800000, v133
	v_cvt_u32_f32_e32 v132, v1
	v_cvt_u32_f32_e32 v133, v133
	v_lshl_add_u64 v[134:135], v[164:165], 3, s[18:19]
	global_atomic_add_x2 v[134:135], v[132:133], off

;     __device__ __forceinline__ void operator()(const pg8::f32x4 (&acc)[2][2][4][2], const pg8::Unit& u, int wr, int wc, int fr, int fq) const {
;     ...
;         if (mode >= 5) {
;             const bool hasF = mode == 5, outF = mode == 7;
;             u32x4 cb2 = {0u, 0u, 0u, 0u}, nb2 = cb2, cbb, nbb; float csc, nsc = 1.f, ss = 0.f;
;             {
;                 if (hasF) cb2 = *(const u32x4*)(base2 + (size_t)row0 * 1024 + col0);
;                 cbb = *(const u32x4*)(baseb + (size_t)row0 * 1024 + col0);
;                 csc = rowscale(row0);
;             }
;             nbb = cbb;
; #pragma unroll
;             for (int p = 0; p < 16; ++p) {
;                 const int g = p >> 1, bj = p & 1, ai = g >> 2, m = g & 3, r = row0 + ai * 128 + m * 16, c = col0 + bj * 128;
;                 if (p < 15) {
;                     const int gn = (p + 1) >> 1, rn = row0 + (gn >> 2) * 128 + (gn & 3) * 16, cn = col0 + ((p + 1) & 1) * 128;
;                     if (hasF) nb2 = *(const u32x4*)(base2 + (size_t)rn * 1024 + cn);
;                     nbb = *(const u32x4*)(baseb + (size_t)rn * 1024 + cn);
;                     if (bj == 1) nsc = rowscale(rn);
;                 }
;                 const f32x4 r0 = {bflo(cbb.x), bfhi(cbb.x), bflo(cbb.y), bfhi(cbb.y)}, r1 = {bflo(cbb.z), bfhi(cbb.z), bflo(cbb.w), bfhi(cbb.w)};
;                 const f32x4 q0 = {bflo(cb2.x), bfhi(cb2.x), bflo(cb2.y), bfhi(cb2.y)}, q1 = {bflo(cb2.z), bfhi(cb2.z), bflo(cb2.w), bfhi(cb2.w)};
;                 const f32x4 v0 = acc[ai][bj][m][0] * csc + q0 + r0, v1 = acc[ai][bj][m][1] * csc + q1 + r1;
;                 if (outF) {
;                     float* op = out + (size_t)r * 1024 + c;
;                     *(f32x4*)op = v0; *(f32x4*)(op + 4) = v1;
;                 } else {
;                     u32x4 w; w.x = pk2(v0[0], v0[1]); w.y = pk2(v0[2], v0[3]); w.z = pk2(v1[0], v1[1]); w.w = pk2(v1[2], v1[3]);
;                     *(u32x4*)(O + (size_t)r * 1024 + c) = w;
;                     ss += (v0[0] * v0[0] + v0[1] * v0[1]) + (v0[2] * v0[2] + v0[3] * v0[3]) + (v1[0] * v1[0] + v1[1] * v1[1]) + (v1[2] * v1[2] + v1[3] * v1[3]);
;                     if (bj == 1) {
;                         ss += __shfl_xor(ss, 16); ss += __shfl_xor(ss, 32);
;                         if (fq == 0) atomicAdd(rss + r, (u64)(ss * RSS_FIX));
;                         ss = 0.f;
;                     }
.LBB0_886:
	v_lshl_add_u32 v158, s24, 8, v137
	v_lshl_or_b32 v156, s22, 8, v141
	v_ashrrev_i32_e32 v159, 31, v158
	v_lshlrev_b64 v[128:129], 11, v[158:159]
	v_ashrrev_i32_e32 v157, 31, v156
	v_lshl_add_u64 v[128:129], s[78:79], 0, v[128:129]
	v_lshlrev_b64 v[130:131], 1, v[156:157]
	v_lshl_add_u64 v[176:177], v[128:129], 0, v[130:131]
	global_load_dwordx4 v[168:171], v[176:177], off
	global_load_dwordx4 v[172:175], v[176:177], off offset:256
	v_or_b32_e32 v160, 16, v158
	v_ashrrev_i32_e32 v161, 31, v160
	v_lshlrev_b64 v[128:129], 11, v[160:161]
	v_lshl_add_u64 v[128:129], s[78:79], 0, v[128:129]
	v_lshl_add_u64 v[162:163], v[128:129], 0, v[130:131]
	global_load_dwordx4 v[128:131], v[162:163], off
	v_pk_add_f32 v[126:127], v[126:127], 0 op_sel_hi:[1,0]
	v_pk_add_f32 v[124:125], v[124:125], 0 op_sel_hi:[1,0]
	v_pk_add_f32 v[118:119], v[118:119], 0 op_sel_hi:[1,0]
	v_pk_add_f32 v[116:117], v[116:117], 0 op_sel_hi:[1,0]
	v_pk_add_f32 v[178:179], v[112:113], 0 op_sel_hi:[1,0]
	v_and_b32_e32 v113, 64, v166
	v_pk_add_f32 v[122:123], v[122:123], 0 op_sel_hi:[1,0]
	v_pk_add_f32 v[120:121], v[120:121], 0 op_sel_hi:[1,0]
	v_pk_add_f32 v[114:115], v[114:115], 0 op_sel_hi:[1,0]
	v_xor_b32_e32 v112, 16, v166
	v_add_u32_e32 v113, 64, v113
	v_xor_b32_e32 v167, 32, v166
	v_cmp_lt_i32_e32 vcc, v112, v113
	s_waitcnt vmcnt(0)
	v_lshlrev_b32_e32 v180, 16, v168
	v_and_b32_e32 v181, 0xffff0000, v168
	v_lshlrev_b32_e32 v168, 16, v169
	v_and_b32_e32 v169, 0xffff0000, v169
	v_lshlrev_b32_e32 v198, 16, v172
	v_and_b32_e32 v199, 0xffff0000, v172
	v_lshlrev_b32_e32 v172, 16, v173
	v_and_b32_e32 v173, 0xffff0000, v173
	v_lshlrev_b32_e32 v196, 16, v170
	v_and_b32_e32 v197, 0xffff0000, v170
	v_lshlrev_b32_e32 v170, 16, v171
	v_and_b32_e32 v171, 0xffff0000, v171
	v_lshlrev_b32_e32 v200, 16, v174
	v_and_b32_e32 v201, 0xffff0000, v174
	v_lshlrev_b32_e32 v174, 16, v175
	v_and_b32_e32 v175, 0xffff0000, v175
	v_pk_add_f32 v[126:127], v[126:127], v[168:169]
	v_pk_add_f32 v[124:125], v[124:125], v[180:181]
	v_pk_add_f32 v[168:169], v[118:119], v[172:173]
	v_pk_add_f32 v[118:119], v[116:117], v[198:199]
	v_pk_add_f32 v[122:123], v[122:123], v[170:171]
	v_pk_add_f32 v[120:121], v[120:121], v[196:197]
	v_pk_add_f32 v[170:171], v[114:115], v[174:175]
	v_pk_add_f32 v[172:173], v[178:179], v[200:201]
	v_mul_f32_e32 v116, v125, v125
	v_mul_f32_e32 v117, v127, v127
	v_mul_f32_e32 v174, v119, v119
	v_mul_f32_e32 v175, v169, v169
	v_cndmask_b32_e32 v112, v166, v112, vcc
	v_cmp_lt_i32_e32 vcc, v167, v113
	v_cvt_pk_bf16_f32 v114, v124, v125
	v_mul_f32_e32 v125, v121, v121
	v_mul_f32_e32 v178, v173, v173
	v_fmac_f32_e32 v116, v124, v124
	v_fmac_f32_e32 v117, v126, v126
	v_fmac_f32_e32 v174, v118, v118
	v_fmac_f32_e32 v175, v168, v168
	v_cndmask_b32_e32 v113, v166, v167, vcc
	v_cvt_pk_bf16_f32 v115, v126, v127
	v_mul_f32_e32 v127, v123, v123
	v_mul_f32_e32 v167, v171, v171
	v_fmac_f32_e32 v125, v120, v120
	v_fmac_f32_e32 v178, v172, v172
	v_add_f32_e32 v116, v116, v117
	v_add_f32_e32 v117, v174, v175
	v_fmac_f32_e32 v127, v122, v122
	v_fmac_f32_e32 v167, v170, v170
	v_add_f32_e32 v116, v125, v116
	v_add_f32_e32 v117, v178, v117
	v_add_f32_e32 v116, v127, v116
	v_add_f32_e32 v117, v167, v117
	v_lshlrev_b32_e32 v112, 2, v112
	v_add_f32_e32 v124, v116, v117
	ds_bpermute_b32 v125, v112, v124
	v_cvt_pk_bf16_f32 v116, v120, v121
	v_cvt_pk_bf16_f32 v117, v122, v123
	global_store_dwordx4 v[176:177], v[114:117], off
	v_lshlrev_b32_e32 v113, 2, v113
	v_cvt_pk_bf16_f32 v118, v118, v119
	s_waitcnt lgkmcnt(0)
	v_add_f32_e32 v114, v124, v125
	ds_bpermute_b32 v115, v113, v114
	v_cvt_pk_bf16_f32 v119, v168, v169
	v_cvt_pk_bf16_f32 v120, v172, v173
	v_cvt_pk_bf16_f32 v121, v170, v171
	global_store_dwordx4 v[176:177], v[118:121], off offset:256
	s_and_saveexec_b64 s[22:23], s[4:5]
	s_cbranch_execz .LBB0_888
	s_waitcnt lgkmcnt(0)
	v_add_f32_e32 v114, v114, v115
	v_mul_f32_e32 v114, 0x4b800000, v114
	v_trunc_f32_e32 v114, v114
	v_mul_f32_e32 v115, 0x2f800000, v114
	v_floor_f32_e32 v115, v115
	v_fmac_f32_e32 v114, 0xcf800000, v115
	v_cvt_u32_f32_e32 v114, v114
	v_cvt_u32_f32_e32 v115, v115
	v_lshl_add_u64 v[116:117], v[158:159], 3, s[12:13]
	global_atomic_add_x2 v[116:117], v[114:115], off
.LBB0_888:
	s_or_b64 exec, exec, s[22:23]
	s_waitcnt lgkmcnt(0)
	global_load_dwordx4 v[114:117], v[162:163], off offset:256
	v_lshlrev_b32_e32 v118, 16, v128
	v_and_b32_e32 v119, 0xffff0000, v128
	v_lshlrev_b32_e32 v120, 16, v129
	v_and_b32_e32 v121, 0xffff0000, v129
	v_lshlrev_b32_e32 v122, 16, v130
	v_and_b32_e32 v123, 0xffff0000, v130
	v_lshlrev_b32_e32 v124, 16, v131
	v_and_b32_e32 v125, 0xffff0000, v131
	v_pk_add_f32 v[110:111], v[110:111], 0 op_sel_hi:[1,0]
	v_pk_add_f32 v[126:127], v[108:109], 0 op_sel_hi:[1,0]
	v_pk_add_f32 v[106:107], v[106:107], 0 op_sel_hi:[1,0]
	v_pk_add_f32 v[104:105], v[104:105], 0 op_sel_hi:[1,0]
	v_or_b32_e32 v108, 32, v158
	v_pk_add_f32 v[120:121], v[110:111], v[120:121]
	v_pk_add_f32 v[118:119], v[126:127], v[118:119]
	v_pk_add_f32 v[124:125], v[106:107], v[124:125]
	v_pk_add_f32 v[122:123], v[104:105], v[122:123]
	v_ashrrev_i32_e32 v109, 31, v108
	v_cvt_pk_bf16_f32 v104, v118, v119
	v_cvt_pk_bf16_f32 v105, v120, v121
	v_cvt_pk_bf16_f32 v106, v122, v123
	v_cvt_pk_bf16_f32 v107, v124, v125
	v_lshlrev_b64 v[110:111], 11, v[108:109]
	global_store_dwordx4 v[162:163], v[104:107], off
	v_mul_f32_e32 v119, v119, v119
	v_mul_f32_e32 v121, v121, v121
	v_lshl_add_u64 v[104:105], s[78:79], 0, v[110:111]
	v_lshl_add_u64 v[110:111], v[156:157], 1, v[104:105]
	global_load_dwordx4 v[104:107], v[110:111], off
	v_mul_f32_e32 v123, v123, v123
	v_fmac_f32_e32 v119, v118, v118
	v_fmac_f32_e32 v121, v120, v120
	v_mul_f32_e32 v125, v125, v125
	v_fmac_f32_e32 v123, v122, v122
	v_add_f32_e32 v118, v119, v121
	v_fmac_f32_e32 v125, v124, v124
	v_add_f32_e32 v118, v123, v118
	v_pk_add_f32 v[102:103], v[102:103], 0 op_sel_hi:[1,0]
	v_pk_add_f32 v[100:101], v[100:101], 0 op_sel_hi:[1,0]
	v_add_f32_e32 v122, v125, v118
	v_pk_add_f32 v[98:99], v[98:99], 0 op_sel_hi:[1,0]
	v_pk_add_f32 v[96:97], v[96:97], 0 op_sel_hi:[1,0]
	s_waitcnt vmcnt(2)
;     __device__ __forceinline__ void operator()(const pg8::f32x4 (&acc)[2][2][4][2], const pg8::Unit& u, int wr, int wc, int fr, int fq) const {
;     ...
;         if (mode >= 5) {
;             const bool hasF = mode == 5, outF = mode == 7;
;             u32x4 cb2 = {0u, 0u, 0u, 0u}, nb2 = cb2, cbb, nbb; float csc, nsc = 1.f, ss = 0.f;
;             {
;                 if (hasF) cb2 = *(const u32x4*)(base2 + (size_t)row0 * 1024 + col0);
;                 cbb = *(const u32x4*)(baseb + (size_t)row0 * 1024 + col0);
;                 csc = rowscale(row0);
;             }
;             nbb = cbb;
; #pragma unroll
;             for (int p = 0; p < 16; ++p) {
;                 const int g = p >> 1, bj = p & 1, ai = g >> 2, m = g & 3, r = row0 + ai * 128 + m * 16, c = col0 + bj * 128;
;                 if (p < 15) {
;                     const int gn = (p + 1) >> 1, rn = row0 + (gn >> 2) * 128 + (gn & 3) * 16, cn = col0 + ((p + 1) & 1) * 128;
;                     if (hasF) nb2 = *(const u32x4*)(base2 + (size_t)rn * 1024 + cn);
;                     nbb = *(const u32x4*)(baseb + (size_t)rn * 1024 + cn);
;                     if (bj == 1) nsc = rowscale(rn);
;                 }
;                 const f32x4 r0 = {bflo(cbb.x), bfhi(cbb.x), bflo(cbb.y), bfhi(cbb.y)}, r1 = {bflo(cbb.z), bfhi(cbb.z), bflo(cbb.w), bfhi(cbb.w)};
;                 const f32x4 q0 = {bflo(cb2.x), bfhi(cb2.x), bflo(cb2.y), bfhi(cb2.y)}, q1 = {bflo(cb2.z), bfhi(cb2.z), bflo(cb2.w), bfhi(cb2.w)};
;                 const f32x4 v0 = acc[ai][bj][m][0] * csc + q0 + r0, v1 = acc[ai][bj][m][1] * csc + q1 + r1;
;                 if (outF) {
;                     float* op = out + (size_t)r * 1024 + c;
;                     *(f32x4*)op = v0; *(f32x4*)(op + 4) = v1;
;                 } else {
;                     u32x4 w; w.x = pk2(v0[0], v0[1]); w.y = pk2(v0[2], v0[3]); w.z = pk2(v1[0], v1[1]); w.w = pk2(v1[2], v1[3]);
;                     *(u32x4*)(O + (size_t)r * 1024 + c) = w;
;                     ss += (v0[0] * v0[0] + v0[1] * v0[1]) + (v0[2] * v0[2] + v0[3] * v0[3]) + (v1[0] * v1[0] + v1[1] * v1[1]) + (v1[2] * v1[2] + v1[3] * v1[3]);
;                     if (bj == 1) {
;                         ss += __shfl_xor(ss, 16); ss += __shfl_xor(ss, 32);
;                         if (fq == 0) atomicAdd(rss + r, (u64)(ss * RSS_FIX));
;                         ss = 0.f;
;                     }
	v_lshlrev_b32_e32 v118, 16, v114
	v_and_b32_e32 v119, 0xffff0000, v114
	v_lshlrev_b32_e32 v114, 16, v115
	v_and_b32_e32 v115, 0xffff0000, v115
	v_lshlrev_b32_e32 v120, 16, v116
	v_and_b32_e32 v121, 0xffff0000, v116
	v_lshlrev_b32_e32 v116, 16, v117
	v_and_b32_e32 v117, 0xffff0000, v117
	v_pk_add_f32 v[102:103], v[102:103], v[114:115]
	v_pk_add_f32 v[100:101], v[100:101], v[118:119]
	v_pk_add_f32 v[114:115], v[98:99], v[116:117]
	v_pk_add_f32 v[116:117], v[96:97], v[120:121]
	v_mul_f32_e32 v97, v101, v101
	v_mul_f32_e32 v98, v103, v103
	v_mul_f32_e32 v99, v117, v117
	v_fmac_f32_e32 v97, v100, v100
	v_fmac_f32_e32 v98, v102, v102
	v_mul_f32_e32 v96, v115, v115
	v_add_f32_e32 v97, v97, v98
	v_fmac_f32_e32 v99, v116, v116
	v_fmac_f32_e32 v96, v114, v114
	v_add_f32_e32 v97, v99, v97
	v_add_f32_e32 v96, v96, v97
	v_add_f32_e32 v96, v122, v96
	ds_bpermute_b32 v97, v112, v96
	v_cvt_pk_bf16_f32 v98, v100, v101
	v_cvt_pk_bf16_f32 v99, v102, v103
	v_cvt_pk_bf16_f32 v100, v116, v117
	v_cvt_pk_bf16_f32 v101, v114, v115
	s_waitcnt lgkmcnt(0)
	v_add_f32_e32 v96, v96, v97
	ds_bpermute_b32 v97, v113, v96
	global_store_dwordx4 v[162:163], v[98:101], off offset:256
	s_and_saveexec_b64 s[22:23], s[4:5]
	s_cbranch_execz .LBB0_890
	s_waitcnt lgkmcnt(0)
	v_add_f32_e32 v96, v96, v97
	v_mul_f32_e32 v96, 0x4b800000, v96
	v_trunc_f32_e32 v96, v96
	v_mul_f32_e32 v97, 0x2f800000, v96
	v_floor_f32_e32 v97, v97
	v_fmac_f32_e32 v96, 0xcf800000, v97
	v_cvt_u32_f32_e32 v96, v96
	v_cvt_u32_f32_e32 v97, v97
	v_lshl_add_u64 v[98:99], v[160:161], 3, s[12:13]
	global_atomic_add_x2 v[98:99], v[96:97], off
.LBB0_890:
	s_or_b64 exec, exec, s[22:23]
	s_waitcnt lgkmcnt(0)
	global_load_dwordx4 v[96:99], v[110:111], off offset:256
	s_waitcnt vmcnt(2)
	v_lshlrev_b32_e32 v100, 16, v104
	v_and_b32_e32 v101, 0xffff0000, v104
	v_lshlrev_b32_e32 v102, 16, v105
	v_and_b32_e32 v103, 0xffff0000, v105
	v_lshlrev_b32_e32 v104, 16, v106
	v_and_b32_e32 v105, 0xffff0000, v106
	v_lshlrev_b32_e32 v106, 16, v107
	v_and_b32_e32 v107, 0xffff0000, v107
	v_pk_add_f32 v[94:95], v[94:95], 0 op_sel_hi:[1,0]
	v_pk_add_f32 v[114:115], v[92:93], 0 op_sel_hi:[1,0]
	v_pk_add_f32 v[90:91], v[90:91], 0 op_sel_hi:[1,0]
	v_pk_add_f32 v[88:89], v[88:89], 0 op_sel_hi:[1,0]
	v_or_b32_e32 v92, 48, v158
	v_pk_add_f32 v[102:103], v[94:95], v[102:103]
	v_pk_add_f32 v[100:101], v[114:115], v[100:101]
	v_pk_add_f32 v[106:107], v[90:91], v[106:107]
	v_pk_add_f32 v[104:105], v[88:89], v[104:105]
	v_ashrrev_i32_e32 v93, 31, v92
	v_cvt_pk_bf16_f32 v88, v100, v101
	v_cvt_pk_bf16_f32 v89, v102, v103
	v_cvt_pk_bf16_f32 v90, v104, v105
	v_cvt_pk_bf16_f32 v91, v106, v107
	v_lshlrev_b64 v[94:95], 11, v[92:93]
	global_store_dwordx4 v[110:111], v[88:91], off
	v_mul_f32_e32 v101, v101, v101
	v_mul_f32_e32 v103, v103, v103
	v_lshl_add_u64 v[88:89], s[78:79], 0, v[94:95]
	v_lshl_add_u64 v[94:95], v[156:157], 1, v[88:89]
	global_load_dwordx4 v[88:91], v[94:95], off
	v_mul_f32_e32 v105, v105, v105
	v_fmac_f32_e32 v101, v100, v100
	v_fmac_f32_e32 v103, v102, v102
	v_mul_f32_e32 v107, v107, v107
	v_fmac_f32_e32 v105, v104, v104
	v_add_f32_e32 v100, v101, v103
	v_fmac_f32_e32 v107, v106, v106
	v_add_f32_e32 v100, v105, v100
	v_pk_add_f32 v[86:87], v[86:87], 0 op_sel_hi:[1,0]
	v_pk_add_f32 v[84:85], v[84:85], 0 op_sel_hi:[1,0]
	v_add_f32_e32 v104, v107, v100
	v_pk_add_f32 v[82:83], v[82:83], 0 op_sel_hi:[1,0]
	v_pk_add_f32 v[80:81], v[80:81], 0 op_sel_hi:[1,0]
	s_waitcnt vmcnt(2)
	v_lshlrev_b32_e32 v100, 16, v96
	v_and_b32_e32 v101, 0xffff0000, v96
	v_lshlrev_b32_e32 v96, 16, v97
	v_and_b32_e32 v97, 0xffff0000, v97
	v_lshlrev_b32_e32 v102, 16, v98
	v_and_b32_e32 v103, 0xffff0000, v98
	v_lshlrev_b32_e32 v98, 16, v99
	v_and_b32_e32 v99, 0xffff0000, v99
	v_pk_add_f32 v[86:87], v[86:87], v[96:97]
	v_pk_add_f32 v[84:85], v[84:85], v[100:101]
	v_pk_add_f32 v[96:97], v[82:83], v[98:99]
	v_pk_add_f32 v[98:99], v[80:81], v[102:103]
	v_mul_f32_e32 v81, v85, v85
	v_mul_f32_e32 v82, v87, v87
	v_mul_f32_e32 v83, v99, v99
	v_fmac_f32_e32 v81, v84, v84
	v_fmac_f32_e32 v82, v86, v86
	v_mul_f32_e32 v80, v97, v97
	v_add_f32_e32 v81, v81, v82
	v_fmac_f32_e32 v83, v98, v98
	v_fmac_f32_e32 v80, v96, v96
	v_add_f32_e32 v81, v83, v81
	v_add_f32_e32 v80, v80, v81
	v_add_f32_e32 v80, v104, v80
	ds_bpermute_b32 v81, v112, v80
	v_cvt_pk_bf16_f32 v82, v84, v85
	v_cvt_pk_bf16_f32 v83, v86, v87
	v_cvt_pk_bf16_f32 v84, v98, v99
	v_cvt_pk_bf16_f32 v85, v96, v97
	s_waitcnt lgkmcnt(0)
	v_add_f32_e32 v80, v80, v81
	ds_bpermute_b32 v81, v113, v80
	global_store_dwordx4 v[110:111], v[82:85], off offset:256
	s_and_saveexec_b64 s[22:23], s[4:5]
	s_cbranch_execz .LBB0_892
	s_waitcnt lgkmcnt(0)
	v_add_f32_e32 v80, v80, v81
	v_mul_f32_e32 v80, 0x4b800000, v80
	v_trunc_f32_e32 v80, v80
	v_mul_f32_e32 v81, 0x2f800000, v80
	v_floor_f32_e32 v81, v81
	v_fmac_f32_e32 v80, 0xcf800000, v81
	v_cvt_u32_f32_e32 v80, v80
	v_cvt_u32_f32_e32 v81, v81
	v_lshl_add_u64 v[82:83], v[108:109], 3, s[12:13]
	global_atomic_add_x2 v[82:83], v[80:81], off
;     __device__ __forceinline__ void operator()(const pg8::f32x4 (&acc)[2][2][4][2], const pg8::Unit& u, int wr, int wc, int fr, int fq) const {
;     ...
;         if (mode >= 5) {
;             const bool hasF = mode == 5, outF = mode == 7;
;             u32x4 cb2 = {0u, 0u, 0u, 0u}, nb2 = cb2, cbb, nbb; float csc, nsc = 1.f, ss = 0.f;
;             {
;                 if (hasF) cb2 = *(const u32x4*)(base2 + (size_t)row0 * 1024 + col0);
;                 cbb = *(const u32x4*)(baseb + (size_t)row0 * 1024 + col0);
;                 csc = rowscale(row0);
;             }
;             nbb = cbb;
; #pragma unroll
;             for (int p = 0; p < 16; ++p) {
;                 const int g = p >> 1, bj = p & 1, ai = g >> 2, m = g & 3, r = row0 + ai * 128 + m * 16, c = col0 + bj * 128;
;                 if (p < 15) {
;                     const int gn = (p + 1) >> 1, rn = row0 + (gn >> 2) * 128 + (gn & 3) * 16, cn = col0 + ((p + 1) & 1) * 128;
;                     if (hasF) nb2 = *(const u32x4*)(base2 + (size_t)rn * 1024 + cn);
;                     nbb = *(const u32x4*)(baseb + (size_t)rn * 1024 + cn);
;                     if (bj == 1) nsc = rowscale(rn);
;                 }
;                 const f32x4 r0 = {bflo(cbb.x), bfhi(cbb.x), bflo(cbb.y), bfhi(cbb.y)}, r1 = {bflo(cbb.z), bfhi(cbb.z), bflo(cbb.w), bfhi(cbb.w)};
;                 const f32x4 q0 = {bflo(cb2.x), bfhi(cb2.x), bflo(cb2.y), bfhi(cb2.y)}, q1 = {bflo(cb2.z), bfhi(cb2.z), bflo(cb2.w), bfhi(cb2.w)};
;                 const f32x4 v0 = acc[ai][bj][m][0] * csc + q0 + r0, v1 = acc[ai][bj][m][1] * csc + q1 + r1;
;                 if (outF) {
;                     float* op = out + (size_t)r * 1024 + c;
;                     *(f32x4*)op = v0; *(f32x4*)(op + 4) = v1;
;                 } else {
;                     u32x4 w; w.x = pk2(v0[0], v0[1]); w.y = pk2(v0[2], v0[3]); w.z = pk2(v1[0], v1[1]); w.w = pk2(v1[2], v1[3]);
;                     *(u32x4*)(O + (size_t)r * 1024 + c) = w;
;                     ss += (v0[0] * v0[0] + v0[1] * v0[1]) + (v0[2] * v0[2] + v0[3] * v0[3]) + (v1[0] * v1[0] + v1[1] * v1[1]) + (v1[2] * v1[2] + v1[3] * v1[3]);
;                     if (bj == 1) {
;                         ss += __shfl_xor(ss, 16); ss += __shfl_xor(ss, 32);
;                         if (fq == 0) atomicAdd(rss + r, (u64)(ss * RSS_FIX));
;                         ss = 0.f;
;                     }
.LBB0_892:
	s_or_b64 exec, exec, s[22:23]
	s_waitcnt lgkmcnt(0)
	global_load_dwordx4 v[80:83], v[94:95], off offset:256
	s_waitcnt vmcnt(2)
	v_lshlrev_b32_e32 v84, 16, v88
	v_and_b32_e32 v85, 0xffff0000, v88
	v_lshlrev_b32_e32 v86, 16, v89
	v_and_b32_e32 v87, 0xffff0000, v89
	v_lshlrev_b32_e32 v88, 16, v90
	v_and_b32_e32 v89, 0xffff0000, v90
	v_lshlrev_b32_e32 v90, 16, v91
	v_and_b32_e32 v91, 0xffff0000, v91
	v_pk_add_f32 v[78:79], v[78:79], 0 op_sel_hi:[1,0]
	v_pk_add_f32 v[96:97], v[76:77], 0 op_sel_hi:[1,0]
	v_pk_add_f32 v[74:75], v[74:75], 0 op_sel_hi:[1,0]
	v_pk_add_f32 v[72:73], v[72:73], 0 op_sel_hi:[1,0]
	v_add_u32_e32 v76, 0x80, v158
	v_pk_add_f32 v[86:87], v[78:79], v[86:87]
	v_pk_add_f32 v[84:85], v[96:97], v[84:85]
	v_pk_add_f32 v[90:91], v[74:75], v[90:91]
	v_pk_add_f32 v[88:89], v[72:73], v[88:89]
	v_ashrrev_i32_e32 v77, 31, v76
	v_cvt_pk_bf16_f32 v72, v84, v85
	v_cvt_pk_bf16_f32 v73, v86, v87
	v_cvt_pk_bf16_f32 v74, v88, v89
	v_cvt_pk_bf16_f32 v75, v90, v91
	v_lshlrev_b64 v[78:79], 11, v[76:77]
	global_store_dwordx4 v[94:95], v[72:75], off
	v_mul_f32_e32 v85, v85, v85
	v_mul_f32_e32 v87, v87, v87
	v_lshl_add_u64 v[72:73], s[78:79], 0, v[78:79]
	v_lshl_add_u64 v[78:79], v[156:157], 1, v[72:73]
	global_load_dwordx4 v[72:75], v[78:79], off
	v_mul_f32_e32 v89, v89, v89
	v_fmac_f32_e32 v85, v84, v84
	v_fmac_f32_e32 v87, v86, v86
	v_mul_f32_e32 v91, v91, v91
	v_fmac_f32_e32 v89, v88, v88
	v_add_f32_e32 v84, v85, v87
	v_fmac_f32_e32 v91, v90, v90
	v_add_f32_e32 v84, v89, v84
	v_pk_add_f32 v[70:71], v[70:71], 0 op_sel_hi:[1,0]
	v_pk_add_f32 v[68:69], v[68:69], 0 op_sel_hi:[1,0]
	v_add_f32_e32 v88, v91, v84
	v_pk_add_f32 v[66:67], v[66:67], 0 op_sel_hi:[1,0]
	v_pk_add_f32 v[64:65], v[64:65], 0 op_sel_hi:[1,0]
	s_waitcnt vmcnt(2)
	v_lshlrev_b32_e32 v84, 16, v80
	v_and_b32_e32 v85, 0xffff0000, v80
	v_lshlrev_b32_e32 v80, 16, v81
	v_and_b32_e32 v81, 0xffff0000, v81
	v_lshlrev_b32_e32 v86, 16, v82
	v_and_b32_e32 v87, 0xffff0000, v82
	v_lshlrev_b32_e32 v82, 16, v83
	v_and_b32_e32 v83, 0xffff0000, v83
	v_pk_add_f32 v[70:71], v[70:71], v[80:81]
	v_pk_add_f32 v[68:69], v[68:69], v[84:85]
	v_pk_add_f32 v[80:81], v[66:67], v[82:83]
	v_pk_add_f32 v[82:83], v[64:65], v[86:87]
	v_mul_f32_e32 v65, v69, v69
	v_mul_f32_e32 v66, v71, v71
	v_mul_f32_e32 v67, v83, v83
	v_fmac_f32_e32 v65, v68, v68
	v_fmac_f32_e32 v66, v70, v70
	v_mul_f32_e32 v64, v81, v81
	v_add_f32_e32 v65, v65, v66
	v_fmac_f32_e32 v67, v82, v82
	v_fmac_f32_e32 v64, v80, v80
	v_add_f32_e32 v65, v67, v65
	v_add_f32_e32 v64, v64, v65
	v_add_f32_e32 v64, v88, v64
	ds_bpermute_b32 v65, v112, v64
	v_cvt_pk_bf16_f32 v66, v68, v69
	v_cvt_pk_bf16_f32 v67, v70, v71
	v_cvt_pk_bf16_f32 v68, v82, v83
	v_cvt_pk_bf16_f32 v69, v80, v81
	s_waitcnt lgkmcnt(0)
	v_add_f32_e32 v64, v64, v65
	ds_bpermute_b32 v65, v113, v64
	global_store_dwordx4 v[94:95], v[66:69], off offset:256
	s_and_saveexec_b64 s[22:23], s[4:5]
	s_cbranch_execz .LBB0_894
	s_waitcnt lgkmcnt(0)
	v_add_f32_e32 v64, v64, v65
	v_mul_f32_e32 v64, 0x4b800000, v64
	v_trunc_f32_e32 v64, v64
	v_mul_f32_e32 v65, 0x2f800000, v64
	v_floor_f32_e32 v65, v65
	v_fmac_f32_e32 v64, 0xcf800000, v65
	v_cvt_u32_f32_e32 v64, v64
	v_cvt_u32_f32_e32 v65, v65
	v_lshl_add_u64 v[66:67], v[92:93], 3, s[12:13]
	global_atomic_add_x2 v[66:67], v[64:65], off
.LBB0_894:
	s_or_b64 exec, exec, s[22:23]
	s_waitcnt lgkmcnt(0)
	global_load_dwordx4 v[64:67], v[78:79], off offset:256
	s_waitcnt vmcnt(2)
	v_lshlrev_b32_e32 v68, 16, v72
	v_and_b32_e32 v69, 0xffff0000, v72
	v_lshlrev_b32_e32 v70, 16, v73
	v_and_b32_e32 v71, 0xffff0000, v73
	v_lshlrev_b32_e32 v72, 16, v74
	v_and_b32_e32 v73, 0xffff0000, v74
	v_lshlrev_b32_e32 v74, 16, v75
	v_and_b32_e32 v75, 0xffff0000, v75
	v_pk_add_f32 v[62:63], v[62:63], 0 op_sel_hi:[1,0]
	v_pk_add_f32 v[80:81], v[60:61], 0 op_sel_hi:[1,0]
	v_pk_add_f32 v[58:59], v[58:59], 0 op_sel_hi:[1,0]
	v_pk_add_f32 v[56:57], v[56:57], 0 op_sel_hi:[1,0]
	v_or_b32_e32 v60, 16, v76
	v_pk_add_f32 v[70:71], v[62:63], v[70:71]
	v_pk_add_f32 v[68:69], v[80:81], v[68:69]
	v_pk_add_f32 v[74:75], v[58:59], v[74:75]
	v_pk_add_f32 v[72:73], v[56:57], v[72:73]
	v_ashrrev_i32_e32 v61, 31, v60
	v_cvt_pk_bf16_f32 v56, v68, v69
	v_cvt_pk_bf16_f32 v57, v70, v71
	v_cvt_pk_bf16_f32 v58, v72, v73
	v_cvt_pk_bf16_f32 v59, v74, v75
	v_lshlrev_b64 v[62:63], 11, v[60:61]
	global_store_dwordx4 v[78:79], v[56:59], off
	v_mul_f32_e32 v69, v69, v69
	v_mul_f32_e32 v71, v71, v71
	v_lshl_add_u64 v[56:57], s[78:79], 0, v[62:63]
	v_lshl_add_u64 v[62:63], v[156:157], 1, v[56:57]
	global_load_dwordx4 v[56:59], v[62:63], off
	v_mul_f32_e32 v73, v73, v73
	v_fmac_f32_e32 v69, v68, v68
	v_fmac_f32_e32 v71, v70, v70
	v_mul_f32_e32 v75, v75, v75
	v_fmac_f32_e32 v73, v72, v72
	v_add_f32_e32 v68, v69, v71
	v_fmac_f32_e32 v75, v74, v74
	v_add_f32_e32 v68, v73, v68
	v_pk_add_f32 v[54:55], v[54:55], 0 op_sel_hi:[1,0]
	v_pk_add_f32 v[52:53], v[52:53], 0 op_sel_hi:[1,0]
	v_add_f32_e32 v72, v75, v68
	v_pk_add_f32 v[50:51], v[50:51], 0 op_sel_hi:[1,0]
	v_pk_add_f32 v[48:49], v[48:49], 0 op_sel_hi:[1,0]
	s_waitcnt vmcnt(2)
	v_lshlrev_b32_e32 v68, 16, v64
	v_and_b32_e32 v69, 0xffff0000, v64
	v_lshlrev_b32_e32 v64, 16, v65
	v_and_b32_e32 v65, 0xffff0000, v65
	v_lshlrev_b32_e32 v70, 16, v66
	v_and_b32_e32 v71, 0xffff0000, v66
	v_lshlrev_b32_e32 v66, 16, v67
	v_and_b32_e32 v67, 0xffff0000, v67
	v_pk_add_f32 v[54:55], v[54:55], v[64:65]
	v_pk_add_f32 v[52:53], v[52:53], v[68:69]
	v_pk_add_f32 v[64:65], v[50:51], v[66:67]
	v_pk_add_f32 v[66:67], v[48:49], v[70:71]
	v_mul_f32_e32 v49, v53, v53
	v_mul_f32_e32 v50, v55, v55
	v_mul_f32_e32 v51, v67, v67
	v_fmac_f32_e32 v49, v52, v52
	v_fmac_f32_e32 v50, v54, v54
	v_mul_f32_e32 v48, v65, v65
	v_add_f32_e32 v49, v49, v50
	v_fmac_f32_e32 v51, v66, v66
	v_fmac_f32_e32 v48, v64, v64
	v_add_f32_e32 v49, v51, v49
	v_add_f32_e32 v48, v48, v49
	v_add_f32_e32 v48, v72, v48
	ds_bpermute_b32 v49, v112, v48
	v_cvt_pk_bf16_f32 v50, v52, v53
	v_cvt_pk_bf16_f32 v51, v54, v55
	v_cvt_pk_bf16_f32 v52, v66, v67
	v_cvt_pk_bf16_f32 v53, v64, v65
	s_waitcnt lgkmcnt(0)
	v_add_f32_e32 v48, v48, v49
	ds_bpermute_b32 v49, v113, v48
	global_store_dwordx4 v[78:79], v[50:53], off offset:256
	s_and_saveexec_b64 s[22:23], s[4:5]
	s_cbranch_execz .LBB0_896
	s_waitcnt lgkmcnt(0)
	v_add_f32_e32 v48, v48, v49
	v_mul_f32_e32 v48, 0x4b800000, v48
	v_trunc_f32_e32 v48, v48
	v_mul_f32_e32 v49, 0x2f800000, v48
	v_floor_f32_e32 v49, v49
	v_fmac_f32_e32 v48, 0xcf800000, v49
	v_cvt_u32_f32_e32 v48, v48
	v_cvt_u32_f32_e32 v49, v49
	v_lshl_add_u64 v[50:51], v[76:77], 3, s[12:13]
	global_atomic_add_x2 v[50:51], v[48:49], off
;     __device__ __forceinline__ void operator()(const pg8::f32x4 (&acc)[2][2][4][2], const pg8::Unit& u, int wr, int wc, int fr, int fq) const {
;     ...
;         if (mode >= 5) {
;             const bool hasF = mode == 5, outF = mode == 7;
;             u32x4 cb2 = {0u, 0u, 0u, 0u}, nb2 = cb2, cbb, nbb; float csc, nsc = 1.f, ss = 0.f;
;             {
;                 if (hasF) cb2 = *(const u32x4*)(base2 + (size_t)row0 * 1024 + col0);
;                 cbb = *(const u32x4*)(baseb + (size_t)row0 * 1024 + col0);
;                 csc = rowscale(row0);
;             }
;             nbb = cbb;
; #pragma unroll
;             for (int p = 0; p < 16; ++p) {
;                 const int g = p >> 1, bj = p & 1, ai = g >> 2, m = g & 3, r = row0 + ai * 128 + m * 16, c = col0 + bj * 128;
;                 if (p < 15) {
;                     const int gn = (p + 1) >> 1, rn = row0 + (gn >> 2) * 128 + (gn & 3) * 16, cn = col0 + ((p + 1) & 1) * 128;
;                     if (hasF) nb2 = *(const u32x4*)(base2 + (size_t)rn * 1024 + cn);
;                     nbb = *(const u32x4*)(baseb + (size_t)rn * 1024 + cn);
;                     if (bj == 1) nsc = rowscale(rn);
;                 }
;                 const f32x4 r0 = {bflo(cbb.x), bfhi(cbb.x), bflo(cbb.y), bfhi(cbb.y)}, r1 = {bflo(cbb.z), bfhi(cbb.z), bflo(cbb.w), bfhi(cbb.w)};
;                 const f32x4 q0 = {bflo(cb2.x), bfhi(cb2.x), bflo(cb2.y), bfhi(cb2.y)}, q1 = {bflo(cb2.z), bfhi(cb2.z), bflo(cb2.w), bfhi(cb2.w)};
;                 const f32x4 v0 = acc[ai][bj][m][0] * csc + q0 + r0, v1 = acc[ai][bj][m][1] * csc + q1 + r1;
;                 if (outF) {
;                     float* op = out + (size_t)r * 1024 + c;
;                     *(f32x4*)op = v0; *(f32x4*)(op + 4) = v1;
;                 } else {
;                     u32x4 w; w.x = pk2(v0[0], v0[1]); w.y = pk2(v0[2], v0[3]); w.z = pk2(v1[0], v1[1]); w.w = pk2(v1[2], v1[3]);
;                     *(u32x4*)(O + (size_t)r * 1024 + c) = w;
;                     ss += (v0[0] * v0[0] + v0[1] * v0[1]) + (v0[2] * v0[2] + v0[3] * v0[3]) + (v1[0] * v1[0] + v1[1] * v1[1]) + (v1[2] * v1[2] + v1[3] * v1[3]);
;                     if (bj == 1) {
;                         ss += __shfl_xor(ss, 16); ss += __shfl_xor(ss, 32);
;                         if (fq == 0) atomicAdd(rss + r, (u64)(ss * RSS_FIX));
;                         ss = 0.f;
;                     }
.LBB0_896:
	s_or_b64 exec, exec, s[22:23]
	s_waitcnt lgkmcnt(0)
	global_load_dwordx4 v[48:51], v[62:63], off offset:256
	s_waitcnt vmcnt(2)
	v_lshlrev_b32_e32 v52, 16, v56
	v_and_b32_e32 v53, 0xffff0000, v56
	v_lshlrev_b32_e32 v54, 16, v57
	v_and_b32_e32 v55, 0xffff0000, v57
	v_lshlrev_b32_e32 v56, 16, v58
	v_and_b32_e32 v57, 0xffff0000, v58
	v_lshlrev_b32_e32 v58, 16, v59
	v_and_b32_e32 v59, 0xffff0000, v59
	v_pk_add_f32 v[46:47], v[46:47], 0 op_sel_hi:[1,0]
	v_pk_add_f32 v[64:65], v[44:45], 0 op_sel_hi:[1,0]
	v_pk_add_f32 v[42:43], v[42:43], 0 op_sel_hi:[1,0]
	v_pk_add_f32 v[40:41], v[40:41], 0 op_sel_hi:[1,0]
	v_or_b32_e32 v44, 32, v76
	v_pk_add_f32 v[54:55], v[46:47], v[54:55]
	v_pk_add_f32 v[52:53], v[64:65], v[52:53]
	v_pk_add_f32 v[58:59], v[42:43], v[58:59]
	v_pk_add_f32 v[56:57], v[40:41], v[56:57]
	v_ashrrev_i32_e32 v45, 31, v44
	v_cvt_pk_bf16_f32 v40, v52, v53
	v_cvt_pk_bf16_f32 v41, v54, v55
	v_cvt_pk_bf16_f32 v42, v56, v57
	v_cvt_pk_bf16_f32 v43, v58, v59
	v_lshlrev_b64 v[46:47], 11, v[44:45]
	global_store_dwordx4 v[62:63], v[40:43], off
	v_mul_f32_e32 v53, v53, v53
	v_mul_f32_e32 v55, v55, v55
	v_lshl_add_u64 v[40:41], s[78:79], 0, v[46:47]
	v_lshl_add_u64 v[46:47], v[156:157], 1, v[40:41]
	global_load_dwordx4 v[40:43], v[46:47], off
	v_mul_f32_e32 v57, v57, v57
	v_fmac_f32_e32 v53, v52, v52
	v_fmac_f32_e32 v55, v54, v54
	v_mul_f32_e32 v59, v59, v59
	v_fmac_f32_e32 v57, v56, v56
	v_add_f32_e32 v52, v53, v55
	v_fmac_f32_e32 v59, v58, v58
	v_add_f32_e32 v52, v57, v52
	v_pk_add_f32 v[38:39], v[38:39], 0 op_sel_hi:[1,0]
	v_pk_add_f32 v[36:37], v[36:37], 0 op_sel_hi:[1,0]
	v_add_f32_e32 v56, v59, v52
	v_pk_add_f32 v[34:35], v[34:35], 0 op_sel_hi:[1,0]
	v_pk_add_f32 v[32:33], v[32:33], 0 op_sel_hi:[1,0]
	s_waitcnt vmcnt(2)
	v_lshlrev_b32_e32 v52, 16, v48
	v_and_b32_e32 v53, 0xffff0000, v48
	v_lshlrev_b32_e32 v48, 16, v49
	v_and_b32_e32 v49, 0xffff0000, v49
	v_lshlrev_b32_e32 v54, 16, v50
	v_and_b32_e32 v55, 0xffff0000, v50
	v_lshlrev_b32_e32 v50, 16, v51
	v_and_b32_e32 v51, 0xffff0000, v51
	v_pk_add_f32 v[38:39], v[38:39], v[48:49]
	v_pk_add_f32 v[36:37], v[36:37], v[52:53]
	v_pk_add_f32 v[48:49], v[34:35], v[50:51]
	v_pk_add_f32 v[50:51], v[32:33], v[54:55]
	v_mul_f32_e32 v33, v37, v37
	v_mul_f32_e32 v34, v39, v39
	v_mul_f32_e32 v35, v51, v51
	v_fmac_f32_e32 v33, v36, v36
	v_fmac_f32_e32 v34, v38, v38
	v_mul_f32_e32 v32, v49, v49
	v_add_f32_e32 v33, v33, v34
	v_fmac_f32_e32 v35, v50, v50
	v_fmac_f32_e32 v32, v48, v48
	v_add_f32_e32 v33, v35, v33
	v_add_f32_e32 v32, v32, v33
	v_add_f32_e32 v32, v56, v32
	ds_bpermute_b32 v33, v112, v32
	v_cvt_pk_bf16_f32 v34, v36, v37
	v_cvt_pk_bf16_f32 v35, v38, v39
	v_cvt_pk_bf16_f32 v36, v50, v51
	v_cvt_pk_bf16_f32 v37, v48, v49
	s_waitcnt lgkmcnt(0)
	v_add_f32_e32 v32, v32, v33
	ds_bpermute_b32 v33, v113, v32
	global_store_dwordx4 v[62:63], v[34:37], off offset:256
	s_and_saveexec_b64 s[22:23], s[4:5]
	s_cbranch_execz .LBB0_898
	s_waitcnt lgkmcnt(0)
	v_add_f32_e32 v32, v32, v33
	v_mul_f32_e32 v32, 0x4b800000, v32
	v_trunc_f32_e32 v32, v32
	v_mul_f32_e32 v33, 0x2f800000, v32
	v_floor_f32_e32 v33, v33
	v_fmac_f32_e32 v32, 0xcf800000, v33
	v_cvt_u32_f32_e32 v32, v32
	v_cvt_u32_f32_e32 v33, v33
	v_lshl_add_u64 v[34:35], v[60:61], 3, s[12:13]
	global_atomic_add_x2 v[34:35], v[32:33], off
;     __device__ __forceinline__ void operator()(const pg8::f32x4 (&acc)[2][2][4][2], const pg8::Unit& u, int wr, int wc, int fr, int fq) const {
;     ...
;         if (mode >= 5) {
;             const bool hasF = mode == 5, outF = mode == 7;
;             u32x4 cb2 = {0u, 0u, 0u, 0u}, nb2 = cb2, cbb, nbb; float csc, nsc = 1.f, ss = 0.f;
;             {
;                 if (hasF) cb2 = *(const u32x4*)(base2 + (size_t)row0 * 1024 + col0);
;                 cbb = *(const u32x4*)(baseb + (size_t)row0 * 1024 + col0);
;                 csc = rowscale(row0);
;             }
;             nbb = cbb;
; #pragma unroll
;             for (int p = 0; p < 16; ++p) {
;                 const int g = p >> 1, bj = p & 1, ai = g >> 2, m = g & 3, r = row0 + ai * 128 + m * 16, c = col0 + bj * 128;
;                 if (p < 15) {
;                     const int gn = (p + 1) >> 1, rn = row0 + (gn >> 2) * 128 + (gn & 3) * 16, cn = col0 + ((p + 1) & 1) * 128;
;                     if (hasF) nb2 = *(const u32x4*)(base2 + (size_t)rn * 1024 + cn);
;                     nbb = *(const u32x4*)(baseb + (size_t)rn * 1024 + cn);
;                     if (bj == 1) nsc = rowscale(rn);
;                 }
;                 const f32x4 r0 = {bflo(cbb.x), bfhi(cbb.x), bflo(cbb.y), bfhi(cbb.y)}, r1 = {bflo(cbb.z), bfhi(cbb.z), bflo(cbb.w), bfhi(cbb.w)};
;                 const f32x4 q0 = {bflo(cb2.x), bfhi(cb2.x), bflo(cb2.y), bfhi(cb2.y)}, q1 = {bflo(cb2.z), bfhi(cb2.z), bflo(cb2.w), bfhi(cb2.w)};
;                 const f32x4 v0 = acc[ai][bj][m][0] * csc + q0 + r0, v1 = acc[ai][bj][m][1] * csc + q1 + r1;
;                 if (outF) {
;                     float* op = out + (size_t)r * 1024 + c;
;                     *(f32x4*)op = v0; *(f32x4*)(op + 4) = v1;
;                 } else {
;                     u32x4 w; w.x = pk2(v0[0], v0[1]); w.y = pk2(v0[2], v0[3]); w.z = pk2(v1[0], v1[1]); w.w = pk2(v1[2], v1[3]);
;                     *(u32x4*)(O + (size_t)r * 1024 + c) = w;
;                     ss += (v0[0] * v0[0] + v0[1] * v0[1]) + (v0[2] * v0[2] + v0[3] * v0[3]) + (v1[0] * v1[0] + v1[1] * v1[1]) + (v1[2] * v1[2] + v1[3] * v1[3]);
;                     if (bj == 1) {
;                         ss += __shfl_xor(ss, 16); ss += __shfl_xor(ss, 32);
;                         if (fq == 0) atomicAdd(rss + r, (u64)(ss * RSS_FIX));
;                         ss = 0.f;
;                     }
.LBB0_898:
	s_or_b64 exec, exec, s[22:23]
	s_waitcnt lgkmcnt(0)
	global_load_dwordx4 v[32:35], v[46:47], off offset:256
	s_waitcnt vmcnt(2)
	v_lshlrev_b32_e32 v36, 16, v40
	v_and_b32_e32 v37, 0xffff0000, v40
	v_lshlrev_b32_e32 v38, 16, v41
	v_and_b32_e32 v39, 0xffff0000, v41
	v_lshlrev_b32_e32 v40, 16, v42
	v_and_b32_e32 v41, 0xffff0000, v42
	v_lshlrev_b32_e32 v42, 16, v43
	v_and_b32_e32 v43, 0xffff0000, v43
	v_pk_add_f32 v[30:31], v[30:31], 0 op_sel_hi:[1,0]
	v_pk_add_f32 v[48:49], v[28:29], 0 op_sel_hi:[1,0]
	v_pk_add_f32 v[26:27], v[26:27], 0 op_sel_hi:[1,0]
	v_pk_add_f32 v[24:25], v[24:25], 0 op_sel_hi:[1,0]
	v_or_b32_e32 v28, 48, v76
	v_pk_add_f32 v[38:39], v[30:31], v[38:39]
	v_pk_add_f32 v[36:37], v[48:49], v[36:37]
	v_pk_add_f32 v[42:43], v[26:27], v[42:43]
	v_pk_add_f32 v[40:41], v[24:25], v[40:41]
	v_ashrrev_i32_e32 v29, 31, v28
	v_cvt_pk_bf16_f32 v24, v36, v37
	v_cvt_pk_bf16_f32 v25, v38, v39
	v_cvt_pk_bf16_f32 v26, v40, v41
	v_cvt_pk_bf16_f32 v27, v42, v43
	v_lshlrev_b64 v[30:31], 11, v[28:29]
	global_store_dwordx4 v[46:47], v[24:27], off
	v_mul_f32_e32 v37, v37, v37
	v_mul_f32_e32 v39, v39, v39
	v_lshl_add_u64 v[24:25], s[78:79], 0, v[30:31]
	v_lshl_add_u64 v[30:31], v[156:157], 1, v[24:25]
	global_load_dwordx4 v[24:27], v[30:31], off
	v_mul_f32_e32 v41, v41, v41
	v_fmac_f32_e32 v37, v36, v36
	v_fmac_f32_e32 v39, v38, v38
	v_mul_f32_e32 v43, v43, v43
	v_fmac_f32_e32 v41, v40, v40
	v_add_f32_e32 v36, v37, v39
	v_fmac_f32_e32 v43, v42, v42
	v_add_f32_e32 v36, v41, v36
	v_pk_add_f32 v[22:23], v[22:23], 0 op_sel_hi:[1,0]
	v_pk_add_f32 v[20:21], v[20:21], 0 op_sel_hi:[1,0]
	v_add_f32_e32 v40, v43, v36
	v_pk_add_f32 v[18:19], v[18:19], 0 op_sel_hi:[1,0]
	v_pk_add_f32 v[16:17], v[16:17], 0 op_sel_hi:[1,0]
	s_waitcnt vmcnt(2)
	v_lshlrev_b32_e32 v36, 16, v32
	v_and_b32_e32 v37, 0xffff0000, v32
	v_lshlrev_b32_e32 v32, 16, v33
	v_and_b32_e32 v33, 0xffff0000, v33
	v_lshlrev_b32_e32 v38, 16, v34
	v_and_b32_e32 v39, 0xffff0000, v34
	v_lshlrev_b32_e32 v34, 16, v35
	v_and_b32_e32 v35, 0xffff0000, v35
	v_pk_add_f32 v[22:23], v[22:23], v[32:33]
	v_pk_add_f32 v[20:21], v[20:21], v[36:37]
	v_pk_add_f32 v[32:33], v[18:19], v[34:35]
	v_pk_add_f32 v[34:35], v[16:17], v[38:39]
	v_mul_f32_e32 v17, v21, v21
	v_mul_f32_e32 v18, v23, v23
	v_mul_f32_e32 v19, v35, v35
	v_fmac_f32_e32 v17, v20, v20
	v_fmac_f32_e32 v18, v22, v22
	v_mul_f32_e32 v16, v33, v33
	v_add_f32_e32 v17, v17, v18
	v_fmac_f32_e32 v19, v34, v34
	v_fmac_f32_e32 v16, v32, v32
	v_add_f32_e32 v17, v19, v17
	v_add_f32_e32 v16, v16, v17
	v_add_f32_e32 v16, v40, v16
	ds_bpermute_b32 v17, v112, v16
	v_cvt_pk_bf16_f32 v18, v20, v21
	v_cvt_pk_bf16_f32 v19, v22, v23
	v_cvt_pk_bf16_f32 v20, v34, v35
	v_cvt_pk_bf16_f32 v21, v32, v33
	s_waitcnt lgkmcnt(0)
	v_add_f32_e32 v16, v16, v17
	ds_bpermute_b32 v17, v113, v16
	global_store_dwordx4 v[46:47], v[18:21], off offset:256
	s_and_saveexec_b64 s[22:23], s[4:5]
	s_cbranch_execz .LBB0_900
	s_waitcnt lgkmcnt(0)
	v_add_f32_e32 v16, v16, v17
	v_mul_f32_e32 v16, 0x4b800000, v16
	v_trunc_f32_e32 v16, v16
	v_mul_f32_e32 v17, 0x2f800000, v16
	v_floor_f32_e32 v17, v17
	v_fmac_f32_e32 v16, 0xcf800000, v17
	v_cvt_u32_f32_e32 v16, v16
	v_cvt_u32_f32_e32 v17, v17
	v_lshl_add_u64 v[18:19], v[44:45], 3, s[12:13]
	global_atomic_add_x2 v[18:19], v[16:17], off
.LBB0_900:
	s_or_b64 exec, exec, s[22:23]
	s_waitcnt lgkmcnt(0)
	global_load_dwordx4 v[16:19], v[30:31], off offset:256
	s_waitcnt vmcnt(2)
	v_lshlrev_b32_e32 v20, 16, v24
	v_and_b32_e32 v21, 0xffff0000, v24
	v_lshlrev_b32_e32 v22, 16, v25
	v_and_b32_e32 v23, 0xffff0000, v25
	v_pk_add_f32 v[14:15], v[14:15], 0 op_sel_hi:[1,0]
	v_pk_add_f32 v[12:13], v[12:13], 0 op_sel_hi:[1,0]
	v_lshlrev_b32_e32 v24, 16, v26
	v_and_b32_e32 v25, 0xffff0000, v26
	v_pk_add_f32 v[8:9], v[8:9], 0 op_sel_hi:[1,0]
	v_pk_add_f32 v[14:15], v[14:15], v[22:23]
	v_pk_add_f32 v[12:13], v[12:13], v[20:21]
	v_lshlrev_b32_e32 v26, 16, v27
	v_and_b32_e32 v27, 0xffff0000, v27
	v_pk_add_f32 v[10:11], v[10:11], 0 op_sel_hi:[1,0]
	v_pk_add_f32 v[32:33], v[0:1], 0 op_sel_hi:[1,0]
	v_pk_add_f32 v[8:9], v[8:9], v[24:25]
	v_cvt_pk_bf16_f32 v0, v12, v13
	v_cvt_pk_bf16_f32 v1, v14, v15
	v_mul_f32_e32 v13, v13, v13
	v_mul_f32_e32 v15, v15, v15
	v_pk_add_f32 v[10:11], v[10:11], v[26:27]
	v_mul_f32_e32 v20, v9, v9
	v_fmac_f32_e32 v13, v12, v12
	v_fmac_f32_e32 v15, v14, v14
	v_mul_f32_e32 v21, v11, v11
	v_fmac_f32_e32 v20, v8, v8
	v_add_f32_e32 v12, v13, v15
	v_fmac_f32_e32 v21, v10, v10
	v_add_f32_e32 v12, v20, v12
	v_pk_add_f32 v[6:7], v[6:7], 0 op_sel_hi:[1,0]
	v_pk_add_f32 v[4:5], v[4:5], 0 op_sel_hi:[1,0]
	v_add_f32_e32 v20, v21, v12
	v_pk_add_f32 v[2:3], v[2:3], 0 op_sel_hi:[1,0]
	s_waitcnt vmcnt(0)
	v_lshlrev_b32_e32 v12, 16, v16
	v_and_b32_e32 v13, 0xffff0000, v16
	v_lshlrev_b32_e32 v14, 16, v17
	v_and_b32_e32 v15, 0xffff0000, v17
	v_lshlrev_b32_e32 v16, 16, v18
	v_and_b32_e32 v17, 0xffff0000, v18
	v_lshlrev_b32_e32 v18, 16, v19
	v_and_b32_e32 v19, 0xffff0000, v19
	v_pk_add_f32 v[6:7], v[6:7], v[14:15]
	v_pk_add_f32 v[4:5], v[4:5], v[12:13]
	v_pk_add_f32 v[12:13], v[2:3], v[18:19]
	v_pk_add_f32 v[14:15], v[32:33], v[16:17]
	v_mul_f32_e32 v3, v5, v5
	v_mul_f32_e32 v16, v7, v7
	v_mul_f32_e32 v17, v15, v15
	v_fmac_f32_e32 v3, v4, v4
	v_fmac_f32_e32 v16, v6, v6
	v_mul_f32_e32 v2, v13, v13
	v_add_f32_e32 v3, v3, v16
	v_fmac_f32_e32 v17, v14, v14
	v_fmac_f32_e32 v2, v12, v12
	v_add_f32_e32 v3, v17, v3
	v_add_f32_e32 v2, v2, v3
	v_add_f32_e32 v16, v20, v2
	ds_bpermute_b32 v17, v112, v16
	v_cvt_pk_bf16_f32 v2, v8, v9
	v_cvt_pk_bf16_f32 v3, v10, v11
	global_store_dwordx4 v[30:31], v[0:3], off
	s_waitcnt lgkmcnt(0)
	s_nop 0
	v_add_f32_e32 v0, v16, v17
	ds_bpermute_b32 v1, v113, v0
	v_cvt_pk_bf16_f32 v2, v4, v5
	v_cvt_pk_bf16_f32 v3, v6, v7
	v_cvt_pk_bf16_f32 v4, v14, v15
	v_cvt_pk_bf16_f32 v5, v12, v13
	global_store_dwordx4 v[30:31], v[2:5], off offset:256
	s_and_saveexec_b64 s[22:23], s[4:5]
	s_cbranch_execz .LBB0_902
	s_waitcnt lgkmcnt(0)
	v_add_f32_e32 v0, v0, v1
	v_mul_f32_e32 v0, 0x4b800000, v0
	v_trunc_f32_e32 v0, v0
	v_mul_f32_e32 v1, 0x2f800000, v0
	v_floor_f32_e32 v1, v1
	v_fmac_f32_e32 v0, 0xcf800000, v1
	v_cvt_u32_f32_e32 v0, v0
	v_cvt_u32_f32_e32 v1, v1
	v_lshl_add_u64 v[2:3], v[28:29], 3, s[12:13]
	global_atomic_add_x2 v[2:3], v[0:1], off

; #define PG8_STAGE(bufoff, gbase, voff) do { _Pragma("unroll") for (int _i = 0; _i < 2; ++_i) \
;         __builtin_amdgcn_global_load_lds((const unsigned*)((const char*)(gbase) + (voff)[_i]), (PG8_LAS unsigned*)(lds + (bufoff) + ldsw + _i * 8192), 16, 0, 0); } while (0)
; #define PG8_WAIT_V(n) asm volatile("s_waitcnt vmcnt(" #n ")" ::: "memory")
; #define PG8_BAR __builtin_amdgcn_s_barrier()
;     __host__ __device__ bool next(int i, Unit& u) const {
;         const long L = (long)(i / khn) * G + c; if (L >= nwg) return false; u.kh = i % khn;
;         int wgid = (int)L; { const int q = nwg / NXCD, r = nwg % NXCD, xcd = wgid % NXCD, off = wgid / NXCD; wgid = (xcd < r ? xcd * (q + 1) : r * (q + 1) + (xcd - r) * q) + off; }
;         const int nig = WGM * nN, gid = wgid / nig, fm = gid * WGM, gsz = (nM - fm) < WGM ? (nM - fm) : WGM;
;         u.pm = fm + ((wgid % nig) % gsz); u.pn = (wgid % nig) / gsz; return true;
; template <class Epi, class Sched, bool ALIGN_EPI = false, bool SP2 = false>
; __device__ __forceinline__ void gemm_phase(PG8_LAS unsigned char* lds, const Gemm g, const Sched& S, const Epi& E) {
;     ...
;     const char* cA = (const char*)g.A + (size_t)cur.pm * tstep + (size_t)cur.kh * K * 2; const char* cB = (const char*)g.Bt + (size_t)cur.pn * tstep + (size_t)cur.kh * K * 2;
;     S.a_ready(cur);
;     if constexpr (SP2) {
;         PG8_STAGE(PG8_SB(0, 0), cB, voffB); PG8_STAGE(PG8_SB(0, 1), cB + hstep, voffB); PG8_STAGE(PG8_SA(0, 0), cA, voffA); PG8_STAGE(PG8_SA(0, 1), cA + hstep, voffA);
;         if (wr == 1) PG8_BAR;
;         PG8_WAIT_V(2); PG8_BAR;
;         PG8_STAGE(PG8_SB(1, 0), cB + kstep, voffB); PG8_STAGE(PG8_SA(1, 0), cA + kstep, voffA); PG8_STAGE(PG8_SB(1, 1), cB + hstep + kstep, voffB);
;         PG8_WAIT_V(6); PG8_BAR;
.LBB0_1026:
	s_or_b64 exec, exec, s[0:1]
	s_and_b64 vcc, exec, s[2:3]
	v_readfirstlane_b32 s1, v182
	s_waitcnt lgkmcnt(0)
	s_barrier
	s_cbranch_vccnz .LBB0_1042
	s_cmp_eq_u32 s42, 0x100
	s_cselect_b32 s49, 0x100, 0
	s_add_i32 s48, s33, s49
	s_add_u32 s24, s78, 0x19300000
	s_addc_u32 s25, s79, 0
	s_ashr_i32 s27, s33, 31
	s_lshr_b32 s0, s27, 29
	s_add_i32 s0, s48, s0
	s_ashr_i32 s2, s0, 3
	s_and_b32 s0, s0, -8
	s_sub_i32 s0, s48, s0
	s_lshr_b32 s3, s0, 31
	s_or_b32 s3, s3, 64
	s_mul_i32 s0, s3, s0
	s_add_i32 s0, s0, s2
	s_ashr_i32 s2, s0, 31
	s_lshr_b32 s2, s2, 27
	s_add_i32 s2, s0, s2
	s_ashr_i32 s3, s2, 5
	s_lshl_b32 s5, s3, 3
	s_sub_i32 s3, 0x80, s5
	s_min_u32 s7, s3, 8
	s_andn2_b32 s2, s2, 31
	s_sub_i32 s8, s0, s2
	v_cvt_f32_ubyte0_e32 v1, s7
	v_cvt_f32_i32_e32 v0, s8
	v_rcp_iflag_f32_e32 v2, v1
	s_lshr_b32 s4, s1, 6
	s_ashr_i32 s0, s8, 30
	s_lshr_b32 s6, s1, 8
	v_mul_f32_e32 v2, v0, v2
	v_trunc_f32_e32 v2, v2
	v_fma_f32 v0, -v2, v1, v0
	v_cvt_i32_f32_e32 v2, v2
	s_lshl_b32 s26, s4, 10
	s_or_b32 s0, s0, 1
	v_cmp_ge_f32_e64 s[2:3], |v0|, v1
	s_and_b64 s[2:3], s[2:3], exec
	s_cselect_b32 s0, s0, 0
	v_readfirstlane_b32 s2, v2
	s_add_i32 s0, s2, s0
	s_mul_i32 s2, s0, s7
	s_sub_i32 s2, s8, s2
	s_sext_i32_i8 s2, s2
	s_add_i32 s16, s5, s2
	s_ashr_i32 s17, s16, 31
	s_lshl_b64 s[2:3], s[16:17], 21
	s_add_u32 s18, s44, s2
	s_addc_u32 s19, s45, s3
	s_bfe_i64 s[2:3], s[0:1], 0x80000
	s_lshl_b64 s[2:3], s[2:3], 21
	s_add_u32 s20, s24, s2
	s_addc_u32 s21, s25, s3
	s_add_i32 s17, s26, 0
	v_lshl_or_b32 v132, v193, 13, v191
	s_add_i32 m0, s17, 0x10000
	v_lshl_or_b32 v128, v195, 13, v191
	global_load_lds_dwordx4 v132, s[20:21]
	s_add_i32 m0, s17, 0x12000
	s_add_u32 s2, s20, 0x100000
	global_load_lds_dwordx4 v128, s[20:21]
	s_addc_u32 s3, s21, 0
	s_add_i32 m0, s17, 0x14000
	s_add_i32 s28, s17, 0x2000
	global_load_lds_dwordx4 v132, s[2:3]
	s_add_i32 m0, s17, 0x16000
	v_lshl_or_b32 v134, v192, 13, v191
	global_load_lds_dwordx4 v128, s[2:3]
	s_mov_b32 m0, s17
	s_add_u32 s2, s18, 0x100000
	v_lshl_or_b32 v130, v194, 13, v191
	global_load_lds_dwordx4 v134, s[18:19]
	s_mov_b32 m0, s28
	s_addc_u32 s3, s19, 0
	s_add_i32 s29, s17, 0x4000
	global_load_lds_dwordx4 v130, s[18:19]
	s_mov_b32 m0, s29
	s_add_i32 s30, s17, 0x6000
	global_load_lds_dwordx4 v134, s[2:3]
	s_mov_b32 m0, s30
	v_mov_b32_e32 v133, 0
	global_load_lds_dwordx4 v130, s[2:3]
	v_mov_b32_e32 v129, v133
	v_mov_b32_e32 v135, v133
	v_mov_b32_e32 v131, v133
	s_cmp_eq_u32 s6, 1
	s_mov_b32 s31, 0
	v_lshl_add_u64 v[6:7], s[20:21], 0, v[132:133]
	v_lshl_add_u64 v[4:5], s[20:21], 0, v[128:129]
	v_lshl_add_u64 v[0:1], s[18:19], 0, v[134:135]
	s_cselect_b64 s[2:3], -1, 0
	s_cmp_lg_u32 s6, 1
	v_lshl_add_u64 v[2:3], s[18:19], 0, v[130:131]
	s_cbranch_scc1 .LBB0_1029
	s_barrier

;     __host__ __device__ bool next(int i, Unit& u) const {
;         const long L = (long)(i / khn) * G + c; if (L >= nwg) return false; u.kh = i % khn;
;         int wgid = (int)L; { const int q = nwg / NXCD, r = nwg % NXCD, xcd = wgid % NXCD, off = wgid / NXCD; wgid = (xcd < r ? xcd * (q + 1) : r * (q + 1) + (xcd - r) * q) + off; }
;         const int nig = WGM * nN, gid = wgid / nig, fm = gid * WGM, gsz = (nM - fm) < WGM ? (nM - fm) : WGM;
;         u.pm = fm + ((wgid % nig) % gsz); u.pn = (wgid % nig) / gsz; return true;
; template <class Epi, class Sched, bool ALIGN_EPI = false, bool SP2 = false>
; __device__ __forceinline__ void gemm_phase(PG8_LAS unsigned char* lds, const Gemm g, const Sched& S, const Epi& E) {
;     ...
;         const bool has_next = S.next(ui + 1, nxt);
.LBB0_1032:
	s_add_i32 s31, s31, 1
	s_cmp_eq_u32 s31, 1
	s_cselect_b32 s50, 0, s31
	s_cmp_eq_u32 s49, 0
	s_cselect_b32 s50, s31, s50
	s_mul_i32 s0, s50, s36
	s_mul_hi_u32 s1, s50, s42
	s_add_i32 s1, s1, s0
	s_mul_i32 s0, s50, s42
	s_add_u32 s12, s0, s33
	s_addc_u32 s13, s1, s27
	v_cmp_gt_i64_e32 vcc, s[12:13], v[142:143]
	v_cmp_lt_i64_e64 s[0:1], s[12:13], v[140:141]
	s_cbranch_vccnz .LBB0_1034
	s_ashr_i32 s8, s12, 31
	s_lshr_b32 s8, s8, 29
	s_add_i32 s8, s12, s8
	s_ashr_i32 s9, s8, 3
	s_and_b32 s8, s8, -8
	s_sub_i32 s8, s12, s8
	s_lshr_b32 s10, s8, 31
	s_or_b32 s10, s10, 64
	s_mul_i32 s8, s10, s8
	s_add_i32 s8, s8, s9
	s_ashr_i32 s9, s8, 31
	s_lshr_b32 s9, s9, 27
	s_add_i32 s9, s8, s9
	s_ashr_i32 s10, s9, 5
	s_lshl_b32 s10, s10, 3
	s_sub_i32 s11, 0x80, s10
	s_min_i32 s11, s11, 8
	s_abs_i32 s12, s11
	v_cvt_f32_u32_e32 v0, s12
	s_sub_i32 s14, 0, s12
	s_andn2_b32 s9, s9, 31
	s_sub_i32 s9, s8, s9
	v_rcp_iflag_f32_e32 v0, v0
	s_abs_i32 s8, s9
	s_xor_b32 s13, s9, s11
	s_ashr_i32 s13, s13, 31
	v_mul_f32_e32 v0, 0x4f7ffffe, v0
	v_cvt_u32_f32_e32 v0, v0
	s_nop 0
	v_readfirstlane_b32 s15, v0
	s_mul_i32 s14, s14, s15
	s_mul_hi_u32 s14, s15, s14
	s_add_i32 s15, s15, s14
	s_mul_hi_u32 s14, s8, s15
	s_mul_i32 s15, s14, s12
	s_sub_i32 s8, s8, s15
	s_add_i32 s22, s14, 1
	s_sub_i32 s15, s8, s12
	s_cmp_ge_u32 s8, s12
	s_cselect_b32 s14, s22, s14
	s_cselect_b32 s8, s15, s8
	s_add_i32 s15, s14, 1
	s_cmp_ge_u32 s8, s12
	s_cselect_b32 s8, s15, s14
	s_xor_b32 s8, s8, s13
	s_sub_i32 s8, s8, s13
	s_mul_i32 s11, s8, s11
	s_sub_i32 s9, s9, s11
	s_add_i32 s10, s9, s10
